# out-proj quarter units run a lean K-loop: only the needed A/B halves staged, the 8 LDS half-tile buffers used as 4 tile sets, one barrier per K-tile, wave halves aligned; streamer workgroups take one
# speedup vs baseline: 1.0255x; 1.0255x over previous
; #define LDS_AS __attribute__((address_space(3)))
; __global__ void __launch_bounds__(512, 2) hymba_mega(Params p) {
;     ...
;     for (int rep = 0; rep < 1 + DUP_P2; ++rep) {
;         const int cq = rep * 64;
;         LDS_AS int* sunit = (LDS_AS int*)((LDS_AS char*)smem + SM_UNIT_OFF);
;     ...
;         const bool streamer = ((blockIdx.x >> 3) & 3) == 0;
;         for (int ph = 0; ph < 4; ++ph) {
;             const int qi = streamer ? (ph == 0 ? 0 : ph == 1 ? 2 : ph == 2 ? 1 : 3) : (ph == 0 ? 1 : ph == 1 ? 0 : ph == 2 ? 2 : 3);
.LBB0_400:
	s_or_b64 exec, exec, s[0:1]
	v_mov_b32_e32 v251, 0x180
	global_load_dwordx2 v[252:253], v251, s[56:57] sc0 sc1
	s_waitcnt vmcnt(0)
	v_mov_b32_e32 v249, v252
	v_mov_b32_e32 v250, v253
	s_and_b32 s0, s2, 24
	s_cmp_lg_u32 s0, 0
	s_mov_b32 s0, 0x20040
	s_cselect_b64 s[12:13], -1, 0
	v_bfe_u32 v141, v0, 20, 10
	v_bfe_u32 v143, v0, 10, 10
	s_add_i32 s63, s0, 0x100
	s_mov_b32 s0, 0x20044
	v_mbcnt_lo_u32_b32 v0, -1, 0
	s_mov_b32 s11, 0
	v_mov_b32_e32 v131, 0
	s_movk_i32 s62, 0x100
	s_movk_i32 s66, 0x21f
	s_movk_i32 s67, 0x1000
	s_movk_i32 s88, 0x1010
	s_mov_b64 s[14:15], 0x10000
	s_mov_b64 s[16:17], 0x20000
	s_mov_b64 s[20:21], 0x30000
	s_movk_i32 s89, 0x90
	s_mov_b32 s90, 0xc2400000
	s_movk_i32 s91, 0x1200
	s_mov_b64 s[22:23], 0x1000
	s_mov_b32 s92, 0x12000
	s_mov_b32 s93, 0xf149f2ca
	s_movk_i32 s94, 0x2100
	s_add_i32 s95, s0, 0x100
	s_mov_b32 s96, 0x10000
	s_mov_b64 s[24:25], 0x10900
	s_mov_b64 s[26:27], 0x10940
	s_mov_b64 s[28:29], 0x1c00
	v_mov_b32_e32 v145, 0xff800000
	v_mbcnt_hi_u32_b32 v174, -1, v0
	v_mov_b32_e32 v147, 0x100
	v_mov_b32_e32 v175, 0x42000
	s_mov_b32 s97, 0
	s_and_b64 vcc, exec, s[12:13]
	s_cbranch_vccnz .Lstr_s97
	s_mov_b32 s97, -1
.Lstr_s97:
	s_waitcnt lgkmcnt(0)
	s_barrier
	s_branch .LBB0_402

; #define QUEUE_LOOP(QI, NUNITS, BODY) \
;         for (;;) { \
;             __syncthreads(); \
;             if (tid == 0) *sunit = (int)atomicAdd(p.ctrl + cq + (QI), 1u); \
;             __syncthreads(); \
;             const int u = *sunit; \
;             if (u >= (NUNITS)) break; \
;             BODY; \
;         }
; __global__ void __launch_bounds__(512, 2) hymba_mega(Params p) {
;     ...
;         for (int ph = 0; ph < 4; ++ph) {
;             const int qi = streamer ? (ph == 0 ? 0 : ph == 1 ? 2 : ph == 2 ? 1 : 3) : (ph == 0 ? 1 : ph == 1 ? 0 : ph == 2 ? 2 : 3);
;             if (qi == 0) { QUEUE_LOOP(0, NU_SF, sample_unit<1>(p, u / NSPLIT, u % NSPLIT, smem, cq)) }
.LBB0_402:
	s_mov_b32 s99, 0x7fffffff
	s_cmp_eq_u32 s97, -1
	s_cselect_b32 s99, 1, s99
	s_and_b64 vcc, exec, s[12:13]
	s_mov_b64 s[0:1], -1
	s_cbranch_vccz .LBB0_409
	s_cmp_eq_u32 s97, 0
	s_cselect_b32 s38, 2, 3
	s_cmp_eq_u32 s97, 1
	s_cselect_b32 s38, 1, s38
	s_cmp_eq_u32 s97, 2
	s_cselect_b32 s38, 0, s38

; __global__ void __launch_bounds__(512, 2) hymba_mega(Params p) {
;     ...
;         for (int ph = 0; ph < 4; ++ph) {
;             const int qi = streamer ? (ph == 0 ? 0 : ph == 1 ? 2 : ph == 2 ? 1 : 3) : (ph == 0 ? 1 : ph == 1 ? 0 : ph == 2 ? 2 : 3);
.LBB0_409:
	s_and_b64 vcc, exec, s[0:1]
	s_cbranch_vccz .LBB0_415
	s_cmp_eq_u32 s97, 0
	s_cselect_b32 s38, 0, 3
	s_cmp_eq_u32 s97, 1
	s_cselect_b32 s38, 2, s38
	s_cmp_eq_u32 s97, 2
	s_cselect_b32 s38, 1, s38

.LBB0_420:
	s_cmp_eq_u32 s99, 0
	s_cbranch_scc1 .LBB0_434
	s_add_i32 s99, s99, -1
	s_barrier
	s_and_saveexec_b64 s[0:1], s[40:41]
	s_cbranch_execz .LBB0_424
	s_mov_b64 s[6:7], exec
	v_mbcnt_lo_u32_b32 v0, s6, 0
	v_mbcnt_hi_u32_b32 v0, s7, v0
	v_cmp_eq_u32_e32 vcc, 0, v0
	s_and_saveexec_b64 s[4:5], vcc
	s_cbranch_execz .LBB0_423
	s_bcnt1_i32_b64 s6, s[6:7]
	v_mov_b32_e32 v1, s6
	global_atomic_add v1, v131, v1, s[56:57] offset:12 sc0

; #define PG8_STAGE(bufoff, gbase, voff) do { _Pragma("unroll") for (int _i = 0; _i < 2; ++_i) \
;         __builtin_amdgcn_global_load_lds((const unsigned*)((const char*)(gbase) + (voff)[_i]), (PG8_LAS unsigned*)(lds + (bufoff) + ldsw + _i * 8192), 16, 0, 0); } while (0)
; #define PG8_WAIT_V(n) asm volatile("s_waitcnt vmcnt(" #n ")" ::: "memory")
; #define PG8_BAR __builtin_amdgcn_s_barrier()
; template <class Epi, class Sched, bool ALIGN_EPI = false, bool SP2 = false>
; __device__ __forceinline__ void gemm_phase(PG8_LAS unsigned char* lds, const Gemm g, const Sched& S, const Epi& E) {
;     ...
;     const char* cA = (const char*)g.A + (size_t)cur.pm * tstep; const char* cB = (const char*)g.Bt + (size_t)cur.pn * tstep;
;     S.a_ready(cur);
;     if constexpr (SP2) {
;         PG8_STAGE(PG8_SB(0, 0), cB, voffB); PG8_STAGE(PG8_SB(0, 1), cB + hstep, voffB); PG8_STAGE(PG8_SA(0, 0), cA, voffA); PG8_STAGE(PG8_SA(0, 1), cA + hstep, voffA);
;         if (wr == 1) PG8_BAR;
;         PG8_WAIT_V(2); PG8_BAR;
;         PG8_STAGE(PG8_SB(1, 0), cB + kstep, voffB); PG8_STAGE(PG8_SA(1, 0), cA + kstep, voffA); PG8_STAGE(PG8_SB(1, 1), cB + hstep + kstep, voffB);
;         PG8_WAIT_V(6); PG8_BAR;
;     } else {
;         PG8_STAGE(PG8_SB(0, 0), cB, voffB); PG8_STAGE(PG8_SA(0, 0), cA, voffA); PG8_STAGE(PG8_SB(0, 1), cB + hstep, voffB); PG8_STAGE(PG8_SA(0, 1), cA + hstep, voffA);
;         if (wr == 1) PG8_BAR;
;         PG8_WAIT_V(4); PG8_BAR;
;         PG8_STAGE(PG8_SB(1, 0), cB + kstep, voffB); PG8_STAGE(PG8_SA(1, 0), cA + kstep, voffA); PG8_STAGE(PG8_SB(1, 1), cB + hstep + kstep, voffB);
;         PG8_WAIT_V(6); PG8_BAR;
;     }
;     for (;;) {
;         const bool has_next = S.next(ui + 1, nxt);
;         const char* nA = has_next ? (const char*)g.A + (size_t)nxt.pm * tstep : cA; const char* nB = has_next ? (const char*)g.Bt + (size_t)nxt.pn * tstep : cB;
;         for (int t = 0; t < nt; t += 2) {
.LBB0_616:
	s_and_b32 s19, s2, 7
	s_mul_i32 s19, s19, 6
	s_lshr_b32 s86, s2, 3
	s_add_i32 s19, s19, s86
	s_bfe_u32 s86, s19, 0x20002
	s_lshr_b32 s88, s19, 4
	s_add_i32 s88, s88, 64
	s_ashr_i32 s89, s88, 31
	s_lshl_b64 s[20:21], s[88:89], 19
	s_add_u32 s90, s70, s20
	s_addc_u32 s91, s71, s21
	s_and_b64 s[20:21], s[38:39], exec
	s_cselect_b32 s19, s91, s97
	s_cselect_b32 s43, s90, s96
	s_ashr_i32 s87, s86, 31
	s_lshl_b64 s[20:21], s[86:87], 19
	s_add_u32 s92, s64, s20
	s_addc_u32 s93, s65, s21
	s_and_b64 s[20:21], s[38:39], exec
	s_cselect_b32 s87, s93, s99
	s_cselect_b32 s89, s92, s98
	s_add_u32 s96, s96, 0x40080
	s_addc_u32 s97, s97, 0
	s_add_u32 s95, s98, 0x100
	v_mov_b32_e32 v0, 0
	s_addc_u32 s20, s99, 0
	s_mov_b32 s21, -2
	s_waitcnt lgkmcnt(0)
	v_mov_b32_e32 v1, v0
	v_mov_b32_e32 v2, v0
	v_mov_b32_e32 v3, v0
	v_mov_b32_e32 v4, v0
	v_mov_b32_e32 v5, v0
	v_mov_b32_e32 v6, v0
	v_mov_b32_e32 v7, v0
	v_mov_b32_e32 v16, v0
	v_mov_b32_e32 v17, v0
	v_mov_b32_e32 v18, v0
	v_mov_b32_e32 v19, v0
	v_mov_b32_e32 v20, v0
	v_mov_b32_e32 v21, v0
	v_mov_b32_e32 v22, v0
	v_mov_b32_e32 v23, v0
	v_mov_b32_e32 v32, v0
	v_mov_b32_e32 v33, v0
	v_mov_b32_e32 v34, v0
	v_mov_b32_e32 v35, v0
	v_mov_b32_e32 v36, v0
	v_mov_b32_e32 v37, v0
	v_mov_b32_e32 v38, v0
	v_mov_b32_e32 v39, v0
	v_mov_b32_e32 v48, v0
	v_mov_b32_e32 v49, v0
	v_mov_b32_e32 v50, v0
	v_mov_b32_e32 v51, v0
	v_mov_b32_e32 v52, v0
	v_mov_b32_e32 v53, v0
	v_mov_b32_e32 v54, v0
	v_mov_b32_e32 v55, v0
	v_mov_b32_e32 v8, v0
	v_mov_b32_e32 v9, v0
	v_mov_b32_e32 v10, v0
	v_mov_b32_e32 v11, v0
	v_mov_b32_e32 v12, v0
	v_mov_b32_e32 v13, v0
	v_mov_b32_e32 v14, v0
	v_mov_b32_e32 v15, v0
	v_mov_b32_e32 v24, v0
	v_mov_b32_e32 v25, v0
	v_mov_b32_e32 v26, v0
	v_mov_b32_e32 v27, v0
	v_mov_b32_e32 v28, v0
	v_mov_b32_e32 v29, v0
	v_mov_b32_e32 v30, v0
	v_mov_b32_e32 v31, v0
	v_mov_b32_e32 v40, v0
	v_mov_b32_e32 v41, v0
	v_mov_b32_e32 v42, v0
	v_mov_b32_e32 v43, v0
	v_mov_b32_e32 v44, v0
	v_mov_b32_e32 v45, v0
	v_mov_b32_e32 v46, v0
	v_mov_b32_e32 v47, v0
	v_mov_b32_e32 v56, v0
	v_mov_b32_e32 v57, v0
	v_mov_b32_e32 v58, v0
	v_mov_b32_e32 v59, v0
	v_mov_b32_e32 v60, v0
	v_mov_b32_e32 v61, v0
	v_mov_b32_e32 v62, v0
	v_mov_b32_e32 v63, v0
	s_waitcnt vmcnt(0)
	v_mov_b32_e32 v64, v0
	v_mov_b32_e32 v65, v0
	v_mov_b32_e32 v66, v0
	v_mov_b32_e32 v67, v0
	v_mov_b32_e32 v68, v0
	v_mov_b32_e32 v69, v0
	v_mov_b32_e32 v70, v0
	v_mov_b32_e32 v71, v0
	v_mov_b32_e32 v80, v0
	v_mov_b32_e32 v81, v0
	v_mov_b32_e32 v82, v0
	v_mov_b32_e32 v83, v0
	v_mov_b32_e32 v84, v0
	v_mov_b32_e32 v85, v0
	v_mov_b32_e32 v86, v0
	v_mov_b32_e32 v87, v0
	v_mov_b32_e32 v96, v0
	v_mov_b32_e32 v97, v0
	v_mov_b32_e32 v98, v0
	v_mov_b32_e32 v99, v0
	v_mov_b32_e32 v100, v0
	v_mov_b32_e32 v101, v0
	v_mov_b32_e32 v102, v0
	v_mov_b32_e32 v103, v0
	v_mov_b32_e32 v112, v0
	v_mov_b32_e32 v113, v0
	v_mov_b32_e32 v114, v0
	v_mov_b32_e32 v115, v0
	v_mov_b32_e32 v116, v0
	v_mov_b32_e32 v117, v0
	v_mov_b32_e32 v118, v0
	v_mov_b32_e32 v119, v0
	v_mov_b32_e32 v72, v0
	v_mov_b32_e32 v73, v0
	v_mov_b32_e32 v74, v0
	v_mov_b32_e32 v75, v0
	v_mov_b32_e32 v76, v0
	v_mov_b32_e32 v77, v0
	v_mov_b32_e32 v78, v0
	v_mov_b32_e32 v79, v0
	v_mov_b32_e32 v88, v0
	v_mov_b32_e32 v89, v0
	v_mov_b32_e32 v90, v0
	v_mov_b32_e32 v91, v0
	v_mov_b32_e32 v92, v0
	v_mov_b32_e32 v93, v0
	v_mov_b32_e32 v94, v0
	v_mov_b32_e32 v95, v0
	v_mov_b32_e32 v104, v0
	v_mov_b32_e32 v105, v0
	v_mov_b32_e32 v106, v0
	v_mov_b32_e32 v107, v0
	v_mov_b32_e32 v108, v0
	v_mov_b32_e32 v109, v0
	v_mov_b32_e32 v110, v0
	v_mov_b32_e32 v111, v0
	v_mov_b32_e32 v120, v0
	v_mov_b32_e32 v121, v0
	v_mov_b32_e32 v122, v0
	v_mov_b32_e32 v123, v0
	v_mov_b32_e32 v124, v0
	v_mov_b32_e32 v125, v0
	v_mov_b32_e32 v126, v0
	v_mov_b32_e32 v127, v0
	s_cmp_eq_u32 s100, 15
	s_cbranch_scc0 .Lp3q_lean
.LBB0_617:
	ds_read_b128 v[150:153], v160
	ds_read_b128 v[154:157], v160 offset:1024
	ds_read_b128 v[168:171], v160 offset:2048
	ds_read_b128 v[176:179], v160 offset:3072
	ds_read_b128 v[180:183], v161
	ds_read_b128 v[184:187], v161 offset:1024
	ds_read_b128 v[188:191], v161 offset:2048
	ds_read_b128 v[192:195], v161 offset:3072
	s_add_u32 s22, s96, 0xfffc0080
	s_addc_u32 s23, s97, -1
	s_cmp_eq_u32 s21, 12
	s_cselect_b32 vcc_hi, s19, s23
	s_cselect_b32 vcc_lo, s43, s22
	s_cselect_b32 s99, s87, s20
	s_cselect_b32 s98, s89, s95
	v_lshl_add_u64 v[172:173], s[96:97], 0, v[134:135]
	s_add_i32 m0, s0, 0xc000
	ds_read_b128 v[196:199], v162
	ds_read_b128 v[200:203], v162 offset:1024
	ds_read_b128 v[204:207], v162 offset:2048
	ds_read_b128 v[208:211], v162 offset:3072
	ds_read_b128 v[212:215], v162 offset:4096
	ds_read_b128 v[216:219], v162 offset:5120
	ds_read_b128 v[220:223], v162 offset:6144
	ds_read_b128 v[224:227], v162 offset:7168
	global_load_lds_dwordx4 v[172:173], off
	v_lshl_add_u64 v[172:173], s[96:97], 0, v[136:137]
	s_add_i32 m0, s0, 0xe000
	s_nop 0
	global_load_lds_dwordx4 v[172:173], off
	s_waitcnt vmcnt(8)
	s_waitcnt lgkmcnt(0)
	s_barrier
; #define PG8_STAGE(bufoff, gbase, voff) do { _Pragma("unroll") for (int _i = 0; _i < 2; ++_i) \
;         __builtin_amdgcn_global_load_lds((const unsigned*)((const char*)(gbase) + (voff)[_i]), (PG8_LAS unsigned*)(lds + (bufoff) + ldsw + _i * 8192), 16, 0, 0); } while (0)
; #define PG8_LDA(dst, b, h) do { _Pragma("unroll") for (int m = 0; m < 4; ++m) _Pragma("unroll") for (int k = 0; k < 2; ++k) dst[m][k] = *(const PG8_LAS bf16x8*)(lds + PG8_SA(b, h) + aoff + m * 2048 + k * 1024); } while (0)
; #define PG8_LDB(dst, b, h) do { _Pragma("unroll") for (int n = 0; n < 2; ++n) _Pragma("unroll") for (int k = 0; k < 2; ++k) dst[n][k] = *(const PG8_LAS bf16x8*)(lds + PG8_SB(b, h) + boff + n * 2048 + k * 1024); } while (0)
; #define PG8_MMA(ai, bj, At, Bt) do { __builtin_amdgcn_s_setprio(1); _Pragma("unroll") for (int m = 0; m < 4; ++m) _Pragma("unroll") for (int n = 0; n < 2; ++n) _Pragma("unroll") for (int k = 0; k < 2; ++k) \
;         acc[ai][bj][m][n] = __builtin_amdgcn_mfma_f32_16x16x32_bf16(Bt[n][k], At[m][k], acc[ai][bj][m][n], 0, 0, 0); __builtin_amdgcn_s_setprio(0); } while (0)
; #define PG8_WAIT_V(n) asm volatile("s_waitcnt vmcnt(" #n ")" ::: "memory")
; #define PG8_WAIT_L(n) asm volatile("s_waitcnt lgkmcnt(" #n ")" ::: "memory")
; #define PG8_BAR __builtin_amdgcn_s_barrier()
; #define PG8_SCHED __builtin_amdgcn_sched_barrier(0)
; template <class Epi, class Sched, bool ALIGN_EPI = false, bool SP2 = false>
; __device__ __forceinline__ void gemm_phase(PG8_LAS unsigned char* lds, const Gemm g, const Sched& S, const Epi& E) {
;     ...
;             PG8_LDB(B0, 0, 0); PG8_LDB(B1, 0, 1); PG8_SCHED; PG8_LDA(At, 0, 0); PG8_STAGE(PG8_SA(1, 1), a1 + hstep, voffA);
;             PG8_WAIT_V(8); PG8_WAIT_L(0); PG8_BAR; PG8_MMA(0, 0, At, B0); PG8_MMA(0, 1, At, B1); PG8_BAR; PG8_SCHED;
;             PG8_LDA(At, 0, 1); PG8_STAGE(PG8_SB(0, 0), b2, voffB); PG8_STAGE(PG8_SB(0, 1), b2 + hstep, voffB); PG8_STAGE(PG8_SA(0, 0), a2, voffA);
;             PG8_WAIT_V(8); PG8_WAIT_L(0); PG8_BAR; PG8_MMA(1, 0, At, B0); PG8_MMA(1, 1, At, B1); PG8_BAR; PG8_SCHED;
	s_setprio 1
	s_waitcnt lgkmcnt(0)
	v_mfma_f32_16x16x32_bf16 v[124:127], v[150:153], v[196:199], v[124:127]
	v_mfma_f32_16x16x32_bf16 v[120:123], v[168:171], v[196:199], v[120:123]
	v_mfma_f32_16x16x32_bf16 v[108:111], v[150:153], v[204:207], v[108:111]
	v_mfma_f32_16x16x32_bf16 v[104:107], v[168:171], v[204:207], v[104:107]
	v_mfma_f32_16x16x32_bf16 v[92:95], v[150:153], v[212:215], v[92:95]
	v_mfma_f32_16x16x32_bf16 v[88:91], v[168:171], v[212:215], v[88:91]
	v_mfma_f32_16x16x32_bf16 v[76:79], v[150:153], v[220:223], v[76:79]
	v_mfma_f32_16x16x32_bf16 v[72:75], v[168:171], v[220:223], v[72:75]
	v_mfma_f32_16x16x32_bf16 v[124:127], v[154:157], v[200:203], v[124:127]
	v_mfma_f32_16x16x32_bf16 v[120:123], v[176:179], v[200:203], v[120:123]
	v_mfma_f32_16x16x32_bf16 v[108:111], v[154:157], v[208:211], v[108:111]
	v_mfma_f32_16x16x32_bf16 v[104:107], v[176:179], v[208:211], v[104:107]
	v_mfma_f32_16x16x32_bf16 v[92:95], v[154:157], v[216:219], v[92:95]
	v_mfma_f32_16x16x32_bf16 v[88:91], v[176:179], v[216:219], v[88:91]
	v_mfma_f32_16x16x32_bf16 v[76:79], v[154:157], v[224:227], v[76:79]
	v_mfma_f32_16x16x32_bf16 v[72:75], v[176:179], v[224:227], v[72:75]
	s_setprio 0
	s_setprio 1
	v_mfma_f32_16x16x32_bf16 v[116:119], v[180:183], v[196:199], v[116:119]
	v_mfma_f32_16x16x32_bf16 v[112:115], v[188:191], v[196:199], v[112:115]
	v_mfma_f32_16x16x32_bf16 v[100:103], v[180:183], v[204:207], v[100:103]
	v_mfma_f32_16x16x32_bf16 v[96:99], v[188:191], v[204:207], v[96:99]
	v_mfma_f32_16x16x32_bf16 v[84:87], v[180:183], v[212:215], v[84:87]
	v_mfma_f32_16x16x32_bf16 v[80:83], v[188:191], v[212:215], v[80:83]
	v_mfma_f32_16x16x32_bf16 v[68:71], v[180:183], v[220:223], v[68:71]
	v_mfma_f32_16x16x32_bf16 v[64:67], v[188:191], v[220:223], v[64:67]
	v_mfma_f32_16x16x32_bf16 v[116:119], v[184:187], v[200:203], v[116:119]
	v_mfma_f32_16x16x32_bf16 v[112:115], v[192:195], v[200:203], v[112:115]
	v_mfma_f32_16x16x32_bf16 v[100:103], v[184:187], v[208:211], v[100:103]
	v_mfma_f32_16x16x32_bf16 v[96:99], v[192:195], v[208:211], v[96:99]
	v_mfma_f32_16x16x32_bf16 v[84:87], v[184:187], v[216:219], v[84:87]
	v_mfma_f32_16x16x32_bf16 v[80:83], v[192:195], v[216:219], v[80:83]
	v_mfma_f32_16x16x32_bf16 v[68:71], v[184:187], v[224:227], v[68:71]
	v_mfma_f32_16x16x32_bf16 v[64:67], v[192:195], v[224:227], v[64:67]
	s_setprio 0
	s_barrier
	s_add_i32 s22, s11, s3
	v_lshl_add_u64 v[172:173], s[98:99], 0, v[142:143]
	s_mov_b32 m0, s22
	ds_read_b128 v[196:199], v162 offset:16384
	ds_read_b128 v[200:203], v162 offset:17408
	ds_read_b128 v[204:207], v162 offset:18432
	ds_read_b128 v[208:211], v162 offset:19456
	ds_read_b128 v[212:215], v162 offset:20480
	ds_read_b128 v[216:219], v162 offset:21504
	ds_read_b128 v[220:223], v162 offset:22528
	ds_read_b128 v[224:227], v162 offset:23552
	global_load_lds_dwordx4 v[172:173], off
	s_add_i32 m0, s22, 0x2000
	s_add_u32 s22, s98, 0x40000
	v_lshl_add_u64 v[228:229], s[98:99], 0, v[146:147]
	s_addc_u32 s23, s99, 0
	s_add_i32 s24, s12, s3
	global_load_lds_dwordx4 v[228:229], off
	v_lshl_add_u64 v[230:231], s[22:23], 0, v[142:143]
	s_mov_b32 m0, s24
	v_lshl_add_u64 v[232:233], vcc, 0, v[144:145]
	global_load_lds_dwordx4 v[230:231], off
	v_lshl_add_u64 v[230:231], s[22:23], 0, v[146:147]
	s_add_i32 m0, s24, 0x2000
	s_nop 0
	global_load_lds_dwordx4 v[230:231], off
	v_lshl_add_u64 v[230:231], vcc, 0, v[140:141]
	s_mov_b32 m0, s0
	s_nop 0
	global_load_lds_dwordx4 v[230:231], off
	s_mov_b32 m0, s1
	s_nop 0
	global_load_lds_dwordx4 v[232:233], off
	s_waitcnt vmcnt(8)
	s_waitcnt lgkmcnt(0)
	s_barrier
	s_setprio 1
	s_waitcnt lgkmcnt(0)
	v_mfma_f32_16x16x32_bf16 v[60:63], v[150:153], v[196:199], v[60:63]
	v_mfma_f32_16x16x32_bf16 v[56:59], v[168:171], v[196:199], v[56:59]
	v_mfma_f32_16x16x32_bf16 v[44:47], v[150:153], v[204:207], v[44:47]
	v_mfma_f32_16x16x32_bf16 v[40:43], v[168:171], v[204:207], v[40:43]
	v_mfma_f32_16x16x32_bf16 v[28:31], v[150:153], v[212:215], v[28:31]
	v_mfma_f32_16x16x32_bf16 v[24:27], v[168:171], v[212:215], v[24:27]
	v_mfma_f32_16x16x32_bf16 v[12:15], v[150:153], v[220:223], v[12:15]
	v_mfma_f32_16x16x32_bf16 v[8:11], v[168:171], v[220:223], v[8:11]
	v_mfma_f32_16x16x32_bf16 v[60:63], v[154:157], v[200:203], v[60:63]
	v_mfma_f32_16x16x32_bf16 v[56:59], v[176:179], v[200:203], v[56:59]
	v_mfma_f32_16x16x32_bf16 v[44:47], v[154:157], v[208:211], v[44:47]
	v_mfma_f32_16x16x32_bf16 v[40:43], v[176:179], v[208:211], v[40:43]
	v_mfma_f32_16x16x32_bf16 v[28:31], v[154:157], v[216:219], v[28:31]
	v_mfma_f32_16x16x32_bf16 v[24:27], v[176:179], v[216:219], v[24:27]
	v_mfma_f32_16x16x32_bf16 v[12:15], v[154:157], v[224:227], v[12:15]
	v_mfma_f32_16x16x32_bf16 v[8:11], v[176:179], v[224:227], v[8:11]
	s_setprio 0
	s_setprio 1
	v_mfma_f32_16x16x32_bf16 v[52:55], v[180:183], v[196:199], v[52:55]
	v_mfma_f32_16x16x32_bf16 v[48:51], v[188:191], v[196:199], v[48:51]
	v_mfma_f32_16x16x32_bf16 v[36:39], v[180:183], v[204:207], v[36:39]
	v_mfma_f32_16x16x32_bf16 v[32:35], v[188:191], v[204:207], v[32:35]
	v_mfma_f32_16x16x32_bf16 v[20:23], v[180:183], v[212:215], v[20:23]
	v_mfma_f32_16x16x32_bf16 v[16:19], v[188:191], v[212:215], v[16:19]
	v_mfma_f32_16x16x32_bf16 v[4:7], v[180:183], v[220:223], v[4:7]
	v_mfma_f32_16x16x32_bf16 v[0:3], v[188:191], v[220:223], v[0:3]
	v_mfma_f32_16x16x32_bf16 v[52:55], v[184:187], v[200:203], v[52:55]
	v_mfma_f32_16x16x32_bf16 v[48:51], v[192:195], v[200:203], v[48:51]
	v_mfma_f32_16x16x32_bf16 v[36:39], v[184:187], v[208:211], v[36:39]
	v_mfma_f32_16x16x32_bf16 v[32:35], v[192:195], v[208:211], v[32:35]
	v_mfma_f32_16x16x32_bf16 v[20:23], v[184:187], v[216:219], v[20:23]
	v_mfma_f32_16x16x32_bf16 v[16:19], v[192:195], v[216:219], v[16:19]
	v_mfma_f32_16x16x32_bf16 v[4:7], v[184:187], v[224:227], v[4:7]
	v_mfma_f32_16x16x32_bf16 v[0:3], v[192:195], v[224:227], v[0:3]
	s_setprio 0
	s_barrier
; #define PG8_STAGE(bufoff, gbase, voff) do { _Pragma("unroll") for (int _i = 0; _i < 2; ++_i) \
;         __builtin_amdgcn_global_load_lds((const unsigned*)((const char*)(gbase) + (voff)[_i]), (PG8_LAS unsigned*)(lds + (bufoff) + ldsw + _i * 8192), 16, 0, 0); } while (0)
; #define PG8_LDA(dst, b, h) do { _Pragma("unroll") for (int m = 0; m < 4; ++m) _Pragma("unroll") for (int k = 0; k < 2; ++k) dst[m][k] = *(const PG8_LAS bf16x8*)(lds + PG8_SA(b, h) + aoff + m * 2048 + k * 1024); } while (0)
; #define PG8_LDB(dst, b, h) do { _Pragma("unroll") for (int n = 0; n < 2; ++n) _Pragma("unroll") for (int k = 0; k < 2; ++k) dst[n][k] = *(const PG8_LAS bf16x8*)(lds + PG8_SB(b, h) + boff + n * 2048 + k * 1024); } while (0)
; #define PG8_MMA(ai, bj, At, Bt) do { __builtin_amdgcn_s_setprio(1); _Pragma("unroll") for (int m = 0; m < 4; ++m) _Pragma("unroll") for (int n = 0; n < 2; ++n) _Pragma("unroll") for (int k = 0; k < 2; ++k) \
;         acc[ai][bj][m][n] = __builtin_amdgcn_mfma_f32_16x16x32_bf16(Bt[n][k], At[m][k], acc[ai][bj][m][n], 0, 0, 0); __builtin_amdgcn_s_setprio(0); } while (0)
; #define PG8_WAIT_V(n) asm volatile("s_waitcnt vmcnt(" #n ")" ::: "memory")
; #define PG8_WAIT_L(n) asm volatile("s_waitcnt lgkmcnt(" #n ")" ::: "memory")
; #define PG8_BAR __builtin_amdgcn_s_barrier()
; #define PG8_SCHED __builtin_amdgcn_sched_barrier(0)
; template <class Epi, class Sched, bool ALIGN_EPI = false, bool SP2 = false>
; __device__ __forceinline__ void gemm_phase(PG8_LAS unsigned char* lds, const Gemm g, const Sched& S, const Epi& E) {
;     ...
;             PG8_LDB(B0, 1, 0); PG8_LDB(B1, 1, 1); PG8_SCHED; PG8_LDA(At, 1, 0); PG8_STAGE(PG8_SA(0, 1), a2 + hstep, voffA);
;             PG8_WAIT_V(8); PG8_WAIT_L(0); PG8_BAR; PG8_MMA(0, 0, At, B0); PG8_MMA(0, 1, At, B1); PG8_BAR; PG8_SCHED;
;             PG8_LDA(At, 1, 1); PG8_STAGE(PG8_SB(1, 0), b3, voffB); PG8_STAGE(PG8_SB(1, 1), b3 + hstep, voffB); PG8_STAGE(PG8_SA(1, 0), a3, voffA);
;             PG8_WAIT_V(8); PG8_WAIT_L(0); PG8_BAR; PG8_MMA(1, 0, At, B0); PG8_MMA(1, 1, At, B1); PG8_BAR; PG8_SCHED;
	ds_read_b128 v[150:153], v163
	ds_read_b128 v[154:157], v163 offset:1024
	ds_read_b128 v[168:171], v163 offset:2048
	ds_read_b128 v[176:179], v163 offset:3072
	ds_read_b128 v[180:183], v164
	ds_read_b128 v[184:187], v164 offset:1024
	ds_read_b128 v[188:191], v164 offset:2048
	ds_read_b128 v[192:195], v164 offset:3072
	s_add_u32 s22, vcc_lo, 0x40000
	s_addc_u32 s23, vcc_hi, 0
	s_mov_b32 m0, s4
	v_lshl_add_u64 v[234:235], s[22:23], 0, v[140:141]
	ds_read_b128 v[196:199], v162 offset:32768
	ds_read_b128 v[200:203], v162 offset:33792
	ds_read_b128 v[204:207], v162 offset:34816
	ds_read_b128 v[208:211], v162 offset:35840
	ds_read_b128 v[212:215], v162 offset:36864
	ds_read_b128 v[216:219], v162 offset:37888
	ds_read_b128 v[220:223], v162 offset:38912
	ds_read_b128 v[224:227], v162 offset:39936
	global_load_lds_dwordx4 v[234:235], off
	v_lshl_add_u64 v[234:235], s[22:23], 0, v[144:145]
	s_mov_b32 m0, s5
	s_nop 0
	global_load_lds_dwordx4 v[234:235], off
	s_waitcnt vmcnt(8)
	s_waitcnt lgkmcnt(0)
	s_barrier
	s_setprio 1
	s_waitcnt lgkmcnt(0)
	v_mfma_f32_16x16x32_bf16 v[124:127], v[150:153], v[196:199], v[124:127]
	v_mfma_f32_16x16x32_bf16 v[120:123], v[168:171], v[196:199], v[120:123]
	v_mfma_f32_16x16x32_bf16 v[108:111], v[150:153], v[204:207], v[108:111]
	v_mfma_f32_16x16x32_bf16 v[104:107], v[168:171], v[204:207], v[104:107]
	v_mfma_f32_16x16x32_bf16 v[92:95], v[150:153], v[212:215], v[92:95]
	v_mfma_f32_16x16x32_bf16 v[88:91], v[168:171], v[212:215], v[88:91]
	v_mfma_f32_16x16x32_bf16 v[76:79], v[150:153], v[220:223], v[76:79]
	v_mfma_f32_16x16x32_bf16 v[72:75], v[168:171], v[220:223], v[72:75]
	v_mfma_f32_16x16x32_bf16 v[124:127], v[154:157], v[200:203], v[124:127]
	v_mfma_f32_16x16x32_bf16 v[120:123], v[176:179], v[200:203], v[120:123]
	v_mfma_f32_16x16x32_bf16 v[108:111], v[154:157], v[208:211], v[108:111]
	v_mfma_f32_16x16x32_bf16 v[104:107], v[176:179], v[208:211], v[104:107]
	v_mfma_f32_16x16x32_bf16 v[92:95], v[154:157], v[216:219], v[92:95]
	v_mfma_f32_16x16x32_bf16 v[88:91], v[176:179], v[216:219], v[88:91]
	v_mfma_f32_16x16x32_bf16 v[76:79], v[154:157], v[224:227], v[76:79]
	v_mfma_f32_16x16x32_bf16 v[72:75], v[176:179], v[224:227], v[72:75]
	s_setprio 0
	s_setprio 1
	v_mfma_f32_16x16x32_bf16 v[116:119], v[180:183], v[196:199], v[116:119]
	v_mfma_f32_16x16x32_bf16 v[112:115], v[188:191], v[196:199], v[112:115]
	v_mfma_f32_16x16x32_bf16 v[100:103], v[180:183], v[204:207], v[100:103]
	v_mfma_f32_16x16x32_bf16 v[96:99], v[188:191], v[204:207], v[96:99]
	v_mfma_f32_16x16x32_bf16 v[84:87], v[180:183], v[212:215], v[84:87]
	v_mfma_f32_16x16x32_bf16 v[80:83], v[188:191], v[212:215], v[80:83]
	v_mfma_f32_16x16x32_bf16 v[68:71], v[180:183], v[220:223], v[68:71]
	v_mfma_f32_16x16x32_bf16 v[64:67], v[188:191], v[220:223], v[64:67]
	v_mfma_f32_16x16x32_bf16 v[116:119], v[184:187], v[200:203], v[116:119]
	v_mfma_f32_16x16x32_bf16 v[112:115], v[192:195], v[200:203], v[112:115]
	v_mfma_f32_16x16x32_bf16 v[100:103], v[184:187], v[208:211], v[100:103]
	v_mfma_f32_16x16x32_bf16 v[96:99], v[192:195], v[208:211], v[96:99]
	v_mfma_f32_16x16x32_bf16 v[84:87], v[184:187], v[216:219], v[84:87]
	v_mfma_f32_16x16x32_bf16 v[80:83], v[192:195], v[216:219], v[80:83]
	v_mfma_f32_16x16x32_bf16 v[68:71], v[184:187], v[224:227], v[68:71]
	v_mfma_f32_16x16x32_bf16 v[64:67], v[192:195], v[224:227], v[64:67]
	s_setprio 0
	s_barrier
	s_add_i32 s22, s17, s3
	v_lshl_add_u64 v[172:173], v[172:173], 0, s[74:75]
	s_mov_b32 m0, s22
	ds_read_b128 v[196:199], v162 offset:49152
	ds_read_b128 v[200:203], v162 offset:50176
	ds_read_b128 v[204:207], v162 offset:51200
	ds_read_b128 v[208:211], v162 offset:52224
	ds_read_b128 v[212:215], v162 offset:53248
	ds_read_b128 v[216:219], v162 offset:54272
	ds_read_b128 v[220:223], v162 offset:55296
	ds_read_b128 v[224:227], v162 offset:56320
	global_load_lds_dwordx4 v[172:173], off
	s_add_i32 m0, s22, 0x2000
	s_add_u32 s22, s98, 0x40080
	v_lshl_add_u64 v[172:173], v[228:229], 0, s[74:75]
	s_addc_u32 s23, s99, 0
	s_add_i32 s24, s18, s3
	global_load_lds_dwordx4 v[172:173], off
	v_lshl_add_u64 v[172:173], s[22:23], 0, v[142:143]
	s_mov_b32 m0, s24
	s_nop 0
	global_load_lds_dwordx4 v[172:173], off
	v_lshl_add_u64 v[172:173], s[22:23], 0, v[146:147]
	s_add_i32 m0, s24, 0x2000
	s_nop 0
	global_load_lds_dwordx4 v[172:173], off
	v_lshl_add_u64 v[172:173], v[230:231], 0, s[74:75]
	s_mov_b32 m0, s6
	s_nop 0
	global_load_lds_dwordx4 v[172:173], off
	v_lshl_add_u64 v[172:173], v[232:233], 0, s[74:75]
	s_mov_b32 m0, s7
	s_nop 0
	global_load_lds_dwordx4 v[172:173], off
	s_waitcnt vmcnt(8)
	s_waitcnt lgkmcnt(0)
	s_barrier
	s_setprio 1
	s_waitcnt lgkmcnt(0)
	v_mfma_f32_16x16x32_bf16 v[60:63], v[150:153], v[196:199], v[60:63]
	v_mfma_f32_16x16x32_bf16 v[56:59], v[168:171], v[196:199], v[56:59]
	v_mfma_f32_16x16x32_bf16 v[44:47], v[150:153], v[204:207], v[44:47]
	v_mfma_f32_16x16x32_bf16 v[40:43], v[168:171], v[204:207], v[40:43]
	v_mfma_f32_16x16x32_bf16 v[28:31], v[150:153], v[212:215], v[28:31]
	v_mfma_f32_16x16x32_bf16 v[24:27], v[168:171], v[212:215], v[24:27]
	v_mfma_f32_16x16x32_bf16 v[12:15], v[150:153], v[220:223], v[12:15]
	v_mfma_f32_16x16x32_bf16 v[8:11], v[168:171], v[220:223], v[8:11]
	v_mfma_f32_16x16x32_bf16 v[60:63], v[154:157], v[200:203], v[60:63]
	v_mfma_f32_16x16x32_bf16 v[56:59], v[176:179], v[200:203], v[56:59]
	v_mfma_f32_16x16x32_bf16 v[44:47], v[154:157], v[208:211], v[44:47]
	v_mfma_f32_16x16x32_bf16 v[40:43], v[176:179], v[208:211], v[40:43]
	v_mfma_f32_16x16x32_bf16 v[28:31], v[154:157], v[216:219], v[28:31]
	v_mfma_f32_16x16x32_bf16 v[24:27], v[176:179], v[216:219], v[24:27]
	v_mfma_f32_16x16x32_bf16 v[12:15], v[154:157], v[224:227], v[12:15]
	v_mfma_f32_16x16x32_bf16 v[8:11], v[176:179], v[224:227], v[8:11]
	s_setprio 0
	s_setprio 1
	v_mfma_f32_16x16x32_bf16 v[52:55], v[180:183], v[196:199], v[52:55]
	v_mfma_f32_16x16x32_bf16 v[48:51], v[188:191], v[196:199], v[48:51]
	v_mfma_f32_16x16x32_bf16 v[36:39], v[180:183], v[204:207], v[36:39]
	v_mfma_f32_16x16x32_bf16 v[32:35], v[188:191], v[204:207], v[32:35]
	v_mfma_f32_16x16x32_bf16 v[20:23], v[180:183], v[212:215], v[20:23]
	v_mfma_f32_16x16x32_bf16 v[16:19], v[188:191], v[212:215], v[16:19]
	v_mfma_f32_16x16x32_bf16 v[4:7], v[180:183], v[220:223], v[4:7]
	v_mfma_f32_16x16x32_bf16 v[0:3], v[188:191], v[220:223], v[0:3]
	v_mfma_f32_16x16x32_bf16 v[52:55], v[184:187], v[200:203], v[52:55]
	v_mfma_f32_16x16x32_bf16 v[48:51], v[192:195], v[200:203], v[48:51]
	v_mfma_f32_16x16x32_bf16 v[36:39], v[184:187], v[208:211], v[36:39]
	v_mfma_f32_16x16x32_bf16 v[32:35], v[192:195], v[208:211], v[32:35]
	v_mfma_f32_16x16x32_bf16 v[20:23], v[184:187], v[216:219], v[20:23]
	v_mfma_f32_16x16x32_bf16 v[16:19], v[192:195], v[216:219], v[16:19]
	v_mfma_f32_16x16x32_bf16 v[4:7], v[184:187], v[224:227], v[4:7]
	v_mfma_f32_16x16x32_bf16 v[0:3], v[192:195], v[224:227], v[0:3]
	s_setprio 0
	s_barrier
	s_add_i32 s21, s21, 2
	s_add_u32 s96, s96, 0x100
	s_addc_u32 s97, s97, 0
	s_add_u32 s95, s95, 0x100
	s_addc_u32 s20, s20, 0
	s_cmp_gt_u32 s21, 13
	s_cbranch_scc0 .LBB0_617
; #define PG8_BAR __builtin_amdgcn_s_barrier()
; template <class Epi, class Sched, bool ALIGN_EPI = false, bool SP2 = false>
; __device__ __forceinline__ void gemm_phase(PG8_LAS unsigned char* lds, const Gemm g, const Sched& S, const Epi& E) {
;     ...
;         if constexpr (ALIGN_EPI) { if (wr == 0) PG8_BAR; }
;         if constexpr (!Epi::AFTER_DRAIN) { E(acc, cur, wr, wc, fr, fq); S.done(cur); }
.Lp3q_kexit:
	s_and_b64 vcc, exec, s[80:81]
	s_cbranch_vccz .LBB0_620
	s_barrier

; #define PG8_BAR __builtin_amdgcn_s_barrier()
; template <class Epi, class Sched, bool ALIGN_EPI = false, bool SP2 = false>
; __device__ __forceinline__ void gemm_phase(PG8_LAS unsigned char* lds, const Gemm g, const Sched& S, const Epi& E) {
;     ...
;         if (!has_next) break;
; #pragma unroll
;         for (int a = 0; a < 2; ++a)
; #pragma unroll
;             for (int b = 0; b < 2; ++b)
; #pragma unroll
;                 for (int m = 0; m < 4; ++m)
; #pragma unroll
;                     for (int n = 0; n < 2; ++n) acc[a][b][m][n] = (f32x4){0.f, 0.f, 0.f, 0.f};
;         cur = nxt; cA = nA; cB = nB; ++ui;
;         if constexpr (ALIGN_EPI) { if (wr == 1) PG8_BAR; }
.Lf3f_st_7:
.Lp3q_epi_done:
	s_andn2_b64 vcc, exec, s[38:39]
	s_mov_b64 s[38:39], -1
	s_cbranch_vccnz .LBB0_609
	s_cmp_lg_u32 s101, 15
	s_cbranch_scc1 .LBB0_608
	s_andn2_b64 vcc, exec, s[72:73]
	s_cbranch_vccnz .LBB0_608
	s_barrier
	s_branch .LBB0_608

; #define PG8_STAGE(bufoff, gbase, voff) do { _Pragma("unroll") for (int _i = 0; _i < 2; ++_i) \
;         __builtin_amdgcn_global_load_lds((const unsigned*)((const char*)(gbase) + (voff)[_i]), (PG8_LAS unsigned*)(lds + (bufoff) + ldsw + _i * 8192), 16, 0, 0); } while (0)
; #define PG8_LDA(dst, b, h) do { _Pragma("unroll") for (int m = 0; m < 4; ++m) _Pragma("unroll") for (int k = 0; k < 2; ++k) dst[m][k] = *(const PG8_LAS bf16x8*)(lds + PG8_SA(b, h) + aoff + m * 2048 + k * 1024); } while (0)
; #define PG8_LDB(dst, b, h) do { _Pragma("unroll") for (int n = 0; n < 2; ++n) _Pragma("unroll") for (int k = 0; k < 2; ++k) dst[n][k] = *(const PG8_LAS bf16x8*)(lds + PG8_SB(b, h) + boff + n * 2048 + k * 1024); } while (0)
; #define PG8_MMA(ai, bj, At, Bt) do { __builtin_amdgcn_s_setprio(1); _Pragma("unroll") for (int m = 0; m < 4; ++m) _Pragma("unroll") for (int n = 0; n < 2; ++n) _Pragma("unroll") for (int k = 0; k < 2; ++k) \
;         acc[ai][bj][m][n] = __builtin_amdgcn_mfma_f32_16x16x32_bf16(Bt[n][k], At[m][k], acc[ai][bj][m][n], 0, 0, 0); __builtin_amdgcn_s_setprio(0); } while (0)
; #define PG8_WAIT_V(n) asm volatile("s_waitcnt vmcnt(" #n ")" ::: "memory")
; #define PG8_BAR __builtin_amdgcn_s_barrier()
; template <class Epi, class Sched, bool ALIGN_EPI = false, bool SP2 = false>
; __device__ __forceinline__ void gemm_phase(PG8_LAS unsigned char* lds, const Gemm g, const Sched& S, const Epi& E) {
;     ...
;         for (int t = 0; t < nt; t += 2) {
;             const bool last = (t == nt - 2);
;             const char* a1 = cA + (size_t)(t + 1) * kstep;
;             const char* a2 = last ? nA : cA + (size_t)(t + 2) * kstep; const char* b2 = last ? nB : cB + (size_t)(t + 2) * kstep;
;             const char* a3 = a2 + kstep; const char* b3 = b2 + kstep;
;             if (last && has_next) S.a_ready(nxt);
;             if constexpr (SP2) {
;             PG8_LDB(B0, 0, 0); PG8_LDB(B1, 0, 1); PG8_SCHED; PG8_LDA(At, 0, 0); PG8_STAGE(PG8_SA(1, 1), a1 + hstep, voffA);
;             PG8_WAIT_V(8); PG8_WAIT_L(0); PG8_BAR; PG8_MMA(0, 0, At, B0); PG8_MMA(0, 1, At, B1); PG8_BAR; PG8_SCHED;
;             PG8_LDA(At, 0, 1); PG8_STAGE(PG8_SB(0, 0), b2, voffB); PG8_STAGE(PG8_SB(0, 1), b2 + hstep, voffB); PG8_STAGE(PG8_SA(0, 0), a2, voffA);
;             PG8_WAIT_V(8); PG8_WAIT_L(0); PG8_BAR; PG8_MMA(1, 0, At, B0); PG8_MMA(1, 1, At, B1); PG8_BAR; PG8_SCHED;
.Lp3q_lean:
	s_bitcmp1_b32 s100, 0
	s_cbranch_scc1 .Lp3q_lean_q0
	s_bitcmp1_b32 s100, 1
	s_cbranch_scc1 .Lp3q_lean_q1
	s_bitcmp1_b32 s100, 2
	s_cbranch_scc1 .Lp3q_lean_q2
	s_branch .Lp3q_lean_q3
.Lp3q_lean_q0:
	s_mov_b32 s22, s94
	s_mov_b32 s23, 0
	s_lshl_b64 s[22:23], s[22:23], 19
	s_add_u32 s22, s22, s70
	s_addc_u32 s23, s23, s71
	s_add_u32 s22, s22, 0x80
	s_addc_u32 s23, s23, 0
	s_mov_b32 s24, s42
	s_mov_b32 s25, 0
	s_lshl_b64 s[24:25], s[24:25], 19
	s_add_u32 s24, s24, s64
	s_addc_u32 s25, s25, s65
	s_add_u32 s24, s24, 0x80
	s_addc_u32 s25, s25, 0
	s_waitcnt vmcnt(0) lgkmcnt(0)
	s_barrier
	s_add_u32 s22, s22, 0x80
	s_addc_u32 s23, s23, 0
	s_add_u32 s24, s24, 0x80
	s_addc_u32 s25, s25, 0
	s_add_i32 m0, s0, 0x4000
	s_nop 0
	global_load_lds_dwordx4 v140, s[22:23]
	s_add_i32 m0, s0, 0x6000
	s_nop 0
	global_load_lds_dwordx4 v144, s[22:23]
	s_add_i32 m0, s0, 0x14000
	s_nop 0
	global_load_lds_dwordx4 v142, s[24:25]
	s_add_i32 m0, s0, 0x16000
	s_nop 0
	global_load_lds_dwordx4 v146, s[24:25]
	s_add_u32 s22, s22, 0x80
	s_addc_u32 s23, s23, 0
	s_add_u32 s24, s24, 0x80
	s_addc_u32 s25, s25, 0
	s_add_i32 m0, s0, 0xc000
	s_nop 0
	global_load_lds_dwordx4 v140, s[22:23]
	s_add_i32 m0, s0, 0xe000
	s_nop 0
	global_load_lds_dwordx4 v144, s[22:23]
	s_add_i32 m0, s0, 0x1c000
	s_nop 0
	global_load_lds_dwordx4 v142, s[24:25]
	s_add_i32 m0, s0, 0x1e000
	s_nop 0
	global_load_lds_dwordx4 v146, s[24:25]
	ds_read_b128 v[150:153], v160
	ds_read_b128 v[154:157], v160 offset:1024
	ds_read_b128 v[168:171], v160 offset:2048
	ds_read_b128 v[176:179], v160 offset:3072
	ds_read_b128 v[196:199], v162
	ds_read_b128 v[200:203], v162 offset:1024
	ds_read_b128 v[204:207], v162 offset:2048
	ds_read_b128 v[208:211], v162 offset:3072
	ds_read_b128 v[212:215], v162 offset:4096
	ds_read_b128 v[216:219], v162 offset:5120
	ds_read_b128 v[220:223], v162 offset:6144
	ds_read_b128 v[224:227], v162 offset:7168
	s_waitcnt lgkmcnt(0)
	v_mfma_f32_16x16x32_bf16 v[124:127], v[150:153], v[196:199], v[124:127]
	v_mfma_f32_16x16x32_bf16 v[120:123], v[168:171], v[196:199], v[120:123]
	v_mfma_f32_16x16x32_bf16 v[108:111], v[150:153], v[204:207], v[108:111]
	v_mfma_f32_16x16x32_bf16 v[104:107], v[168:171], v[204:207], v[104:107]
	v_mfma_f32_16x16x32_bf16 v[92:95], v[150:153], v[212:215], v[92:95]
	v_mfma_f32_16x16x32_bf16 v[88:91], v[168:171], v[212:215], v[88:91]
	v_mfma_f32_16x16x32_bf16 v[76:79], v[150:153], v[220:223], v[76:79]
	v_mfma_f32_16x16x32_bf16 v[72:75], v[168:171], v[220:223], v[72:75]
	v_mfma_f32_16x16x32_bf16 v[124:127], v[154:157], v[200:203], v[124:127]
	v_mfma_f32_16x16x32_bf16 v[120:123], v[176:179], v[200:203], v[120:123]
	v_mfma_f32_16x16x32_bf16 v[108:111], v[154:157], v[208:211], v[108:111]
	v_mfma_f32_16x16x32_bf16 v[104:107], v[176:179], v[208:211], v[104:107]
	v_mfma_f32_16x16x32_bf16 v[92:95], v[154:157], v[216:219], v[92:95]
	v_mfma_f32_16x16x32_bf16 v[88:91], v[176:179], v[216:219], v[88:91]
	v_mfma_f32_16x16x32_bf16 v[76:79], v[154:157], v[224:227], v[76:79]
	v_mfma_f32_16x16x32_bf16 v[72:75], v[176:179], v[224:227], v[72:75]
	s_waitcnt vmcnt(8)
	s_barrier
	ds_read_b128 v[150:153], v163
	ds_read_b128 v[154:157], v163 offset:1024
	ds_read_b128 v[168:171], v163 offset:2048
	ds_read_b128 v[176:179], v163 offset:3072
	ds_read_b128 v[196:199], v162 offset:32768
	ds_read_b128 v[200:203], v162 offset:33792
	ds_read_b128 v[204:207], v162 offset:34816
	ds_read_b128 v[208:211], v162 offset:35840
	ds_read_b128 v[212:215], v162 offset:36864
	ds_read_b128 v[216:219], v162 offset:37888
	ds_read_b128 v[220:223], v162 offset:38912
	ds_read_b128 v[224:227], v162 offset:39936
	s_add_u32 s22, s22, 0x80
	s_addc_u32 s23, s23, 0
	s_add_u32 s24, s24, 0x80
	s_addc_u32 s25, s25, 0
	s_mov_b32 m0, s0
	s_nop 0
	global_load_lds_dwordx4 v140, s[22:23]
	s_add_i32 m0, s0, 0x2000
	s_nop 0
	global_load_lds_dwordx4 v144, s[22:23]
	s_add_i32 m0, s0, 0x10000
	s_nop 0
	global_load_lds_dwordx4 v142, s[24:25]
	s_add_i32 m0, s0, 0x12000
	s_nop 0
	global_load_lds_dwordx4 v146, s[24:25]
	s_waitcnt lgkmcnt(0)
	v_mfma_f32_16x16x32_bf16 v[124:127], v[150:153], v[196:199], v[124:127]
	v_mfma_f32_16x16x32_bf16 v[120:123], v[168:171], v[196:199], v[120:123]
	v_mfma_f32_16x16x32_bf16 v[108:111], v[150:153], v[204:207], v[108:111]
	v_mfma_f32_16x16x32_bf16 v[104:107], v[168:171], v[204:207], v[104:107]
	v_mfma_f32_16x16x32_bf16 v[92:95], v[150:153], v[212:215], v[92:95]
	v_mfma_f32_16x16x32_bf16 v[88:91], v[168:171], v[212:215], v[88:91]
	v_mfma_f32_16x16x32_bf16 v[76:79], v[150:153], v[220:223], v[76:79]
	v_mfma_f32_16x16x32_bf16 v[72:75], v[168:171], v[220:223], v[72:75]
	v_mfma_f32_16x16x32_bf16 v[124:127], v[154:157], v[200:203], v[124:127]
	v_mfma_f32_16x16x32_bf16 v[120:123], v[176:179], v[200:203], v[120:123]
	v_mfma_f32_16x16x32_bf16 v[108:111], v[154:157], v[208:211], v[108:111]
	v_mfma_f32_16x16x32_bf16 v[104:107], v[176:179], v[208:211], v[104:107]
	v_mfma_f32_16x16x32_bf16 v[92:95], v[154:157], v[216:219], v[92:95]
	v_mfma_f32_16x16x32_bf16 v[88:91], v[176:179], v[216:219], v[88:91]
	v_mfma_f32_16x16x32_bf16 v[76:79], v[154:157], v[224:227], v[76:79]
	v_mfma_f32_16x16x32_bf16 v[72:75], v[176:179], v[224:227], v[72:75]
	s_waitcnt vmcnt(8)
	s_barrier
; #define PG8_STAGE(bufoff, gbase, voff) do { _Pragma("unroll") for (int _i = 0; _i < 2; ++_i) \
;         __builtin_amdgcn_global_load_lds((const unsigned*)((const char*)(gbase) + (voff)[_i]), (PG8_LAS unsigned*)(lds + (bufoff) + ldsw + _i * 8192), 16, 0, 0); } while (0)
; #define PG8_LDA(dst, b, h) do { _Pragma("unroll") for (int m = 0; m < 4; ++m) _Pragma("unroll") for (int k = 0; k < 2; ++k) dst[m][k] = *(const PG8_LAS bf16x8*)(lds + PG8_SA(b, h) + aoff + m * 2048 + k * 1024); } while (0)
; #define PG8_LDB(dst, b, h) do { _Pragma("unroll") for (int n = 0; n < 2; ++n) _Pragma("unroll") for (int k = 0; k < 2; ++k) dst[n][k] = *(const PG8_LAS bf16x8*)(lds + PG8_SB(b, h) + boff + n * 2048 + k * 1024); } while (0)
; #define PG8_MMA(ai, bj, At, Bt) do { __builtin_amdgcn_s_setprio(1); _Pragma("unroll") for (int m = 0; m < 4; ++m) _Pragma("unroll") for (int n = 0; n < 2; ++n) _Pragma("unroll") for (int k = 0; k < 2; ++k) \
;         acc[ai][bj][m][n] = __builtin_amdgcn_mfma_f32_16x16x32_bf16(Bt[n][k], At[m][k], acc[ai][bj][m][n], 0, 0, 0); __builtin_amdgcn_s_setprio(0); } while (0)
; #define PG8_WAIT_V(n) asm volatile("s_waitcnt vmcnt(" #n ")" ::: "memory")
; template <class Epi, class Sched, bool ALIGN_EPI = false, bool SP2 = false>
; __device__ __forceinline__ void gemm_phase(PG8_LAS unsigned char* lds, const Gemm g, const Sched& S, const Epi& E) {
;     ...
;             PG8_LDB(B0, 0, 0); PG8_LDB(B1, 0, 1); PG8_SCHED; PG8_LDA(At, 0, 0); PG8_STAGE(PG8_SA(1, 1), a1 + hstep, voffA);
;             PG8_WAIT_V(8); PG8_WAIT_L(0); PG8_BAR; PG8_MMA(0, 0, At, B0); PG8_MMA(0, 1, At, B1); PG8_BAR; PG8_SCHED;
;             PG8_LDA(At, 0, 1); PG8_STAGE(PG8_SB(0, 0), b2, voffB); PG8_STAGE(PG8_SB(0, 1), b2 + hstep, voffB); PG8_STAGE(PG8_SA(0, 0), a2, voffA);
;             PG8_WAIT_V(8); PG8_WAIT_L(0); PG8_BAR; PG8_MMA(1, 0, At, B0); PG8_MMA(1, 1, At, B1); PG8_BAR; PG8_SCHED;
;             PG8_LDB(B0, 1, 0); PG8_LDB(B1, 1, 1); PG8_SCHED; PG8_LDA(At, 1, 0); PG8_STAGE(PG8_SA(0, 1), a2 + hstep, voffA);
;             PG8_WAIT_V(8); PG8_WAIT_L(0); PG8_BAR; PG8_MMA(0, 0, At, B0); PG8_MMA(0, 1, At, B1); PG8_BAR; PG8_SCHED;
;             PG8_LDA(At, 1, 1); PG8_STAGE(PG8_SB(1, 0), b3, voffB); PG8_STAGE(PG8_SB(1, 1), b3 + hstep, voffB); PG8_STAGE(PG8_SA(1, 0), a3, voffA);
;             PG8_WAIT_V(8); PG8_WAIT_L(0); PG8_BAR; PG8_MMA(1, 0, At, B0); PG8_MMA(1, 1, At, B1); PG8_BAR; PG8_SCHED;
	ds_read_b128 v[150:153], v161
	ds_read_b128 v[154:157], v161 offset:1024
	ds_read_b128 v[168:171], v161 offset:2048
	ds_read_b128 v[176:179], v161 offset:3072
	ds_read_b128 v[196:199], v162 offset:16384
	ds_read_b128 v[200:203], v162 offset:17408
	ds_read_b128 v[204:207], v162 offset:18432
	ds_read_b128 v[208:211], v162 offset:19456
	ds_read_b128 v[212:215], v162 offset:20480
	ds_read_b128 v[216:219], v162 offset:21504
	ds_read_b128 v[220:223], v162 offset:22528
	ds_read_b128 v[224:227], v162 offset:23552
	s_add_u32 s22, s22, 0x80
	s_addc_u32 s23, s23, 0
	s_add_u32 s24, s24, 0x80
	s_addc_u32 s25, s25, 0
	s_add_i32 m0, s0, 0x8000
	s_nop 0
	global_load_lds_dwordx4 v140, s[22:23]
	s_add_i32 m0, s0, 0xa000
	s_nop 0
	global_load_lds_dwordx4 v144, s[22:23]
	s_add_i32 m0, s0, 0x18000
	s_nop 0
	global_load_lds_dwordx4 v142, s[24:25]
	s_add_i32 m0, s0, 0x1a000
	s_nop 0
	global_load_lds_dwordx4 v146, s[24:25]
	s_waitcnt lgkmcnt(0)
	v_mfma_f32_16x16x32_bf16 v[124:127], v[150:153], v[196:199], v[124:127]
	v_mfma_f32_16x16x32_bf16 v[120:123], v[168:171], v[196:199], v[120:123]
	v_mfma_f32_16x16x32_bf16 v[108:111], v[150:153], v[204:207], v[108:111]
	v_mfma_f32_16x16x32_bf16 v[104:107], v[168:171], v[204:207], v[104:107]
	v_mfma_f32_16x16x32_bf16 v[92:95], v[150:153], v[212:215], v[92:95]
	v_mfma_f32_16x16x32_bf16 v[88:91], v[168:171], v[212:215], v[88:91]
	v_mfma_f32_16x16x32_bf16 v[76:79], v[150:153], v[220:223], v[76:79]
	v_mfma_f32_16x16x32_bf16 v[72:75], v[168:171], v[220:223], v[72:75]
	v_mfma_f32_16x16x32_bf16 v[124:127], v[154:157], v[200:203], v[124:127]
	v_mfma_f32_16x16x32_bf16 v[120:123], v[176:179], v[200:203], v[120:123]
	v_mfma_f32_16x16x32_bf16 v[108:111], v[154:157], v[208:211], v[108:111]
	v_mfma_f32_16x16x32_bf16 v[104:107], v[176:179], v[208:211], v[104:107]
	v_mfma_f32_16x16x32_bf16 v[92:95], v[154:157], v[216:219], v[92:95]
	v_mfma_f32_16x16x32_bf16 v[88:91], v[176:179], v[216:219], v[88:91]
	v_mfma_f32_16x16x32_bf16 v[76:79], v[154:157], v[224:227], v[76:79]
	v_mfma_f32_16x16x32_bf16 v[72:75], v[176:179], v[224:227], v[72:75]
	s_waitcnt vmcnt(8)
	s_barrier
	ds_read_b128 v[150:153], v164
	ds_read_b128 v[154:157], v164 offset:1024
	ds_read_b128 v[168:171], v164 offset:2048
	ds_read_b128 v[176:179], v164 offset:3072
	ds_read_b128 v[196:199], v162 offset:49152
	ds_read_b128 v[200:203], v162 offset:50176
	ds_read_b128 v[204:207], v162 offset:51200
	ds_read_b128 v[208:211], v162 offset:52224
	ds_read_b128 v[212:215], v162 offset:53248
	ds_read_b128 v[216:219], v162 offset:54272
	ds_read_b128 v[220:223], v162 offset:55296
	ds_read_b128 v[224:227], v162 offset:56320
	s_add_u32 s22, s22, 0x80
	s_addc_u32 s23, s23, 0
	s_add_u32 s24, s24, 0x80
	s_addc_u32 s25, s25, 0
	s_add_i32 m0, s0, 0x4000
	s_nop 0
	global_load_lds_dwordx4 v140, s[22:23]
	s_add_i32 m0, s0, 0x6000
	s_nop 0
	global_load_lds_dwordx4 v144, s[22:23]
	s_add_i32 m0, s0, 0x14000
	s_nop 0
	global_load_lds_dwordx4 v142, s[24:25]
	s_add_i32 m0, s0, 0x16000
	s_nop 0
	global_load_lds_dwordx4 v146, s[24:25]
	s_waitcnt lgkmcnt(0)
	v_mfma_f32_16x16x32_bf16 v[124:127], v[150:153], v[196:199], v[124:127]
	v_mfma_f32_16x16x32_bf16 v[120:123], v[168:171], v[196:199], v[120:123]
	v_mfma_f32_16x16x32_bf16 v[108:111], v[150:153], v[204:207], v[108:111]
	v_mfma_f32_16x16x32_bf16 v[104:107], v[168:171], v[204:207], v[104:107]
	v_mfma_f32_16x16x32_bf16 v[92:95], v[150:153], v[212:215], v[92:95]
	v_mfma_f32_16x16x32_bf16 v[88:91], v[168:171], v[212:215], v[88:91]
	v_mfma_f32_16x16x32_bf16 v[76:79], v[150:153], v[220:223], v[76:79]
	v_mfma_f32_16x16x32_bf16 v[72:75], v[168:171], v[220:223], v[72:75]
	v_mfma_f32_16x16x32_bf16 v[124:127], v[154:157], v[200:203], v[124:127]
	v_mfma_f32_16x16x32_bf16 v[120:123], v[176:179], v[200:203], v[120:123]
	v_mfma_f32_16x16x32_bf16 v[108:111], v[154:157], v[208:211], v[108:111]
	v_mfma_f32_16x16x32_bf16 v[104:107], v[176:179], v[208:211], v[104:107]
	v_mfma_f32_16x16x32_bf16 v[92:95], v[154:157], v[216:219], v[92:95]
	v_mfma_f32_16x16x32_bf16 v[88:91], v[176:179], v[216:219], v[88:91]
	v_mfma_f32_16x16x32_bf16 v[76:79], v[154:157], v[224:227], v[76:79]
	v_mfma_f32_16x16x32_bf16 v[72:75], v[176:179], v[224:227], v[72:75]
	s_waitcnt vmcnt(8)
	s_barrier
	ds_read_b128 v[150:153], v160
	ds_read_b128 v[154:157], v160 offset:1024
	ds_read_b128 v[168:171], v160 offset:2048
	ds_read_b128 v[176:179], v160 offset:3072
	ds_read_b128 v[196:199], v162
	ds_read_b128 v[200:203], v162 offset:1024
	ds_read_b128 v[204:207], v162 offset:2048
	ds_read_b128 v[208:211], v162 offset:3072
	ds_read_b128 v[212:215], v162 offset:4096
	ds_read_b128 v[216:219], v162 offset:5120
	ds_read_b128 v[220:223], v162 offset:6144
	ds_read_b128 v[224:227], v162 offset:7168
	s_add_u32 s22, s22, 0x80
	s_addc_u32 s23, s23, 0
	s_add_u32 s24, s24, 0x80
	s_addc_u32 s25, s25, 0
	s_add_i32 m0, s0, 0xc000
	s_nop 0
	global_load_lds_dwordx4 v140, s[22:23]
	s_add_i32 m0, s0, 0xe000
	s_nop 0
	global_load_lds_dwordx4 v144, s[22:23]
	s_add_i32 m0, s0, 0x1c000
	s_nop 0
	global_load_lds_dwordx4 v142, s[24:25]
	s_add_i32 m0, s0, 0x1e000
	s_nop 0
	global_load_lds_dwordx4 v146, s[24:25]
	s_waitcnt lgkmcnt(0)
	v_mfma_f32_16x16x32_bf16 v[124:127], v[150:153], v[196:199], v[124:127]
	v_mfma_f32_16x16x32_bf16 v[120:123], v[168:171], v[196:199], v[120:123]
	v_mfma_f32_16x16x32_bf16 v[108:111], v[150:153], v[204:207], v[108:111]
	v_mfma_f32_16x16x32_bf16 v[104:107], v[168:171], v[204:207], v[104:107]
	v_mfma_f32_16x16x32_bf16 v[92:95], v[150:153], v[212:215], v[92:95]
	v_mfma_f32_16x16x32_bf16 v[88:91], v[168:171], v[212:215], v[88:91]
	v_mfma_f32_16x16x32_bf16 v[76:79], v[150:153], v[220:223], v[76:79]
	v_mfma_f32_16x16x32_bf16 v[72:75], v[168:171], v[220:223], v[72:75]
	v_mfma_f32_16x16x32_bf16 v[124:127], v[154:157], v[200:203], v[124:127]
	v_mfma_f32_16x16x32_bf16 v[120:123], v[176:179], v[200:203], v[120:123]
	v_mfma_f32_16x16x32_bf16 v[108:111], v[154:157], v[208:211], v[108:111]
	v_mfma_f32_16x16x32_bf16 v[104:107], v[176:179], v[208:211], v[104:107]
	v_mfma_f32_16x16x32_bf16 v[92:95], v[154:157], v[216:219], v[92:95]
	v_mfma_f32_16x16x32_bf16 v[88:91], v[176:179], v[216:219], v[88:91]
	v_mfma_f32_16x16x32_bf16 v[76:79], v[154:157], v[224:227], v[76:79]
	v_mfma_f32_16x16x32_bf16 v[72:75], v[176:179], v[224:227], v[72:75]
	s_waitcnt vmcnt(8)
	s_barrier
; #define PG8_STAGE(bufoff, gbase, voff) do { _Pragma("unroll") for (int _i = 0; _i < 2; ++_i) \
;         __builtin_amdgcn_global_load_lds((const unsigned*)((const char*)(gbase) + (voff)[_i]), (PG8_LAS unsigned*)(lds + (bufoff) + ldsw + _i * 8192), 16, 0, 0); } while (0)
; #define PG8_LDA(dst, b, h) do { _Pragma("unroll") for (int m = 0; m < 4; ++m) _Pragma("unroll") for (int k = 0; k < 2; ++k) dst[m][k] = *(const PG8_LAS bf16x8*)(lds + PG8_SA(b, h) + aoff + m * 2048 + k * 1024); } while (0)
; #define PG8_LDB(dst, b, h) do { _Pragma("unroll") for (int n = 0; n < 2; ++n) _Pragma("unroll") for (int k = 0; k < 2; ++k) dst[n][k] = *(const PG8_LAS bf16x8*)(lds + PG8_SB(b, h) + boff + n * 2048 + k * 1024); } while (0)
; #define PG8_MMA(ai, bj, At, Bt) do { __builtin_amdgcn_s_setprio(1); _Pragma("unroll") for (int m = 0; m < 4; ++m) _Pragma("unroll") for (int n = 0; n < 2; ++n) _Pragma("unroll") for (int k = 0; k < 2; ++k) \
;         acc[ai][bj][m][n] = __builtin_amdgcn_mfma_f32_16x16x32_bf16(Bt[n][k], At[m][k], acc[ai][bj][m][n], 0, 0, 0); __builtin_amdgcn_s_setprio(0); } while (0)
; #define PG8_WAIT_V(n) asm volatile("s_waitcnt vmcnt(" #n ")" ::: "memory")
; template <class Epi, class Sched, bool ALIGN_EPI = false, bool SP2 = false>
; __device__ __forceinline__ void gemm_phase(PG8_LAS unsigned char* lds, const Gemm g, const Sched& S, const Epi& E) {
;     ...
;             PG8_LDB(B0, 0, 0); PG8_LDB(B1, 0, 1); PG8_SCHED; PG8_LDA(At, 0, 0); PG8_STAGE(PG8_SA(1, 1), a1 + hstep, voffA);
;             PG8_WAIT_V(8); PG8_WAIT_L(0); PG8_BAR; PG8_MMA(0, 0, At, B0); PG8_MMA(0, 1, At, B1); PG8_BAR; PG8_SCHED;
;             PG8_LDA(At, 0, 1); PG8_STAGE(PG8_SB(0, 0), b2, voffB); PG8_STAGE(PG8_SB(0, 1), b2 + hstep, voffB); PG8_STAGE(PG8_SA(0, 0), a2, voffA);
;             PG8_WAIT_V(8); PG8_WAIT_L(0); PG8_BAR; PG8_MMA(1, 0, At, B0); PG8_MMA(1, 1, At, B1); PG8_BAR; PG8_SCHED;
;             PG8_LDB(B0, 1, 0); PG8_LDB(B1, 1, 1); PG8_SCHED; PG8_LDA(At, 1, 0); PG8_STAGE(PG8_SA(0, 1), a2 + hstep, voffA);
;             PG8_WAIT_V(8); PG8_WAIT_L(0); PG8_BAR; PG8_MMA(0, 0, At, B0); PG8_MMA(0, 1, At, B1); PG8_BAR; PG8_SCHED;
;             PG8_LDA(At, 1, 1); PG8_STAGE(PG8_SB(1, 0), b3, voffB); PG8_STAGE(PG8_SB(1, 1), b3 + hstep, voffB); PG8_STAGE(PG8_SA(1, 0), a3, voffA);
;             PG8_WAIT_V(8); PG8_WAIT_L(0); PG8_BAR; PG8_MMA(1, 0, At, B0); PG8_MMA(1, 1, At, B1); PG8_BAR; PG8_SCHED;
	ds_read_b128 v[150:153], v163
	ds_read_b128 v[154:157], v163 offset:1024
	ds_read_b128 v[168:171], v163 offset:2048
	ds_read_b128 v[176:179], v163 offset:3072
	ds_read_b128 v[196:199], v162 offset:32768
	ds_read_b128 v[200:203], v162 offset:33792
	ds_read_b128 v[204:207], v162 offset:34816
	ds_read_b128 v[208:211], v162 offset:35840
	ds_read_b128 v[212:215], v162 offset:36864
	ds_read_b128 v[216:219], v162 offset:37888
	ds_read_b128 v[220:223], v162 offset:38912
	ds_read_b128 v[224:227], v162 offset:39936
	s_add_u32 s22, s22, 0x80
	s_addc_u32 s23, s23, 0
	s_add_u32 s24, s24, 0x80
	s_addc_u32 s25, s25, 0
	s_mov_b32 m0, s0
	s_nop 0
	global_load_lds_dwordx4 v140, s[22:23]
	s_add_i32 m0, s0, 0x2000
	s_nop 0
	global_load_lds_dwordx4 v144, s[22:23]
	s_add_i32 m0, s0, 0x10000
	s_nop 0
	global_load_lds_dwordx4 v142, s[24:25]
	s_add_i32 m0, s0, 0x12000
	s_nop 0
	global_load_lds_dwordx4 v146, s[24:25]
	s_waitcnt lgkmcnt(0)
	v_mfma_f32_16x16x32_bf16 v[124:127], v[150:153], v[196:199], v[124:127]
	v_mfma_f32_16x16x32_bf16 v[120:123], v[168:171], v[196:199], v[120:123]
	v_mfma_f32_16x16x32_bf16 v[108:111], v[150:153], v[204:207], v[108:111]
	v_mfma_f32_16x16x32_bf16 v[104:107], v[168:171], v[204:207], v[104:107]
	v_mfma_f32_16x16x32_bf16 v[92:95], v[150:153], v[212:215], v[92:95]
	v_mfma_f32_16x16x32_bf16 v[88:91], v[168:171], v[212:215], v[88:91]
	v_mfma_f32_16x16x32_bf16 v[76:79], v[150:153], v[220:223], v[76:79]
	v_mfma_f32_16x16x32_bf16 v[72:75], v[168:171], v[220:223], v[72:75]
	v_mfma_f32_16x16x32_bf16 v[124:127], v[154:157], v[200:203], v[124:127]
	v_mfma_f32_16x16x32_bf16 v[120:123], v[176:179], v[200:203], v[120:123]
	v_mfma_f32_16x16x32_bf16 v[108:111], v[154:157], v[208:211], v[108:111]
	v_mfma_f32_16x16x32_bf16 v[104:107], v[176:179], v[208:211], v[104:107]
	v_mfma_f32_16x16x32_bf16 v[92:95], v[154:157], v[216:219], v[92:95]
	v_mfma_f32_16x16x32_bf16 v[88:91], v[176:179], v[216:219], v[88:91]
	v_mfma_f32_16x16x32_bf16 v[76:79], v[154:157], v[224:227], v[76:79]
	v_mfma_f32_16x16x32_bf16 v[72:75], v[176:179], v[224:227], v[72:75]
	s_waitcnt vmcnt(8)
	s_barrier
	ds_read_b128 v[150:153], v161
	ds_read_b128 v[154:157], v161 offset:1024
	ds_read_b128 v[168:171], v161 offset:2048
	ds_read_b128 v[176:179], v161 offset:3072
	ds_read_b128 v[196:199], v162 offset:16384
	ds_read_b128 v[200:203], v162 offset:17408
	ds_read_b128 v[204:207], v162 offset:18432
	ds_read_b128 v[208:211], v162 offset:19456
	ds_read_b128 v[212:215], v162 offset:20480
	ds_read_b128 v[216:219], v162 offset:21504
	ds_read_b128 v[220:223], v162 offset:22528
	ds_read_b128 v[224:227], v162 offset:23552
	s_add_u32 s22, s22, 0x80
	s_addc_u32 s23, s23, 0
	s_add_u32 s24, s24, 0x80
	s_addc_u32 s25, s25, 0
	s_add_i32 m0, s0, 0x8000
	s_nop 0
	global_load_lds_dwordx4 v140, s[22:23]
	s_add_i32 m0, s0, 0xa000
	s_nop 0
	global_load_lds_dwordx4 v144, s[22:23]
	s_add_i32 m0, s0, 0x18000
	s_nop 0
	global_load_lds_dwordx4 v142, s[24:25]
	s_add_i32 m0, s0, 0x1a000
	s_nop 0
	global_load_lds_dwordx4 v146, s[24:25]
	s_waitcnt lgkmcnt(0)
	v_mfma_f32_16x16x32_bf16 v[124:127], v[150:153], v[196:199], v[124:127]
	v_mfma_f32_16x16x32_bf16 v[120:123], v[168:171], v[196:199], v[120:123]
	v_mfma_f32_16x16x32_bf16 v[108:111], v[150:153], v[204:207], v[108:111]
	v_mfma_f32_16x16x32_bf16 v[104:107], v[168:171], v[204:207], v[104:107]
	v_mfma_f32_16x16x32_bf16 v[92:95], v[150:153], v[212:215], v[92:95]
	v_mfma_f32_16x16x32_bf16 v[88:91], v[168:171], v[212:215], v[88:91]
	v_mfma_f32_16x16x32_bf16 v[76:79], v[150:153], v[220:223], v[76:79]
	v_mfma_f32_16x16x32_bf16 v[72:75], v[168:171], v[220:223], v[72:75]
	v_mfma_f32_16x16x32_bf16 v[124:127], v[154:157], v[200:203], v[124:127]
	v_mfma_f32_16x16x32_bf16 v[120:123], v[176:179], v[200:203], v[120:123]
	v_mfma_f32_16x16x32_bf16 v[108:111], v[154:157], v[208:211], v[108:111]
	v_mfma_f32_16x16x32_bf16 v[104:107], v[176:179], v[208:211], v[104:107]
	v_mfma_f32_16x16x32_bf16 v[92:95], v[154:157], v[216:219], v[92:95]
	v_mfma_f32_16x16x32_bf16 v[88:91], v[176:179], v[216:219], v[88:91]
	v_mfma_f32_16x16x32_bf16 v[76:79], v[154:157], v[224:227], v[76:79]
	v_mfma_f32_16x16x32_bf16 v[72:75], v[176:179], v[224:227], v[72:75]
	s_waitcnt vmcnt(8)
	s_barrier
	ds_read_b128 v[150:153], v164
	ds_read_b128 v[154:157], v164 offset:1024
	ds_read_b128 v[168:171], v164 offset:2048
	ds_read_b128 v[176:179], v164 offset:3072
	ds_read_b128 v[196:199], v162 offset:49152
	ds_read_b128 v[200:203], v162 offset:50176
	ds_read_b128 v[204:207], v162 offset:51200
	ds_read_b128 v[208:211], v162 offset:52224
	ds_read_b128 v[212:215], v162 offset:53248
	ds_read_b128 v[216:219], v162 offset:54272
	ds_read_b128 v[220:223], v162 offset:55296
	ds_read_b128 v[224:227], v162 offset:56320
	s_add_u32 s22, s22, 0x80
	s_addc_u32 s23, s23, 0
	s_add_u32 s24, s24, 0x80
	s_addc_u32 s25, s25, 0
	s_add_i32 m0, s0, 0x4000
	s_nop 0
	global_load_lds_dwordx4 v140, s[22:23]
	s_add_i32 m0, s0, 0x6000
	s_nop 0
	global_load_lds_dwordx4 v144, s[22:23]
	s_add_i32 m0, s0, 0x14000
	s_nop 0
	global_load_lds_dwordx4 v142, s[24:25]
	s_add_i32 m0, s0, 0x16000
	s_nop 0
	global_load_lds_dwordx4 v146, s[24:25]
	s_waitcnt lgkmcnt(0)
	v_mfma_f32_16x16x32_bf16 v[124:127], v[150:153], v[196:199], v[124:127]
	v_mfma_f32_16x16x32_bf16 v[120:123], v[168:171], v[196:199], v[120:123]
	v_mfma_f32_16x16x32_bf16 v[108:111], v[150:153], v[204:207], v[108:111]
	v_mfma_f32_16x16x32_bf16 v[104:107], v[168:171], v[204:207], v[104:107]
	v_mfma_f32_16x16x32_bf16 v[92:95], v[150:153], v[212:215], v[92:95]
	v_mfma_f32_16x16x32_bf16 v[88:91], v[168:171], v[212:215], v[88:91]
	v_mfma_f32_16x16x32_bf16 v[76:79], v[150:153], v[220:223], v[76:79]
	v_mfma_f32_16x16x32_bf16 v[72:75], v[168:171], v[220:223], v[72:75]
	v_mfma_f32_16x16x32_bf16 v[124:127], v[154:157], v[200:203], v[124:127]
	v_mfma_f32_16x16x32_bf16 v[120:123], v[176:179], v[200:203], v[120:123]
	v_mfma_f32_16x16x32_bf16 v[108:111], v[154:157], v[208:211], v[108:111]
	v_mfma_f32_16x16x32_bf16 v[104:107], v[176:179], v[208:211], v[104:107]
	v_mfma_f32_16x16x32_bf16 v[92:95], v[154:157], v[216:219], v[92:95]
	v_mfma_f32_16x16x32_bf16 v[88:91], v[176:179], v[216:219], v[88:91]
	v_mfma_f32_16x16x32_bf16 v[76:79], v[154:157], v[224:227], v[76:79]
	v_mfma_f32_16x16x32_bf16 v[72:75], v[176:179], v[224:227], v[72:75]
	s_waitcnt vmcnt(8)
	s_barrier
; #define PG8_STAGE(bufoff, gbase, voff) do { _Pragma("unroll") for (int _i = 0; _i < 2; ++_i) \
;         __builtin_amdgcn_global_load_lds((const unsigned*)((const char*)(gbase) + (voff)[_i]), (PG8_LAS unsigned*)(lds + (bufoff) + ldsw + _i * 8192), 16, 0, 0); } while (0)
; #define PG8_LDA(dst, b, h) do { _Pragma("unroll") for (int m = 0; m < 4; ++m) _Pragma("unroll") for (int k = 0; k < 2; ++k) dst[m][k] = *(const PG8_LAS bf16x8*)(lds + PG8_SA(b, h) + aoff + m * 2048 + k * 1024); } while (0)
; #define PG8_LDB(dst, b, h) do { _Pragma("unroll") for (int n = 0; n < 2; ++n) _Pragma("unroll") for (int k = 0; k < 2; ++k) dst[n][k] = *(const PG8_LAS bf16x8*)(lds + PG8_SB(b, h) + boff + n * 2048 + k * 1024); } while (0)
; #define PG8_MMA(ai, bj, At, Bt) do { __builtin_amdgcn_s_setprio(1); _Pragma("unroll") for (int m = 0; m < 4; ++m) _Pragma("unroll") for (int n = 0; n < 2; ++n) _Pragma("unroll") for (int k = 0; k < 2; ++k) \
;         acc[ai][bj][m][n] = __builtin_amdgcn_mfma_f32_16x16x32_bf16(Bt[n][k], At[m][k], acc[ai][bj][m][n], 0, 0, 0); __builtin_amdgcn_s_setprio(0); } while (0)
; #define PG8_WAIT_V(n) asm volatile("s_waitcnt vmcnt(" #n ")" ::: "memory")
; template <class Epi, class Sched, bool ALIGN_EPI = false, bool SP2 = false>
; __device__ __forceinline__ void gemm_phase(PG8_LAS unsigned char* lds, const Gemm g, const Sched& S, const Epi& E) {
;     ...
;             PG8_LDB(B0, 0, 0); PG8_LDB(B1, 0, 1); PG8_SCHED; PG8_LDA(At, 0, 0); PG8_STAGE(PG8_SA(1, 1), a1 + hstep, voffA);
;             PG8_WAIT_V(8); PG8_WAIT_L(0); PG8_BAR; PG8_MMA(0, 0, At, B0); PG8_MMA(0, 1, At, B1); PG8_BAR; PG8_SCHED;
;             PG8_LDA(At, 0, 1); PG8_STAGE(PG8_SB(0, 0), b2, voffB); PG8_STAGE(PG8_SB(0, 1), b2 + hstep, voffB); PG8_STAGE(PG8_SA(0, 0), a2, voffA);
;             PG8_WAIT_V(8); PG8_WAIT_L(0); PG8_BAR; PG8_MMA(1, 0, At, B0); PG8_MMA(1, 1, At, B1); PG8_BAR; PG8_SCHED;
;             PG8_LDB(B0, 1, 0); PG8_LDB(B1, 1, 1); PG8_SCHED; PG8_LDA(At, 1, 0); PG8_STAGE(PG8_SA(0, 1), a2 + hstep, voffA);
;             PG8_WAIT_V(8); PG8_WAIT_L(0); PG8_BAR; PG8_MMA(0, 0, At, B0); PG8_MMA(0, 1, At, B1); PG8_BAR; PG8_SCHED;
;             PG8_LDA(At, 1, 1); PG8_STAGE(PG8_SB(1, 0), b3, voffB); PG8_STAGE(PG8_SB(1, 1), b3 + hstep, voffB); PG8_STAGE(PG8_SA(1, 0), a3, voffA);
;             PG8_WAIT_V(8); PG8_WAIT_L(0); PG8_BAR; PG8_MMA(1, 0, At, B0); PG8_MMA(1, 1, At, B1); PG8_BAR; PG8_SCHED;
	ds_read_b128 v[150:153], v160
	ds_read_b128 v[154:157], v160 offset:1024
	ds_read_b128 v[168:171], v160 offset:2048
	ds_read_b128 v[176:179], v160 offset:3072
	ds_read_b128 v[196:199], v162
	ds_read_b128 v[200:203], v162 offset:1024
	ds_read_b128 v[204:207], v162 offset:2048
	ds_read_b128 v[208:211], v162 offset:3072
	ds_read_b128 v[212:215], v162 offset:4096
	ds_read_b128 v[216:219], v162 offset:5120
	ds_read_b128 v[220:223], v162 offset:6144
	ds_read_b128 v[224:227], v162 offset:7168
	s_add_u32 s22, s22, 0x80
	s_addc_u32 s23, s23, 0
	s_add_u32 s24, s24, 0x80
	s_addc_u32 s25, s25, 0
	s_add_i32 m0, s0, 0xc000
	s_nop 0
	global_load_lds_dwordx4 v140, s[22:23]
	s_add_i32 m0, s0, 0xe000
	s_nop 0
	global_load_lds_dwordx4 v144, s[22:23]
	s_add_i32 m0, s0, 0x1c000
	s_nop 0
	global_load_lds_dwordx4 v142, s[24:25]
	s_add_i32 m0, s0, 0x1e000
	s_nop 0
	global_load_lds_dwordx4 v146, s[24:25]
	s_waitcnt lgkmcnt(0)
	v_mfma_f32_16x16x32_bf16 v[124:127], v[150:153], v[196:199], v[124:127]
	v_mfma_f32_16x16x32_bf16 v[120:123], v[168:171], v[196:199], v[120:123]
	v_mfma_f32_16x16x32_bf16 v[108:111], v[150:153], v[204:207], v[108:111]
	v_mfma_f32_16x16x32_bf16 v[104:107], v[168:171], v[204:207], v[104:107]
	v_mfma_f32_16x16x32_bf16 v[92:95], v[150:153], v[212:215], v[92:95]
	v_mfma_f32_16x16x32_bf16 v[88:91], v[168:171], v[212:215], v[88:91]
	v_mfma_f32_16x16x32_bf16 v[76:79], v[150:153], v[220:223], v[76:79]
	v_mfma_f32_16x16x32_bf16 v[72:75], v[168:171], v[220:223], v[72:75]
	v_mfma_f32_16x16x32_bf16 v[124:127], v[154:157], v[200:203], v[124:127]
	v_mfma_f32_16x16x32_bf16 v[120:123], v[176:179], v[200:203], v[120:123]
	v_mfma_f32_16x16x32_bf16 v[108:111], v[154:157], v[208:211], v[108:111]
	v_mfma_f32_16x16x32_bf16 v[104:107], v[176:179], v[208:211], v[104:107]
	v_mfma_f32_16x16x32_bf16 v[92:95], v[154:157], v[216:219], v[92:95]
	v_mfma_f32_16x16x32_bf16 v[88:91], v[176:179], v[216:219], v[88:91]
	v_mfma_f32_16x16x32_bf16 v[76:79], v[154:157], v[224:227], v[76:79]
	v_mfma_f32_16x16x32_bf16 v[72:75], v[176:179], v[224:227], v[72:75]
	s_waitcnt vmcnt(8)
	s_barrier
	ds_read_b128 v[150:153], v163
	ds_read_b128 v[154:157], v163 offset:1024
	ds_read_b128 v[168:171], v163 offset:2048
	ds_read_b128 v[176:179], v163 offset:3072
	ds_read_b128 v[196:199], v162 offset:32768
	ds_read_b128 v[200:203], v162 offset:33792
	ds_read_b128 v[204:207], v162 offset:34816
	ds_read_b128 v[208:211], v162 offset:35840
	ds_read_b128 v[212:215], v162 offset:36864
	ds_read_b128 v[216:219], v162 offset:37888
	ds_read_b128 v[220:223], v162 offset:38912
	ds_read_b128 v[224:227], v162 offset:39936
	s_add_u32 s22, s22, 0x80
	s_addc_u32 s23, s23, 0
	s_add_u32 s24, s24, 0x80
	s_addc_u32 s25, s25, 0
	s_mov_b32 m0, s0
	s_nop 0
	global_load_lds_dwordx4 v140, s[22:23]
	s_add_i32 m0, s0, 0x2000
	s_nop 0
	global_load_lds_dwordx4 v144, s[22:23]
	s_add_i32 m0, s0, 0x10000
	s_nop 0
	global_load_lds_dwordx4 v142, s[24:25]
	s_add_i32 m0, s0, 0x12000
	s_nop 0
	global_load_lds_dwordx4 v146, s[24:25]
	s_waitcnt lgkmcnt(0)
	v_mfma_f32_16x16x32_bf16 v[124:127], v[150:153], v[196:199], v[124:127]
	v_mfma_f32_16x16x32_bf16 v[120:123], v[168:171], v[196:199], v[120:123]
	v_mfma_f32_16x16x32_bf16 v[108:111], v[150:153], v[204:207], v[108:111]
	v_mfma_f32_16x16x32_bf16 v[104:107], v[168:171], v[204:207], v[104:107]
	v_mfma_f32_16x16x32_bf16 v[92:95], v[150:153], v[212:215], v[92:95]
	v_mfma_f32_16x16x32_bf16 v[88:91], v[168:171], v[212:215], v[88:91]
	v_mfma_f32_16x16x32_bf16 v[76:79], v[150:153], v[220:223], v[76:79]
	v_mfma_f32_16x16x32_bf16 v[72:75], v[168:171], v[220:223], v[72:75]
	v_mfma_f32_16x16x32_bf16 v[124:127], v[154:157], v[200:203], v[124:127]
	v_mfma_f32_16x16x32_bf16 v[120:123], v[176:179], v[200:203], v[120:123]
	v_mfma_f32_16x16x32_bf16 v[108:111], v[154:157], v[208:211], v[108:111]
	v_mfma_f32_16x16x32_bf16 v[104:107], v[176:179], v[208:211], v[104:107]
	v_mfma_f32_16x16x32_bf16 v[92:95], v[154:157], v[216:219], v[92:95]
	v_mfma_f32_16x16x32_bf16 v[88:91], v[176:179], v[216:219], v[88:91]
	v_mfma_f32_16x16x32_bf16 v[76:79], v[154:157], v[224:227], v[76:79]
	v_mfma_f32_16x16x32_bf16 v[72:75], v[176:179], v[224:227], v[72:75]
	s_waitcnt vmcnt(8)
	s_barrier
	ds_read_b128 v[150:153], v161
	ds_read_b128 v[154:157], v161 offset:1024
	ds_read_b128 v[168:171], v161 offset:2048
	ds_read_b128 v[176:179], v161 offset:3072
	ds_read_b128 v[196:199], v162 offset:16384
	ds_read_b128 v[200:203], v162 offset:17408
	ds_read_b128 v[204:207], v162 offset:18432
	ds_read_b128 v[208:211], v162 offset:19456
	ds_read_b128 v[212:215], v162 offset:20480
	ds_read_b128 v[216:219], v162 offset:21504
	ds_read_b128 v[220:223], v162 offset:22528
	ds_read_b128 v[224:227], v162 offset:23552
	s_add_u32 s22, s22, 0x80
	s_addc_u32 s23, s23, 0
	s_add_u32 s24, s24, 0x80
	s_addc_u32 s25, s25, 0
	s_add_i32 m0, s0, 0x8000
	s_nop 0
	global_load_lds_dwordx4 v140, s[22:23]
	s_add_i32 m0, s0, 0xa000
	s_nop 0
	global_load_lds_dwordx4 v144, s[22:23]
	s_add_i32 m0, s0, 0x18000
	s_nop 0
	global_load_lds_dwordx4 v142, s[24:25]
	s_add_i32 m0, s0, 0x1a000
	s_nop 0
	global_load_lds_dwordx4 v146, s[24:25]
	s_waitcnt lgkmcnt(0)
	v_mfma_f32_16x16x32_bf16 v[124:127], v[150:153], v[196:199], v[124:127]
	v_mfma_f32_16x16x32_bf16 v[120:123], v[168:171], v[196:199], v[120:123]
	v_mfma_f32_16x16x32_bf16 v[108:111], v[150:153], v[204:207], v[108:111]
	v_mfma_f32_16x16x32_bf16 v[104:107], v[168:171], v[204:207], v[104:107]
	v_mfma_f32_16x16x32_bf16 v[92:95], v[150:153], v[212:215], v[92:95]
	v_mfma_f32_16x16x32_bf16 v[88:91], v[168:171], v[212:215], v[88:91]
	v_mfma_f32_16x16x32_bf16 v[76:79], v[150:153], v[220:223], v[76:79]
	v_mfma_f32_16x16x32_bf16 v[72:75], v[168:171], v[220:223], v[72:75]
	v_mfma_f32_16x16x32_bf16 v[124:127], v[154:157], v[200:203], v[124:127]
	v_mfma_f32_16x16x32_bf16 v[120:123], v[176:179], v[200:203], v[120:123]
	v_mfma_f32_16x16x32_bf16 v[108:111], v[154:157], v[208:211], v[108:111]
	v_mfma_f32_16x16x32_bf16 v[104:107], v[176:179], v[208:211], v[104:107]
	v_mfma_f32_16x16x32_bf16 v[92:95], v[154:157], v[216:219], v[92:95]
	v_mfma_f32_16x16x32_bf16 v[88:91], v[176:179], v[216:219], v[88:91]
	v_mfma_f32_16x16x32_bf16 v[76:79], v[154:157], v[224:227], v[76:79]
	v_mfma_f32_16x16x32_bf16 v[72:75], v[176:179], v[224:227], v[72:75]
	s_waitcnt vmcnt(8)
	s_barrier
; #define PG8_STAGE(bufoff, gbase, voff) do { _Pragma("unroll") for (int _i = 0; _i < 2; ++_i) \
;         __builtin_amdgcn_global_load_lds((const unsigned*)((const char*)(gbase) + (voff)[_i]), (PG8_LAS unsigned*)(lds + (bufoff) + ldsw + _i * 8192), 16, 0, 0); } while (0)
; #define PG8_LDA(dst, b, h) do { _Pragma("unroll") for (int m = 0; m < 4; ++m) _Pragma("unroll") for (int k = 0; k < 2; ++k) dst[m][k] = *(const PG8_LAS bf16x8*)(lds + PG8_SA(b, h) + aoff + m * 2048 + k * 1024); } while (0)
; #define PG8_LDB(dst, b, h) do { _Pragma("unroll") for (int n = 0; n < 2; ++n) _Pragma("unroll") for (int k = 0; k < 2; ++k) dst[n][k] = *(const PG8_LAS bf16x8*)(lds + PG8_SB(b, h) + boff + n * 2048 + k * 1024); } while (0)
; #define PG8_MMA(ai, bj, At, Bt) do { __builtin_amdgcn_s_setprio(1); _Pragma("unroll") for (int m = 0; m < 4; ++m) _Pragma("unroll") for (int n = 0; n < 2; ++n) _Pragma("unroll") for (int k = 0; k < 2; ++k) \
;         acc[ai][bj][m][n] = __builtin_amdgcn_mfma_f32_16x16x32_bf16(Bt[n][k], At[m][k], acc[ai][bj][m][n], 0, 0, 0); __builtin_amdgcn_s_setprio(0); } while (0)
; #define PG8_WAIT_V(n) asm volatile("s_waitcnt vmcnt(" #n ")" ::: "memory")
; template <class Epi, class Sched, bool ALIGN_EPI = false, bool SP2 = false>
; __device__ __forceinline__ void gemm_phase(PG8_LAS unsigned char* lds, const Gemm g, const Sched& S, const Epi& E) {
;     ...
;             PG8_LDB(B0, 0, 0); PG8_LDB(B1, 0, 1); PG8_SCHED; PG8_LDA(At, 0, 0); PG8_STAGE(PG8_SA(1, 1), a1 + hstep, voffA);
;             PG8_WAIT_V(8); PG8_WAIT_L(0); PG8_BAR; PG8_MMA(0, 0, At, B0); PG8_MMA(0, 1, At, B1); PG8_BAR; PG8_SCHED;
;             PG8_LDA(At, 0, 1); PG8_STAGE(PG8_SB(0, 0), b2, voffB); PG8_STAGE(PG8_SB(0, 1), b2 + hstep, voffB); PG8_STAGE(PG8_SA(0, 0), a2, voffA);
;             PG8_WAIT_V(8); PG8_WAIT_L(0); PG8_BAR; PG8_MMA(1, 0, At, B0); PG8_MMA(1, 1, At, B1); PG8_BAR; PG8_SCHED;
;             PG8_LDB(B0, 1, 0); PG8_LDB(B1, 1, 1); PG8_SCHED; PG8_LDA(At, 1, 0); PG8_STAGE(PG8_SA(0, 1), a2 + hstep, voffA);
;             PG8_WAIT_V(8); PG8_WAIT_L(0); PG8_BAR; PG8_MMA(0, 0, At, B0); PG8_MMA(0, 1, At, B1); PG8_BAR; PG8_SCHED;
;             PG8_LDA(At, 1, 1); PG8_STAGE(PG8_SB(1, 0), b3, voffB); PG8_STAGE(PG8_SB(1, 1), b3 + hstep, voffB); PG8_STAGE(PG8_SA(1, 0), a3, voffA);
;             PG8_WAIT_V(8); PG8_WAIT_L(0); PG8_BAR; PG8_MMA(1, 0, At, B0); PG8_MMA(1, 1, At, B1); PG8_BAR; PG8_SCHED;
	ds_read_b128 v[150:153], v164
	ds_read_b128 v[154:157], v164 offset:1024
	ds_read_b128 v[168:171], v164 offset:2048
	ds_read_b128 v[176:179], v164 offset:3072
	ds_read_b128 v[196:199], v162 offset:49152
	ds_read_b128 v[200:203], v162 offset:50176
	ds_read_b128 v[204:207], v162 offset:51200
	ds_read_b128 v[208:211], v162 offset:52224
	ds_read_b128 v[212:215], v162 offset:53248
	ds_read_b128 v[216:219], v162 offset:54272
	ds_read_b128 v[220:223], v162 offset:55296
	ds_read_b128 v[224:227], v162 offset:56320
	s_add_u32 s22, s22, 0x80
	s_addc_u32 s23, s23, 0
	s_add_u32 s24, s24, 0x80
	s_addc_u32 s25, s25, 0
	s_add_i32 m0, s0, 0x4000
	s_nop 0
	global_load_lds_dwordx4 v140, s[22:23]
	s_add_i32 m0, s0, 0x6000
	s_nop 0
	global_load_lds_dwordx4 v144, s[22:23]
	s_add_i32 m0, s0, 0x14000
	s_nop 0
	global_load_lds_dwordx4 v142, s[24:25]
	s_add_i32 m0, s0, 0x16000
	s_nop 0
	global_load_lds_dwordx4 v146, s[24:25]
	s_waitcnt lgkmcnt(0)
	v_mfma_f32_16x16x32_bf16 v[124:127], v[150:153], v[196:199], v[124:127]
	v_mfma_f32_16x16x32_bf16 v[120:123], v[168:171], v[196:199], v[120:123]
	v_mfma_f32_16x16x32_bf16 v[108:111], v[150:153], v[204:207], v[108:111]
	v_mfma_f32_16x16x32_bf16 v[104:107], v[168:171], v[204:207], v[104:107]
	v_mfma_f32_16x16x32_bf16 v[92:95], v[150:153], v[212:215], v[92:95]
	v_mfma_f32_16x16x32_bf16 v[88:91], v[168:171], v[212:215], v[88:91]
	v_mfma_f32_16x16x32_bf16 v[76:79], v[150:153], v[220:223], v[76:79]
	v_mfma_f32_16x16x32_bf16 v[72:75], v[168:171], v[220:223], v[72:75]
	v_mfma_f32_16x16x32_bf16 v[124:127], v[154:157], v[200:203], v[124:127]
	v_mfma_f32_16x16x32_bf16 v[120:123], v[176:179], v[200:203], v[120:123]
	v_mfma_f32_16x16x32_bf16 v[108:111], v[154:157], v[208:211], v[108:111]
	v_mfma_f32_16x16x32_bf16 v[104:107], v[176:179], v[208:211], v[104:107]
	v_mfma_f32_16x16x32_bf16 v[92:95], v[154:157], v[216:219], v[92:95]
	v_mfma_f32_16x16x32_bf16 v[88:91], v[176:179], v[216:219], v[88:91]
	v_mfma_f32_16x16x32_bf16 v[76:79], v[154:157], v[224:227], v[76:79]
	v_mfma_f32_16x16x32_bf16 v[72:75], v[176:179], v[224:227], v[72:75]
	s_waitcnt vmcnt(8)
	s_barrier
	ds_read_b128 v[150:153], v160
	ds_read_b128 v[154:157], v160 offset:1024
	ds_read_b128 v[168:171], v160 offset:2048
	ds_read_b128 v[176:179], v160 offset:3072
	ds_read_b128 v[196:199], v162
	ds_read_b128 v[200:203], v162 offset:1024
	ds_read_b128 v[204:207], v162 offset:2048
	ds_read_b128 v[208:211], v162 offset:3072
	ds_read_b128 v[212:215], v162 offset:4096
	ds_read_b128 v[216:219], v162 offset:5120
	ds_read_b128 v[220:223], v162 offset:6144
	ds_read_b128 v[224:227], v162 offset:7168
	s_add_u32 s22, s22, 0x80
	s_addc_u32 s23, s23, 0
	s_add_u32 s24, s24, 0x80
	s_addc_u32 s25, s25, 0
	s_add_i32 m0, s0, 0xc000
	s_nop 0
	global_load_lds_dwordx4 v140, s[22:23]
	s_add_i32 m0, s0, 0xe000
	s_nop 0
	global_load_lds_dwordx4 v144, s[22:23]
	s_add_i32 m0, s0, 0x1c000
	s_nop 0
	global_load_lds_dwordx4 v142, s[24:25]
	s_add_i32 m0, s0, 0x1e000
	s_nop 0
	global_load_lds_dwordx4 v146, s[24:25]
	s_waitcnt lgkmcnt(0)
	v_mfma_f32_16x16x32_bf16 v[124:127], v[150:153], v[196:199], v[124:127]
	v_mfma_f32_16x16x32_bf16 v[120:123], v[168:171], v[196:199], v[120:123]
	v_mfma_f32_16x16x32_bf16 v[108:111], v[150:153], v[204:207], v[108:111]
	v_mfma_f32_16x16x32_bf16 v[104:107], v[168:171], v[204:207], v[104:107]
	v_mfma_f32_16x16x32_bf16 v[92:95], v[150:153], v[212:215], v[92:95]
	v_mfma_f32_16x16x32_bf16 v[88:91], v[168:171], v[212:215], v[88:91]
	v_mfma_f32_16x16x32_bf16 v[76:79], v[150:153], v[220:223], v[76:79]
	v_mfma_f32_16x16x32_bf16 v[72:75], v[168:171], v[220:223], v[72:75]
	v_mfma_f32_16x16x32_bf16 v[124:127], v[154:157], v[200:203], v[124:127]
	v_mfma_f32_16x16x32_bf16 v[120:123], v[176:179], v[200:203], v[120:123]
	v_mfma_f32_16x16x32_bf16 v[108:111], v[154:157], v[208:211], v[108:111]
	v_mfma_f32_16x16x32_bf16 v[104:107], v[176:179], v[208:211], v[104:107]
	v_mfma_f32_16x16x32_bf16 v[92:95], v[154:157], v[216:219], v[92:95]
	v_mfma_f32_16x16x32_bf16 v[88:91], v[176:179], v[216:219], v[88:91]
	v_mfma_f32_16x16x32_bf16 v[76:79], v[154:157], v[224:227], v[76:79]
	v_mfma_f32_16x16x32_bf16 v[72:75], v[176:179], v[224:227], v[72:75]
	s_waitcnt vmcnt(8)
	s_barrier
	ds_read_b128 v[150:153], v163
	ds_read_b128 v[154:157], v163 offset:1024
	ds_read_b128 v[168:171], v163 offset:2048
	ds_read_b128 v[176:179], v163 offset:3072
	ds_read_b128 v[196:199], v162 offset:32768
	ds_read_b128 v[200:203], v162 offset:33792
	ds_read_b128 v[204:207], v162 offset:34816
	ds_read_b128 v[208:211], v162 offset:35840
	ds_read_b128 v[212:215], v162 offset:36864
	ds_read_b128 v[216:219], v162 offset:37888
	ds_read_b128 v[220:223], v162 offset:38912
	ds_read_b128 v[224:227], v162 offset:39936
	s_waitcnt lgkmcnt(0)
	v_mfma_f32_16x16x32_bf16 v[124:127], v[150:153], v[196:199], v[124:127]
	v_mfma_f32_16x16x32_bf16 v[120:123], v[168:171], v[196:199], v[120:123]
	v_mfma_f32_16x16x32_bf16 v[108:111], v[150:153], v[204:207], v[108:111]
	v_mfma_f32_16x16x32_bf16 v[104:107], v[168:171], v[204:207], v[104:107]
	v_mfma_f32_16x16x32_bf16 v[92:95], v[150:153], v[212:215], v[92:95]
	v_mfma_f32_16x16x32_bf16 v[88:91], v[168:171], v[212:215], v[88:91]
	v_mfma_f32_16x16x32_bf16 v[76:79], v[150:153], v[220:223], v[76:79]
	v_mfma_f32_16x16x32_bf16 v[72:75], v[168:171], v[220:223], v[72:75]
	v_mfma_f32_16x16x32_bf16 v[124:127], v[154:157], v[200:203], v[124:127]
	v_mfma_f32_16x16x32_bf16 v[120:123], v[176:179], v[200:203], v[120:123]
	v_mfma_f32_16x16x32_bf16 v[108:111], v[154:157], v[208:211], v[108:111]
	v_mfma_f32_16x16x32_bf16 v[104:107], v[176:179], v[208:211], v[104:107]
	v_mfma_f32_16x16x32_bf16 v[92:95], v[154:157], v[216:219], v[92:95]
	v_mfma_f32_16x16x32_bf16 v[88:91], v[176:179], v[216:219], v[88:91]
	v_mfma_f32_16x16x32_bf16 v[76:79], v[154:157], v[224:227], v[76:79]
	v_mfma_f32_16x16x32_bf16 v[72:75], v[176:179], v[224:227], v[72:75]
	s_waitcnt vmcnt(4)
	s_barrier
; #define PG8_STAGE(bufoff, gbase, voff) do { _Pragma("unroll") for (int _i = 0; _i < 2; ++_i) \
;         __builtin_amdgcn_global_load_lds((const unsigned*)((const char*)(gbase) + (voff)[_i]), (PG8_LAS unsigned*)(lds + (bufoff) + ldsw + _i * 8192), 16, 0, 0); } while (0)
; #define PG8_LDA(dst, b, h) do { _Pragma("unroll") for (int m = 0; m < 4; ++m) _Pragma("unroll") for (int k = 0; k < 2; ++k) dst[m][k] = *(const PG8_LAS bf16x8*)(lds + PG8_SA(b, h) + aoff + m * 2048 + k * 1024); } while (0)
; #define PG8_LDB(dst, b, h) do { _Pragma("unroll") for (int n = 0; n < 2; ++n) _Pragma("unroll") for (int k = 0; k < 2; ++k) dst[n][k] = *(const PG8_LAS bf16x8*)(lds + PG8_SB(b, h) + boff + n * 2048 + k * 1024); } while (0)
; #define PG8_MMA(ai, bj, At, Bt) do { __builtin_amdgcn_s_setprio(1); _Pragma("unroll") for (int m = 0; m < 4; ++m) _Pragma("unroll") for (int n = 0; n < 2; ++n) _Pragma("unroll") for (int k = 0; k < 2; ++k) \
;         acc[ai][bj][m][n] = __builtin_amdgcn_mfma_f32_16x16x32_bf16(Bt[n][k], At[m][k], acc[ai][bj][m][n], 0, 0, 0); __builtin_amdgcn_s_setprio(0); } while (0)
; #define PG8_WAIT_V(n) asm volatile("s_waitcnt vmcnt(" #n ")" ::: "memory")
; template <class Epi, class Sched, bool ALIGN_EPI = false, bool SP2 = false>
; __device__ __forceinline__ void gemm_phase(PG8_LAS unsigned char* lds, const Gemm g, const Sched& S, const Epi& E) {
;     ...
;             PG8_LDB(B0, 0, 0); PG8_LDB(B1, 0, 1); PG8_SCHED; PG8_LDA(At, 0, 0); PG8_STAGE(PG8_SA(1, 1), a1 + hstep, voffA);
;             PG8_WAIT_V(8); PG8_WAIT_L(0); PG8_BAR; PG8_MMA(0, 0, At, B0); PG8_MMA(0, 1, At, B1); PG8_BAR; PG8_SCHED;
;             PG8_LDA(At, 0, 1); PG8_STAGE(PG8_SB(0, 0), b2, voffB); PG8_STAGE(PG8_SB(0, 1), b2 + hstep, voffB); PG8_STAGE(PG8_SA(0, 0), a2, voffA);
;             PG8_WAIT_V(8); PG8_WAIT_L(0); PG8_BAR; PG8_MMA(1, 0, At, B0); PG8_MMA(1, 1, At, B1); PG8_BAR; PG8_SCHED;
;             PG8_LDB(B0, 1, 0); PG8_LDB(B1, 1, 1); PG8_SCHED; PG8_LDA(At, 1, 0); PG8_STAGE(PG8_SA(0, 1), a2 + hstep, voffA);
;             PG8_WAIT_V(8); PG8_WAIT_L(0); PG8_BAR; PG8_MMA(0, 0, At, B0); PG8_MMA(0, 1, At, B1); PG8_BAR; PG8_SCHED;
;             PG8_LDA(At, 1, 1); PG8_STAGE(PG8_SB(1, 0), b3, voffB); PG8_STAGE(PG8_SB(1, 1), b3 + hstep, voffB); PG8_STAGE(PG8_SA(1, 0), a3, voffA);
;             PG8_WAIT_V(8); PG8_WAIT_L(0); PG8_BAR; PG8_MMA(1, 0, At, B0); PG8_MMA(1, 1, At, B1); PG8_BAR; PG8_SCHED;
	ds_read_b128 v[150:153], v161
	ds_read_b128 v[154:157], v161 offset:1024
	ds_read_b128 v[168:171], v161 offset:2048
	ds_read_b128 v[176:179], v161 offset:3072
	ds_read_b128 v[196:199], v162 offset:16384
	ds_read_b128 v[200:203], v162 offset:17408
	ds_read_b128 v[204:207], v162 offset:18432
	ds_read_b128 v[208:211], v162 offset:19456
	ds_read_b128 v[212:215], v162 offset:20480
	ds_read_b128 v[216:219], v162 offset:21504
	ds_read_b128 v[220:223], v162 offset:22528
	ds_read_b128 v[224:227], v162 offset:23552
	s_waitcnt lgkmcnt(0)
	v_mfma_f32_16x16x32_bf16 v[124:127], v[150:153], v[196:199], v[124:127]
	v_mfma_f32_16x16x32_bf16 v[120:123], v[168:171], v[196:199], v[120:123]
	v_mfma_f32_16x16x32_bf16 v[108:111], v[150:153], v[204:207], v[108:111]
	v_mfma_f32_16x16x32_bf16 v[104:107], v[168:171], v[204:207], v[104:107]
	v_mfma_f32_16x16x32_bf16 v[92:95], v[150:153], v[212:215], v[92:95]
	v_mfma_f32_16x16x32_bf16 v[88:91], v[168:171], v[212:215], v[88:91]
	v_mfma_f32_16x16x32_bf16 v[76:79], v[150:153], v[220:223], v[76:79]
	v_mfma_f32_16x16x32_bf16 v[72:75], v[168:171], v[220:223], v[72:75]
	v_mfma_f32_16x16x32_bf16 v[124:127], v[154:157], v[200:203], v[124:127]
	v_mfma_f32_16x16x32_bf16 v[120:123], v[176:179], v[200:203], v[120:123]
	v_mfma_f32_16x16x32_bf16 v[108:111], v[154:157], v[208:211], v[108:111]
	v_mfma_f32_16x16x32_bf16 v[104:107], v[176:179], v[208:211], v[104:107]
	v_mfma_f32_16x16x32_bf16 v[92:95], v[154:157], v[216:219], v[92:95]
	v_mfma_f32_16x16x32_bf16 v[88:91], v[176:179], v[216:219], v[88:91]
	v_mfma_f32_16x16x32_bf16 v[76:79], v[154:157], v[224:227], v[76:79]
	v_mfma_f32_16x16x32_bf16 v[72:75], v[176:179], v[224:227], v[72:75]
	s_waitcnt vmcnt(0)
	s_barrier
	ds_read_b128 v[150:153], v164
	ds_read_b128 v[154:157], v164 offset:1024
	ds_read_b128 v[168:171], v164 offset:2048
	ds_read_b128 v[176:179], v164 offset:3072
	ds_read_b128 v[196:199], v162 offset:49152
	ds_read_b128 v[200:203], v162 offset:50176
	ds_read_b128 v[204:207], v162 offset:51200
	ds_read_b128 v[208:211], v162 offset:52224
	ds_read_b128 v[212:215], v162 offset:53248
	ds_read_b128 v[216:219], v162 offset:54272
	ds_read_b128 v[220:223], v162 offset:55296
	ds_read_b128 v[224:227], v162 offset:56320
	s_waitcnt lgkmcnt(0)
	v_mfma_f32_16x16x32_bf16 v[124:127], v[150:153], v[196:199], v[124:127]
	v_mfma_f32_16x16x32_bf16 v[120:123], v[168:171], v[196:199], v[120:123]
	v_mfma_f32_16x16x32_bf16 v[108:111], v[150:153], v[204:207], v[108:111]
	v_mfma_f32_16x16x32_bf16 v[104:107], v[168:171], v[204:207], v[104:107]
	v_mfma_f32_16x16x32_bf16 v[92:95], v[150:153], v[212:215], v[92:95]
	v_mfma_f32_16x16x32_bf16 v[88:91], v[168:171], v[212:215], v[88:91]
	v_mfma_f32_16x16x32_bf16 v[76:79], v[150:153], v[220:223], v[76:79]
	v_mfma_f32_16x16x32_bf16 v[72:75], v[168:171], v[220:223], v[72:75]
	v_mfma_f32_16x16x32_bf16 v[124:127], v[154:157], v[200:203], v[124:127]
	v_mfma_f32_16x16x32_bf16 v[120:123], v[176:179], v[200:203], v[120:123]
	v_mfma_f32_16x16x32_bf16 v[108:111], v[154:157], v[208:211], v[108:111]
	v_mfma_f32_16x16x32_bf16 v[104:107], v[176:179], v[208:211], v[104:107]
	v_mfma_f32_16x16x32_bf16 v[92:95], v[154:157], v[216:219], v[92:95]
	v_mfma_f32_16x16x32_bf16 v[88:91], v[176:179], v[216:219], v[88:91]
	v_mfma_f32_16x16x32_bf16 v[76:79], v[154:157], v[224:227], v[76:79]
	v_mfma_f32_16x16x32_bf16 v[72:75], v[176:179], v[224:227], v[72:75]
	s_branch .LBB0_620
.Lp3q_lean_q1:
	s_mov_b32 s22, s94
	s_mov_b32 s23, 0
	s_lshl_b64 s[22:23], s[22:23], 19
	s_add_u32 s22, s22, s70
	s_addc_u32 s23, s23, s71
	s_add_u32 s22, s22, 0x80
	s_addc_u32 s23, s23, 0
	s_mov_b32 s24, s42
	s_mov_b32 s25, 0
	s_lshl_b64 s[24:25], s[24:25], 19
	s_add_u32 s24, s24, s64
	s_addc_u32 s25, s25, s65
	s_add_u32 s24, s24, 0x80
	s_addc_u32 s25, s25, 0
	s_add_u32 s24, s24, 0x40000
	s_addc_u32 s25, s25, 0
	s_waitcnt vmcnt(0) lgkmcnt(0)
	s_barrier
	s_add_u32 s22, s22, 0x80
	s_addc_u32 s23, s23, 0
	s_add_u32 s24, s24, 0x80
	s_addc_u32 s25, s25, 0
	s_add_i32 m0, s0, 0x4000
	s_nop 0
	global_load_lds_dwordx4 v140, s[22:23]
	s_add_i32 m0, s0, 0x6000
	s_nop 0
	global_load_lds_dwordx4 v144, s[22:23]
	s_add_i32 m0, s0, 0x10000
	s_nop 0
	global_load_lds_dwordx4 v142, s[24:25]
	s_add_i32 m0, s0, 0x12000
	s_nop 0
	global_load_lds_dwordx4 v146, s[24:25]
	s_add_u32 s22, s22, 0x80
	s_addc_u32 s23, s23, 0
	s_add_u32 s24, s24, 0x80
	s_addc_u32 s25, s25, 0
	s_add_i32 m0, s0, 0xc000
	s_nop 0
	global_load_lds_dwordx4 v140, s[22:23]
	s_add_i32 m0, s0, 0xe000
	s_nop 0
	global_load_lds_dwordx4 v144, s[22:23]
	s_add_i32 m0, s0, 0x18000
	s_nop 0
	global_load_lds_dwordx4 v142, s[24:25]
	s_add_i32 m0, s0, 0x1a000
	s_nop 0
	global_load_lds_dwordx4 v146, s[24:25]
	ds_read_b128 v[180:183], v161
	ds_read_b128 v[184:187], v161 offset:1024
	ds_read_b128 v[188:191], v161 offset:2048
	ds_read_b128 v[192:195], v161 offset:3072
	ds_read_b128 v[196:199], v162
	ds_read_b128 v[200:203], v162 offset:1024
	ds_read_b128 v[204:207], v162 offset:2048
	ds_read_b128 v[208:211], v162 offset:3072
	ds_read_b128 v[212:215], v162 offset:4096
	ds_read_b128 v[216:219], v162 offset:5120
	ds_read_b128 v[220:223], v162 offset:6144
	ds_read_b128 v[224:227], v162 offset:7168
	s_waitcnt lgkmcnt(0)
	v_mfma_f32_16x16x32_bf16 v[116:119], v[180:183], v[196:199], v[116:119]
	v_mfma_f32_16x16x32_bf16 v[112:115], v[188:191], v[196:199], v[112:115]
	v_mfma_f32_16x16x32_bf16 v[100:103], v[180:183], v[204:207], v[100:103]
	v_mfma_f32_16x16x32_bf16 v[96:99], v[188:191], v[204:207], v[96:99]
	v_mfma_f32_16x16x32_bf16 v[84:87], v[180:183], v[212:215], v[84:87]
	v_mfma_f32_16x16x32_bf16 v[80:83], v[188:191], v[212:215], v[80:83]
	v_mfma_f32_16x16x32_bf16 v[68:71], v[180:183], v[220:223], v[68:71]
	v_mfma_f32_16x16x32_bf16 v[64:67], v[188:191], v[220:223], v[64:67]
	v_mfma_f32_16x16x32_bf16 v[116:119], v[184:187], v[200:203], v[116:119]
	v_mfma_f32_16x16x32_bf16 v[112:115], v[192:195], v[200:203], v[112:115]
	v_mfma_f32_16x16x32_bf16 v[100:103], v[184:187], v[208:211], v[100:103]
	v_mfma_f32_16x16x32_bf16 v[96:99], v[192:195], v[208:211], v[96:99]
	v_mfma_f32_16x16x32_bf16 v[84:87], v[184:187], v[216:219], v[84:87]
	v_mfma_f32_16x16x32_bf16 v[80:83], v[192:195], v[216:219], v[80:83]
	v_mfma_f32_16x16x32_bf16 v[68:71], v[184:187], v[224:227], v[68:71]
	v_mfma_f32_16x16x32_bf16 v[64:67], v[192:195], v[224:227], v[64:67]
	s_waitcnt vmcnt(8)
	s_barrier
; #define PG8_STAGE(bufoff, gbase, voff) do { _Pragma("unroll") for (int _i = 0; _i < 2; ++_i) \
;         __builtin_amdgcn_global_load_lds((const unsigned*)((const char*)(gbase) + (voff)[_i]), (PG8_LAS unsigned*)(lds + (bufoff) + ldsw + _i * 8192), 16, 0, 0); } while (0)
; #define PG8_LDA(dst, b, h) do { _Pragma("unroll") for (int m = 0; m < 4; ++m) _Pragma("unroll") for (int k = 0; k < 2; ++k) dst[m][k] = *(const PG8_LAS bf16x8*)(lds + PG8_SA(b, h) + aoff + m * 2048 + k * 1024); } while (0)
; #define PG8_LDB(dst, b, h) do { _Pragma("unroll") for (int n = 0; n < 2; ++n) _Pragma("unroll") for (int k = 0; k < 2; ++k) dst[n][k] = *(const PG8_LAS bf16x8*)(lds + PG8_SB(b, h) + boff + n * 2048 + k * 1024); } while (0)
; #define PG8_MMA(ai, bj, At, Bt) do { __builtin_amdgcn_s_setprio(1); _Pragma("unroll") for (int m = 0; m < 4; ++m) _Pragma("unroll") for (int n = 0; n < 2; ++n) _Pragma("unroll") for (int k = 0; k < 2; ++k) \
;         acc[ai][bj][m][n] = __builtin_amdgcn_mfma_f32_16x16x32_bf16(Bt[n][k], At[m][k], acc[ai][bj][m][n], 0, 0, 0); __builtin_amdgcn_s_setprio(0); } while (0)
; #define PG8_WAIT_V(n) asm volatile("s_waitcnt vmcnt(" #n ")" ::: "memory")
; template <class Epi, class Sched, bool ALIGN_EPI = false, bool SP2 = false>
; __device__ __forceinline__ void gemm_phase(PG8_LAS unsigned char* lds, const Gemm g, const Sched& S, const Epi& E) {
;     ...
;             PG8_LDB(B0, 0, 0); PG8_LDB(B1, 0, 1); PG8_SCHED; PG8_LDA(At, 0, 0); PG8_STAGE(PG8_SA(1, 1), a1 + hstep, voffA);
;             PG8_WAIT_V(8); PG8_WAIT_L(0); PG8_BAR; PG8_MMA(0, 0, At, B0); PG8_MMA(0, 1, At, B1); PG8_BAR; PG8_SCHED;
;             PG8_LDA(At, 0, 1); PG8_STAGE(PG8_SB(0, 0), b2, voffB); PG8_STAGE(PG8_SB(0, 1), b2 + hstep, voffB); PG8_STAGE(PG8_SA(0, 0), a2, voffA);
;             PG8_WAIT_V(8); PG8_WAIT_L(0); PG8_BAR; PG8_MMA(1, 0, At, B0); PG8_MMA(1, 1, At, B1); PG8_BAR; PG8_SCHED;
;             PG8_LDB(B0, 1, 0); PG8_LDB(B1, 1, 1); PG8_SCHED; PG8_LDA(At, 1, 0); PG8_STAGE(PG8_SA(0, 1), a2 + hstep, voffA);
;             PG8_WAIT_V(8); PG8_WAIT_L(0); PG8_BAR; PG8_MMA(0, 0, At, B0); PG8_MMA(0, 1, At, B1); PG8_BAR; PG8_SCHED;
;             PG8_LDA(At, 1, 1); PG8_STAGE(PG8_SB(1, 0), b3, voffB); PG8_STAGE(PG8_SB(1, 1), b3 + hstep, voffB); PG8_STAGE(PG8_SA(1, 0), a3, voffA);
;             PG8_WAIT_V(8); PG8_WAIT_L(0); PG8_BAR; PG8_MMA(1, 0, At, B0); PG8_MMA(1, 1, At, B1); PG8_BAR; PG8_SCHED;
	ds_read_b128 v[180:183], v164
	ds_read_b128 v[184:187], v164 offset:1024
	ds_read_b128 v[188:191], v164 offset:2048
	ds_read_b128 v[192:195], v164 offset:3072
	ds_read_b128 v[196:199], v162 offset:32768
	ds_read_b128 v[200:203], v162 offset:33792
	ds_read_b128 v[204:207], v162 offset:34816
	ds_read_b128 v[208:211], v162 offset:35840
	ds_read_b128 v[212:215], v162 offset:36864
	ds_read_b128 v[216:219], v162 offset:37888
	ds_read_b128 v[220:223], v162 offset:38912
	ds_read_b128 v[224:227], v162 offset:39936
	s_add_u32 s22, s22, 0x80
	s_addc_u32 s23, s23, 0
	s_add_u32 s24, s24, 0x80
	s_addc_u32 s25, s25, 0
	s_mov_b32 m0, s0
	s_nop 0
	global_load_lds_dwordx4 v140, s[22:23]
	s_add_i32 m0, s0, 0x2000
	s_nop 0
	global_load_lds_dwordx4 v144, s[22:23]
	s_add_i32 m0, s0, 0x14000
	s_nop 0
	global_load_lds_dwordx4 v142, s[24:25]
	s_add_i32 m0, s0, 0x16000
	s_nop 0
	global_load_lds_dwordx4 v146, s[24:25]
	s_waitcnt lgkmcnt(0)
	v_mfma_f32_16x16x32_bf16 v[116:119], v[180:183], v[196:199], v[116:119]
	v_mfma_f32_16x16x32_bf16 v[112:115], v[188:191], v[196:199], v[112:115]
	v_mfma_f32_16x16x32_bf16 v[100:103], v[180:183], v[204:207], v[100:103]
	v_mfma_f32_16x16x32_bf16 v[96:99], v[188:191], v[204:207], v[96:99]
	v_mfma_f32_16x16x32_bf16 v[84:87], v[180:183], v[212:215], v[84:87]
	v_mfma_f32_16x16x32_bf16 v[80:83], v[188:191], v[212:215], v[80:83]
	v_mfma_f32_16x16x32_bf16 v[68:71], v[180:183], v[220:223], v[68:71]
	v_mfma_f32_16x16x32_bf16 v[64:67], v[188:191], v[220:223], v[64:67]
	v_mfma_f32_16x16x32_bf16 v[116:119], v[184:187], v[200:203], v[116:119]
	v_mfma_f32_16x16x32_bf16 v[112:115], v[192:195], v[200:203], v[112:115]
	v_mfma_f32_16x16x32_bf16 v[100:103], v[184:187], v[208:211], v[100:103]
	v_mfma_f32_16x16x32_bf16 v[96:99], v[192:195], v[208:211], v[96:99]
	v_mfma_f32_16x16x32_bf16 v[84:87], v[184:187], v[216:219], v[84:87]
	v_mfma_f32_16x16x32_bf16 v[80:83], v[192:195], v[216:219], v[80:83]
	v_mfma_f32_16x16x32_bf16 v[68:71], v[184:187], v[224:227], v[68:71]
	v_mfma_f32_16x16x32_bf16 v[64:67], v[192:195], v[224:227], v[64:67]
	s_waitcnt vmcnt(8)
	s_barrier
	ds_read_b128 v[180:183], v160
	ds_read_b128 v[184:187], v160 offset:1024
	ds_read_b128 v[188:191], v160 offset:2048
	ds_read_b128 v[192:195], v160 offset:3072
	ds_read_b128 v[196:199], v162 offset:16384
	ds_read_b128 v[200:203], v162 offset:17408
	ds_read_b128 v[204:207], v162 offset:18432
	ds_read_b128 v[208:211], v162 offset:19456
	ds_read_b128 v[212:215], v162 offset:20480
	ds_read_b128 v[216:219], v162 offset:21504
	ds_read_b128 v[220:223], v162 offset:22528
	ds_read_b128 v[224:227], v162 offset:23552
	s_add_u32 s22, s22, 0x80
	s_addc_u32 s23, s23, 0
	s_add_u32 s24, s24, 0x80
	s_addc_u32 s25, s25, 0
	s_add_i32 m0, s0, 0x8000
	s_nop 0
	global_load_lds_dwordx4 v140, s[22:23]
	s_add_i32 m0, s0, 0xa000
	s_nop 0
	global_load_lds_dwordx4 v144, s[22:23]
	s_add_i32 m0, s0, 0x1c000
	s_nop 0
	global_load_lds_dwordx4 v142, s[24:25]
	s_add_i32 m0, s0, 0x1e000
	s_nop 0
	global_load_lds_dwordx4 v146, s[24:25]
	s_waitcnt lgkmcnt(0)
	v_mfma_f32_16x16x32_bf16 v[116:119], v[180:183], v[196:199], v[116:119]
	v_mfma_f32_16x16x32_bf16 v[112:115], v[188:191], v[196:199], v[112:115]
	v_mfma_f32_16x16x32_bf16 v[100:103], v[180:183], v[204:207], v[100:103]
	v_mfma_f32_16x16x32_bf16 v[96:99], v[188:191], v[204:207], v[96:99]
	v_mfma_f32_16x16x32_bf16 v[84:87], v[180:183], v[212:215], v[84:87]
	v_mfma_f32_16x16x32_bf16 v[80:83], v[188:191], v[212:215], v[80:83]
	v_mfma_f32_16x16x32_bf16 v[68:71], v[180:183], v[220:223], v[68:71]
	v_mfma_f32_16x16x32_bf16 v[64:67], v[188:191], v[220:223], v[64:67]
	v_mfma_f32_16x16x32_bf16 v[116:119], v[184:187], v[200:203], v[116:119]
	v_mfma_f32_16x16x32_bf16 v[112:115], v[192:195], v[200:203], v[112:115]
	v_mfma_f32_16x16x32_bf16 v[100:103], v[184:187], v[208:211], v[100:103]
	v_mfma_f32_16x16x32_bf16 v[96:99], v[192:195], v[208:211], v[96:99]
	v_mfma_f32_16x16x32_bf16 v[84:87], v[184:187], v[216:219], v[84:87]
	v_mfma_f32_16x16x32_bf16 v[80:83], v[192:195], v[216:219], v[80:83]
	v_mfma_f32_16x16x32_bf16 v[68:71], v[184:187], v[224:227], v[68:71]
	v_mfma_f32_16x16x32_bf16 v[64:67], v[192:195], v[224:227], v[64:67]
	s_waitcnt vmcnt(8)
	s_barrier
	ds_read_b128 v[180:183], v163
	ds_read_b128 v[184:187], v163 offset:1024
	ds_read_b128 v[188:191], v163 offset:2048
	ds_read_b128 v[192:195], v163 offset:3072
	ds_read_b128 v[196:199], v162 offset:49152
	ds_read_b128 v[200:203], v162 offset:50176
	ds_read_b128 v[204:207], v162 offset:51200
	ds_read_b128 v[208:211], v162 offset:52224
	ds_read_b128 v[212:215], v162 offset:53248
	ds_read_b128 v[216:219], v162 offset:54272
	ds_read_b128 v[220:223], v162 offset:55296
	ds_read_b128 v[224:227], v162 offset:56320
	s_add_u32 s22, s22, 0x80
	s_addc_u32 s23, s23, 0
	s_add_u32 s24, s24, 0x80
	s_addc_u32 s25, s25, 0
	s_add_i32 m0, s0, 0x4000
	s_nop 0
	global_load_lds_dwordx4 v140, s[22:23]
	s_add_i32 m0, s0, 0x6000
	s_nop 0
	global_load_lds_dwordx4 v144, s[22:23]
	s_add_i32 m0, s0, 0x10000
	s_nop 0
	global_load_lds_dwordx4 v142, s[24:25]
	s_add_i32 m0, s0, 0x12000
	s_nop 0
	global_load_lds_dwordx4 v146, s[24:25]
	s_waitcnt lgkmcnt(0)
	v_mfma_f32_16x16x32_bf16 v[116:119], v[180:183], v[196:199], v[116:119]
	v_mfma_f32_16x16x32_bf16 v[112:115], v[188:191], v[196:199], v[112:115]
	v_mfma_f32_16x16x32_bf16 v[100:103], v[180:183], v[204:207], v[100:103]
	v_mfma_f32_16x16x32_bf16 v[96:99], v[188:191], v[204:207], v[96:99]
	v_mfma_f32_16x16x32_bf16 v[84:87], v[180:183], v[212:215], v[84:87]
	v_mfma_f32_16x16x32_bf16 v[80:83], v[188:191], v[212:215], v[80:83]
	v_mfma_f32_16x16x32_bf16 v[68:71], v[180:183], v[220:223], v[68:71]
	v_mfma_f32_16x16x32_bf16 v[64:67], v[188:191], v[220:223], v[64:67]
	v_mfma_f32_16x16x32_bf16 v[116:119], v[184:187], v[200:203], v[116:119]
	v_mfma_f32_16x16x32_bf16 v[112:115], v[192:195], v[200:203], v[112:115]
	v_mfma_f32_16x16x32_bf16 v[100:103], v[184:187], v[208:211], v[100:103]
	v_mfma_f32_16x16x32_bf16 v[96:99], v[192:195], v[208:211], v[96:99]
	v_mfma_f32_16x16x32_bf16 v[84:87], v[184:187], v[216:219], v[84:87]
	v_mfma_f32_16x16x32_bf16 v[80:83], v[192:195], v[216:219], v[80:83]
	v_mfma_f32_16x16x32_bf16 v[68:71], v[184:187], v[224:227], v[68:71]
	v_mfma_f32_16x16x32_bf16 v[64:67], v[192:195], v[224:227], v[64:67]
	s_waitcnt vmcnt(8)
	s_barrier
; #define PG8_STAGE(bufoff, gbase, voff) do { _Pragma("unroll") for (int _i = 0; _i < 2; ++_i) \
;         __builtin_amdgcn_global_load_lds((const unsigned*)((const char*)(gbase) + (voff)[_i]), (PG8_LAS unsigned*)(lds + (bufoff) + ldsw + _i * 8192), 16, 0, 0); } while (0)
; #define PG8_LDA(dst, b, h) do { _Pragma("unroll") for (int m = 0; m < 4; ++m) _Pragma("unroll") for (int k = 0; k < 2; ++k) dst[m][k] = *(const PG8_LAS bf16x8*)(lds + PG8_SA(b, h) + aoff + m * 2048 + k * 1024); } while (0)
; #define PG8_LDB(dst, b, h) do { _Pragma("unroll") for (int n = 0; n < 2; ++n) _Pragma("unroll") for (int k = 0; k < 2; ++k) dst[n][k] = *(const PG8_LAS bf16x8*)(lds + PG8_SB(b, h) + boff + n * 2048 + k * 1024); } while (0)
; #define PG8_MMA(ai, bj, At, Bt) do { __builtin_amdgcn_s_setprio(1); _Pragma("unroll") for (int m = 0; m < 4; ++m) _Pragma("unroll") for (int n = 0; n < 2; ++n) _Pragma("unroll") for (int k = 0; k < 2; ++k) \
;         acc[ai][bj][m][n] = __builtin_amdgcn_mfma_f32_16x16x32_bf16(Bt[n][k], At[m][k], acc[ai][bj][m][n], 0, 0, 0); __builtin_amdgcn_s_setprio(0); } while (0)
; #define PG8_WAIT_V(n) asm volatile("s_waitcnt vmcnt(" #n ")" ::: "memory")
; template <class Epi, class Sched, bool ALIGN_EPI = false, bool SP2 = false>
; __device__ __forceinline__ void gemm_phase(PG8_LAS unsigned char* lds, const Gemm g, const Sched& S, const Epi& E) {
;     ...
;             PG8_LDB(B0, 0, 0); PG8_LDB(B1, 0, 1); PG8_SCHED; PG8_LDA(At, 0, 0); PG8_STAGE(PG8_SA(1, 1), a1 + hstep, voffA);
;             PG8_WAIT_V(8); PG8_WAIT_L(0); PG8_BAR; PG8_MMA(0, 0, At, B0); PG8_MMA(0, 1, At, B1); PG8_BAR; PG8_SCHED;
;             PG8_LDA(At, 0, 1); PG8_STAGE(PG8_SB(0, 0), b2, voffB); PG8_STAGE(PG8_SB(0, 1), b2 + hstep, voffB); PG8_STAGE(PG8_SA(0, 0), a2, voffA);
;             PG8_WAIT_V(8); PG8_WAIT_L(0); PG8_BAR; PG8_MMA(1, 0, At, B0); PG8_MMA(1, 1, At, B1); PG8_BAR; PG8_SCHED;
;             PG8_LDB(B0, 1, 0); PG8_LDB(B1, 1, 1); PG8_SCHED; PG8_LDA(At, 1, 0); PG8_STAGE(PG8_SA(0, 1), a2 + hstep, voffA);
;             PG8_WAIT_V(8); PG8_WAIT_L(0); PG8_BAR; PG8_MMA(0, 0, At, B0); PG8_MMA(0, 1, At, B1); PG8_BAR; PG8_SCHED;
;             PG8_LDA(At, 1, 1); PG8_STAGE(PG8_SB(1, 0), b3, voffB); PG8_STAGE(PG8_SB(1, 1), b3 + hstep, voffB); PG8_STAGE(PG8_SA(1, 0), a3, voffA);
;             PG8_WAIT_V(8); PG8_WAIT_L(0); PG8_BAR; PG8_MMA(1, 0, At, B0); PG8_MMA(1, 1, At, B1); PG8_BAR; PG8_SCHED;
	ds_read_b128 v[180:183], v161
	ds_read_b128 v[184:187], v161 offset:1024
	ds_read_b128 v[188:191], v161 offset:2048
	ds_read_b128 v[192:195], v161 offset:3072
	ds_read_b128 v[196:199], v162
	ds_read_b128 v[200:203], v162 offset:1024
	ds_read_b128 v[204:207], v162 offset:2048
	ds_read_b128 v[208:211], v162 offset:3072
	ds_read_b128 v[212:215], v162 offset:4096
	ds_read_b128 v[216:219], v162 offset:5120
	ds_read_b128 v[220:223], v162 offset:6144
	ds_read_b128 v[224:227], v162 offset:7168
	s_add_u32 s22, s22, 0x80
	s_addc_u32 s23, s23, 0
	s_add_u32 s24, s24, 0x80
	s_addc_u32 s25, s25, 0
	s_add_i32 m0, s0, 0xc000
	s_nop 0
	global_load_lds_dwordx4 v140, s[22:23]
	s_add_i32 m0, s0, 0xe000
	s_nop 0
	global_load_lds_dwordx4 v144, s[22:23]
	s_add_i32 m0, s0, 0x18000
	s_nop 0
	global_load_lds_dwordx4 v142, s[24:25]
	s_add_i32 m0, s0, 0x1a000
	s_nop 0
	global_load_lds_dwordx4 v146, s[24:25]
	s_waitcnt lgkmcnt(0)
	v_mfma_f32_16x16x32_bf16 v[116:119], v[180:183], v[196:199], v[116:119]
	v_mfma_f32_16x16x32_bf16 v[112:115], v[188:191], v[196:199], v[112:115]
	v_mfma_f32_16x16x32_bf16 v[100:103], v[180:183], v[204:207], v[100:103]
	v_mfma_f32_16x16x32_bf16 v[96:99], v[188:191], v[204:207], v[96:99]
	v_mfma_f32_16x16x32_bf16 v[84:87], v[180:183], v[212:215], v[84:87]
	v_mfma_f32_16x16x32_bf16 v[80:83], v[188:191], v[212:215], v[80:83]
	v_mfma_f32_16x16x32_bf16 v[68:71], v[180:183], v[220:223], v[68:71]
	v_mfma_f32_16x16x32_bf16 v[64:67], v[188:191], v[220:223], v[64:67]
	v_mfma_f32_16x16x32_bf16 v[116:119], v[184:187], v[200:203], v[116:119]
	v_mfma_f32_16x16x32_bf16 v[112:115], v[192:195], v[200:203], v[112:115]
	v_mfma_f32_16x16x32_bf16 v[100:103], v[184:187], v[208:211], v[100:103]
	v_mfma_f32_16x16x32_bf16 v[96:99], v[192:195], v[208:211], v[96:99]
	v_mfma_f32_16x16x32_bf16 v[84:87], v[184:187], v[216:219], v[84:87]
	v_mfma_f32_16x16x32_bf16 v[80:83], v[192:195], v[216:219], v[80:83]
	v_mfma_f32_16x16x32_bf16 v[68:71], v[184:187], v[224:227], v[68:71]
	v_mfma_f32_16x16x32_bf16 v[64:67], v[192:195], v[224:227], v[64:67]
	s_waitcnt vmcnt(8)
	s_barrier
	ds_read_b128 v[180:183], v164
	ds_read_b128 v[184:187], v164 offset:1024
	ds_read_b128 v[188:191], v164 offset:2048
	ds_read_b128 v[192:195], v164 offset:3072
	ds_read_b128 v[196:199], v162 offset:32768
	ds_read_b128 v[200:203], v162 offset:33792
	ds_read_b128 v[204:207], v162 offset:34816
	ds_read_b128 v[208:211], v162 offset:35840
	ds_read_b128 v[212:215], v162 offset:36864
	ds_read_b128 v[216:219], v162 offset:37888
	ds_read_b128 v[220:223], v162 offset:38912
	ds_read_b128 v[224:227], v162 offset:39936
	s_add_u32 s22, s22, 0x80
	s_addc_u32 s23, s23, 0
	s_add_u32 s24, s24, 0x80
	s_addc_u32 s25, s25, 0
	s_mov_b32 m0, s0
	s_nop 0
	global_load_lds_dwordx4 v140, s[22:23]
	s_add_i32 m0, s0, 0x2000
	s_nop 0
	global_load_lds_dwordx4 v144, s[22:23]
	s_add_i32 m0, s0, 0x14000
	s_nop 0
	global_load_lds_dwordx4 v142, s[24:25]
	s_add_i32 m0, s0, 0x16000
	s_nop 0
	global_load_lds_dwordx4 v146, s[24:25]
	s_waitcnt lgkmcnt(0)
	v_mfma_f32_16x16x32_bf16 v[116:119], v[180:183], v[196:199], v[116:119]
	v_mfma_f32_16x16x32_bf16 v[112:115], v[188:191], v[196:199], v[112:115]
	v_mfma_f32_16x16x32_bf16 v[100:103], v[180:183], v[204:207], v[100:103]
	v_mfma_f32_16x16x32_bf16 v[96:99], v[188:191], v[204:207], v[96:99]
	v_mfma_f32_16x16x32_bf16 v[84:87], v[180:183], v[212:215], v[84:87]
	v_mfma_f32_16x16x32_bf16 v[80:83], v[188:191], v[212:215], v[80:83]
	v_mfma_f32_16x16x32_bf16 v[68:71], v[180:183], v[220:223], v[68:71]
	v_mfma_f32_16x16x32_bf16 v[64:67], v[188:191], v[220:223], v[64:67]
	v_mfma_f32_16x16x32_bf16 v[116:119], v[184:187], v[200:203], v[116:119]
	v_mfma_f32_16x16x32_bf16 v[112:115], v[192:195], v[200:203], v[112:115]
	v_mfma_f32_16x16x32_bf16 v[100:103], v[184:187], v[208:211], v[100:103]
	v_mfma_f32_16x16x32_bf16 v[96:99], v[192:195], v[208:211], v[96:99]
	v_mfma_f32_16x16x32_bf16 v[84:87], v[184:187], v[216:219], v[84:87]
	v_mfma_f32_16x16x32_bf16 v[80:83], v[192:195], v[216:219], v[80:83]
	v_mfma_f32_16x16x32_bf16 v[68:71], v[184:187], v[224:227], v[68:71]
	v_mfma_f32_16x16x32_bf16 v[64:67], v[192:195], v[224:227], v[64:67]
	s_waitcnt vmcnt(8)
	s_barrier
	ds_read_b128 v[180:183], v160
	ds_read_b128 v[184:187], v160 offset:1024
	ds_read_b128 v[188:191], v160 offset:2048
	ds_read_b128 v[192:195], v160 offset:3072
	ds_read_b128 v[196:199], v162 offset:16384
	ds_read_b128 v[200:203], v162 offset:17408
	ds_read_b128 v[204:207], v162 offset:18432
	ds_read_b128 v[208:211], v162 offset:19456
	ds_read_b128 v[212:215], v162 offset:20480
	ds_read_b128 v[216:219], v162 offset:21504
	ds_read_b128 v[220:223], v162 offset:22528
	ds_read_b128 v[224:227], v162 offset:23552
	s_add_u32 s22, s22, 0x80
	s_addc_u32 s23, s23, 0
	s_add_u32 s24, s24, 0x80
	s_addc_u32 s25, s25, 0
	s_add_i32 m0, s0, 0x8000
	s_nop 0
	global_load_lds_dwordx4 v140, s[22:23]
	s_add_i32 m0, s0, 0xa000
	s_nop 0
	global_load_lds_dwordx4 v144, s[22:23]
	s_add_i32 m0, s0, 0x1c000
	s_nop 0
	global_load_lds_dwordx4 v142, s[24:25]
	s_add_i32 m0, s0, 0x1e000
	s_nop 0
	global_load_lds_dwordx4 v146, s[24:25]
	s_waitcnt lgkmcnt(0)
	v_mfma_f32_16x16x32_bf16 v[116:119], v[180:183], v[196:199], v[116:119]
	v_mfma_f32_16x16x32_bf16 v[112:115], v[188:191], v[196:199], v[112:115]
	v_mfma_f32_16x16x32_bf16 v[100:103], v[180:183], v[204:207], v[100:103]
	v_mfma_f32_16x16x32_bf16 v[96:99], v[188:191], v[204:207], v[96:99]
	v_mfma_f32_16x16x32_bf16 v[84:87], v[180:183], v[212:215], v[84:87]
	v_mfma_f32_16x16x32_bf16 v[80:83], v[188:191], v[212:215], v[80:83]
	v_mfma_f32_16x16x32_bf16 v[68:71], v[180:183], v[220:223], v[68:71]
	v_mfma_f32_16x16x32_bf16 v[64:67], v[188:191], v[220:223], v[64:67]
	v_mfma_f32_16x16x32_bf16 v[116:119], v[184:187], v[200:203], v[116:119]
	v_mfma_f32_16x16x32_bf16 v[112:115], v[192:195], v[200:203], v[112:115]
	v_mfma_f32_16x16x32_bf16 v[100:103], v[184:187], v[208:211], v[100:103]
	v_mfma_f32_16x16x32_bf16 v[96:99], v[192:195], v[208:211], v[96:99]
	v_mfma_f32_16x16x32_bf16 v[84:87], v[184:187], v[216:219], v[84:87]
	v_mfma_f32_16x16x32_bf16 v[80:83], v[192:195], v[216:219], v[80:83]
	v_mfma_f32_16x16x32_bf16 v[68:71], v[184:187], v[224:227], v[68:71]
	v_mfma_f32_16x16x32_bf16 v[64:67], v[192:195], v[224:227], v[64:67]
	s_waitcnt vmcnt(8)
	s_barrier
; #define PG8_STAGE(bufoff, gbase, voff) do { _Pragma("unroll") for (int _i = 0; _i < 2; ++_i) \
;         __builtin_amdgcn_global_load_lds((const unsigned*)((const char*)(gbase) + (voff)[_i]), (PG8_LAS unsigned*)(lds + (bufoff) + ldsw + _i * 8192), 16, 0, 0); } while (0)
; #define PG8_LDA(dst, b, h) do { _Pragma("unroll") for (int m = 0; m < 4; ++m) _Pragma("unroll") for (int k = 0; k < 2; ++k) dst[m][k] = *(const PG8_LAS bf16x8*)(lds + PG8_SA(b, h) + aoff + m * 2048 + k * 1024); } while (0)
; #define PG8_LDB(dst, b, h) do { _Pragma("unroll") for (int n = 0; n < 2; ++n) _Pragma("unroll") for (int k = 0; k < 2; ++k) dst[n][k] = *(const PG8_LAS bf16x8*)(lds + PG8_SB(b, h) + boff + n * 2048 + k * 1024); } while (0)
; #define PG8_MMA(ai, bj, At, Bt) do { __builtin_amdgcn_s_setprio(1); _Pragma("unroll") for (int m = 0; m < 4; ++m) _Pragma("unroll") for (int n = 0; n < 2; ++n) _Pragma("unroll") for (int k = 0; k < 2; ++k) \
;         acc[ai][bj][m][n] = __builtin_amdgcn_mfma_f32_16x16x32_bf16(Bt[n][k], At[m][k], acc[ai][bj][m][n], 0, 0, 0); __builtin_amdgcn_s_setprio(0); } while (0)
; #define PG8_WAIT_V(n) asm volatile("s_waitcnt vmcnt(" #n ")" ::: "memory")
; template <class Epi, class Sched, bool ALIGN_EPI = false, bool SP2 = false>
; __device__ __forceinline__ void gemm_phase(PG8_LAS unsigned char* lds, const Gemm g, const Sched& S, const Epi& E) {
;     ...
;             PG8_LDB(B0, 0, 0); PG8_LDB(B1, 0, 1); PG8_SCHED; PG8_LDA(At, 0, 0); PG8_STAGE(PG8_SA(1, 1), a1 + hstep, voffA);
;             PG8_WAIT_V(8); PG8_WAIT_L(0); PG8_BAR; PG8_MMA(0, 0, At, B0); PG8_MMA(0, 1, At, B1); PG8_BAR; PG8_SCHED;
;             PG8_LDA(At, 0, 1); PG8_STAGE(PG8_SB(0, 0), b2, voffB); PG8_STAGE(PG8_SB(0, 1), b2 + hstep, voffB); PG8_STAGE(PG8_SA(0, 0), a2, voffA);
;             PG8_WAIT_V(8); PG8_WAIT_L(0); PG8_BAR; PG8_MMA(1, 0, At, B0); PG8_MMA(1, 1, At, B1); PG8_BAR; PG8_SCHED;
;             PG8_LDB(B0, 1, 0); PG8_LDB(B1, 1, 1); PG8_SCHED; PG8_LDA(At, 1, 0); PG8_STAGE(PG8_SA(0, 1), a2 + hstep, voffA);
;             PG8_WAIT_V(8); PG8_WAIT_L(0); PG8_BAR; PG8_MMA(0, 0, At, B0); PG8_MMA(0, 1, At, B1); PG8_BAR; PG8_SCHED;
;             PG8_LDA(At, 1, 1); PG8_STAGE(PG8_SB(1, 0), b3, voffB); PG8_STAGE(PG8_SB(1, 1), b3 + hstep, voffB); PG8_STAGE(PG8_SA(1, 0), a3, voffA);
;             PG8_WAIT_V(8); PG8_WAIT_L(0); PG8_BAR; PG8_MMA(1, 0, At, B0); PG8_MMA(1, 1, At, B1); PG8_BAR; PG8_SCHED;
	ds_read_b128 v[180:183], v163
	ds_read_b128 v[184:187], v163 offset:1024
	ds_read_b128 v[188:191], v163 offset:2048
	ds_read_b128 v[192:195], v163 offset:3072
	ds_read_b128 v[196:199], v162 offset:49152
	ds_read_b128 v[200:203], v162 offset:50176
	ds_read_b128 v[204:207], v162 offset:51200
	ds_read_b128 v[208:211], v162 offset:52224
	ds_read_b128 v[212:215], v162 offset:53248
	ds_read_b128 v[216:219], v162 offset:54272
	ds_read_b128 v[220:223], v162 offset:55296
	ds_read_b128 v[224:227], v162 offset:56320
	s_add_u32 s22, s22, 0x80
	s_addc_u32 s23, s23, 0
	s_add_u32 s24, s24, 0x80
	s_addc_u32 s25, s25, 0
	s_add_i32 m0, s0, 0x4000
	s_nop 0
	global_load_lds_dwordx4 v140, s[22:23]
	s_add_i32 m0, s0, 0x6000
	s_nop 0
	global_load_lds_dwordx4 v144, s[22:23]
	s_add_i32 m0, s0, 0x10000
	s_nop 0
	global_load_lds_dwordx4 v142, s[24:25]
	s_add_i32 m0, s0, 0x12000
	s_nop 0
	global_load_lds_dwordx4 v146, s[24:25]
	s_waitcnt lgkmcnt(0)
	v_mfma_f32_16x16x32_bf16 v[116:119], v[180:183], v[196:199], v[116:119]
	v_mfma_f32_16x16x32_bf16 v[112:115], v[188:191], v[196:199], v[112:115]
	v_mfma_f32_16x16x32_bf16 v[100:103], v[180:183], v[204:207], v[100:103]
	v_mfma_f32_16x16x32_bf16 v[96:99], v[188:191], v[204:207], v[96:99]
	v_mfma_f32_16x16x32_bf16 v[84:87], v[180:183], v[212:215], v[84:87]
	v_mfma_f32_16x16x32_bf16 v[80:83], v[188:191], v[212:215], v[80:83]
	v_mfma_f32_16x16x32_bf16 v[68:71], v[180:183], v[220:223], v[68:71]
	v_mfma_f32_16x16x32_bf16 v[64:67], v[188:191], v[220:223], v[64:67]
	v_mfma_f32_16x16x32_bf16 v[116:119], v[184:187], v[200:203], v[116:119]
	v_mfma_f32_16x16x32_bf16 v[112:115], v[192:195], v[200:203], v[112:115]
	v_mfma_f32_16x16x32_bf16 v[100:103], v[184:187], v[208:211], v[100:103]
	v_mfma_f32_16x16x32_bf16 v[96:99], v[192:195], v[208:211], v[96:99]
	v_mfma_f32_16x16x32_bf16 v[84:87], v[184:187], v[216:219], v[84:87]
	v_mfma_f32_16x16x32_bf16 v[80:83], v[192:195], v[216:219], v[80:83]
	v_mfma_f32_16x16x32_bf16 v[68:71], v[184:187], v[224:227], v[68:71]
	v_mfma_f32_16x16x32_bf16 v[64:67], v[192:195], v[224:227], v[64:67]
	s_waitcnt vmcnt(8)
	s_barrier
	ds_read_b128 v[180:183], v161
	ds_read_b128 v[184:187], v161 offset:1024
	ds_read_b128 v[188:191], v161 offset:2048
	ds_read_b128 v[192:195], v161 offset:3072
	ds_read_b128 v[196:199], v162
	ds_read_b128 v[200:203], v162 offset:1024
	ds_read_b128 v[204:207], v162 offset:2048
	ds_read_b128 v[208:211], v162 offset:3072
	ds_read_b128 v[212:215], v162 offset:4096
	ds_read_b128 v[216:219], v162 offset:5120
	ds_read_b128 v[220:223], v162 offset:6144
	ds_read_b128 v[224:227], v162 offset:7168
	s_add_u32 s22, s22, 0x80
	s_addc_u32 s23, s23, 0
	s_add_u32 s24, s24, 0x80
	s_addc_u32 s25, s25, 0
	s_add_i32 m0, s0, 0xc000
	s_nop 0
	global_load_lds_dwordx4 v140, s[22:23]
	s_add_i32 m0, s0, 0xe000
	s_nop 0
	global_load_lds_dwordx4 v144, s[22:23]
	s_add_i32 m0, s0, 0x18000
	s_nop 0
	global_load_lds_dwordx4 v142, s[24:25]
	s_add_i32 m0, s0, 0x1a000
	s_nop 0
	global_load_lds_dwordx4 v146, s[24:25]
	s_waitcnt lgkmcnt(0)
	v_mfma_f32_16x16x32_bf16 v[116:119], v[180:183], v[196:199], v[116:119]
	v_mfma_f32_16x16x32_bf16 v[112:115], v[188:191], v[196:199], v[112:115]
	v_mfma_f32_16x16x32_bf16 v[100:103], v[180:183], v[204:207], v[100:103]
	v_mfma_f32_16x16x32_bf16 v[96:99], v[188:191], v[204:207], v[96:99]
	v_mfma_f32_16x16x32_bf16 v[84:87], v[180:183], v[212:215], v[84:87]
	v_mfma_f32_16x16x32_bf16 v[80:83], v[188:191], v[212:215], v[80:83]
	v_mfma_f32_16x16x32_bf16 v[68:71], v[180:183], v[220:223], v[68:71]
	v_mfma_f32_16x16x32_bf16 v[64:67], v[188:191], v[220:223], v[64:67]
	v_mfma_f32_16x16x32_bf16 v[116:119], v[184:187], v[200:203], v[116:119]
	v_mfma_f32_16x16x32_bf16 v[112:115], v[192:195], v[200:203], v[112:115]
	v_mfma_f32_16x16x32_bf16 v[100:103], v[184:187], v[208:211], v[100:103]
	v_mfma_f32_16x16x32_bf16 v[96:99], v[192:195], v[208:211], v[96:99]
	v_mfma_f32_16x16x32_bf16 v[84:87], v[184:187], v[216:219], v[84:87]
	v_mfma_f32_16x16x32_bf16 v[80:83], v[192:195], v[216:219], v[80:83]
	v_mfma_f32_16x16x32_bf16 v[68:71], v[184:187], v[224:227], v[68:71]
	v_mfma_f32_16x16x32_bf16 v[64:67], v[192:195], v[224:227], v[64:67]
	s_waitcnt vmcnt(8)
	s_barrier
	ds_read_b128 v[180:183], v164
	ds_read_b128 v[184:187], v164 offset:1024
	ds_read_b128 v[188:191], v164 offset:2048
	ds_read_b128 v[192:195], v164 offset:3072
	ds_read_b128 v[196:199], v162 offset:32768
	ds_read_b128 v[200:203], v162 offset:33792
	ds_read_b128 v[204:207], v162 offset:34816
	ds_read_b128 v[208:211], v162 offset:35840
	ds_read_b128 v[212:215], v162 offset:36864
	ds_read_b128 v[216:219], v162 offset:37888
	ds_read_b128 v[220:223], v162 offset:38912
	ds_read_b128 v[224:227], v162 offset:39936
	s_add_u32 s22, s22, 0x80
	s_addc_u32 s23, s23, 0
	s_add_u32 s24, s24, 0x80
	s_addc_u32 s25, s25, 0
	s_mov_b32 m0, s0
	s_nop 0
	global_load_lds_dwordx4 v140, s[22:23]
	s_add_i32 m0, s0, 0x2000
	s_nop 0
	global_load_lds_dwordx4 v144, s[22:23]
	s_add_i32 m0, s0, 0x14000
	s_nop 0
	global_load_lds_dwordx4 v142, s[24:25]
	s_add_i32 m0, s0, 0x16000
	s_nop 0
	global_load_lds_dwordx4 v146, s[24:25]
	s_waitcnt lgkmcnt(0)
	v_mfma_f32_16x16x32_bf16 v[116:119], v[180:183], v[196:199], v[116:119]
	v_mfma_f32_16x16x32_bf16 v[112:115], v[188:191], v[196:199], v[112:115]
	v_mfma_f32_16x16x32_bf16 v[100:103], v[180:183], v[204:207], v[100:103]
	v_mfma_f32_16x16x32_bf16 v[96:99], v[188:191], v[204:207], v[96:99]
	v_mfma_f32_16x16x32_bf16 v[84:87], v[180:183], v[212:215], v[84:87]
	v_mfma_f32_16x16x32_bf16 v[80:83], v[188:191], v[212:215], v[80:83]
	v_mfma_f32_16x16x32_bf16 v[68:71], v[180:183], v[220:223], v[68:71]
	v_mfma_f32_16x16x32_bf16 v[64:67], v[188:191], v[220:223], v[64:67]
	v_mfma_f32_16x16x32_bf16 v[116:119], v[184:187], v[200:203], v[116:119]
	v_mfma_f32_16x16x32_bf16 v[112:115], v[192:195], v[200:203], v[112:115]
	v_mfma_f32_16x16x32_bf16 v[100:103], v[184:187], v[208:211], v[100:103]
	v_mfma_f32_16x16x32_bf16 v[96:99], v[192:195], v[208:211], v[96:99]
	v_mfma_f32_16x16x32_bf16 v[84:87], v[184:187], v[216:219], v[84:87]
	v_mfma_f32_16x16x32_bf16 v[80:83], v[192:195], v[216:219], v[80:83]
	v_mfma_f32_16x16x32_bf16 v[68:71], v[184:187], v[224:227], v[68:71]
	v_mfma_f32_16x16x32_bf16 v[64:67], v[192:195], v[224:227], v[64:67]
	s_waitcnt vmcnt(8)
	s_barrier
; #define PG8_STAGE(bufoff, gbase, voff) do { _Pragma("unroll") for (int _i = 0; _i < 2; ++_i) \
;         __builtin_amdgcn_global_load_lds((const unsigned*)((const char*)(gbase) + (voff)[_i]), (PG8_LAS unsigned*)(lds + (bufoff) + ldsw + _i * 8192), 16, 0, 0); } while (0)
; #define PG8_LDA(dst, b, h) do { _Pragma("unroll") for (int m = 0; m < 4; ++m) _Pragma("unroll") for (int k = 0; k < 2; ++k) dst[m][k] = *(const PG8_LAS bf16x8*)(lds + PG8_SA(b, h) + aoff + m * 2048 + k * 1024); } while (0)
; #define PG8_LDB(dst, b, h) do { _Pragma("unroll") for (int n = 0; n < 2; ++n) _Pragma("unroll") for (int k = 0; k < 2; ++k) dst[n][k] = *(const PG8_LAS bf16x8*)(lds + PG8_SB(b, h) + boff + n * 2048 + k * 1024); } while (0)
; #define PG8_MMA(ai, bj, At, Bt) do { __builtin_amdgcn_s_setprio(1); _Pragma("unroll") for (int m = 0; m < 4; ++m) _Pragma("unroll") for (int n = 0; n < 2; ++n) _Pragma("unroll") for (int k = 0; k < 2; ++k) \
;         acc[ai][bj][m][n] = __builtin_amdgcn_mfma_f32_16x16x32_bf16(Bt[n][k], At[m][k], acc[ai][bj][m][n], 0, 0, 0); __builtin_amdgcn_s_setprio(0); } while (0)
; #define PG8_WAIT_V(n) asm volatile("s_waitcnt vmcnt(" #n ")" ::: "memory")
; template <class Epi, class Sched, bool ALIGN_EPI = false, bool SP2 = false>
; __device__ __forceinline__ void gemm_phase(PG8_LAS unsigned char* lds, const Gemm g, const Sched& S, const Epi& E) {
;     ...
;             PG8_LDB(B0, 0, 0); PG8_LDB(B1, 0, 1); PG8_SCHED; PG8_LDA(At, 0, 0); PG8_STAGE(PG8_SA(1, 1), a1 + hstep, voffA);
;             PG8_WAIT_V(8); PG8_WAIT_L(0); PG8_BAR; PG8_MMA(0, 0, At, B0); PG8_MMA(0, 1, At, B1); PG8_BAR; PG8_SCHED;
;             PG8_LDA(At, 0, 1); PG8_STAGE(PG8_SB(0, 0), b2, voffB); PG8_STAGE(PG8_SB(0, 1), b2 + hstep, voffB); PG8_STAGE(PG8_SA(0, 0), a2, voffA);
;             PG8_WAIT_V(8); PG8_WAIT_L(0); PG8_BAR; PG8_MMA(1, 0, At, B0); PG8_MMA(1, 1, At, B1); PG8_BAR; PG8_SCHED;
;             PG8_LDB(B0, 1, 0); PG8_LDB(B1, 1, 1); PG8_SCHED; PG8_LDA(At, 1, 0); PG8_STAGE(PG8_SA(0, 1), a2 + hstep, voffA);
;             PG8_WAIT_V(8); PG8_WAIT_L(0); PG8_BAR; PG8_MMA(0, 0, At, B0); PG8_MMA(0, 1, At, B1); PG8_BAR; PG8_SCHED;
;             PG8_LDA(At, 1, 1); PG8_STAGE(PG8_SB(1, 0), b3, voffB); PG8_STAGE(PG8_SB(1, 1), b3 + hstep, voffB); PG8_STAGE(PG8_SA(1, 0), a3, voffA);
;             PG8_WAIT_V(8); PG8_WAIT_L(0); PG8_BAR; PG8_MMA(1, 0, At, B0); PG8_MMA(1, 1, At, B1); PG8_BAR; PG8_SCHED;
	ds_read_b128 v[180:183], v160
	ds_read_b128 v[184:187], v160 offset:1024
	ds_read_b128 v[188:191], v160 offset:2048
	ds_read_b128 v[192:195], v160 offset:3072
	ds_read_b128 v[196:199], v162 offset:16384
	ds_read_b128 v[200:203], v162 offset:17408
	ds_read_b128 v[204:207], v162 offset:18432
	ds_read_b128 v[208:211], v162 offset:19456
	ds_read_b128 v[212:215], v162 offset:20480
	ds_read_b128 v[216:219], v162 offset:21504
	ds_read_b128 v[220:223], v162 offset:22528
	ds_read_b128 v[224:227], v162 offset:23552
	s_add_u32 s22, s22, 0x80
	s_addc_u32 s23, s23, 0
	s_add_u32 s24, s24, 0x80
	s_addc_u32 s25, s25, 0
	s_add_i32 m0, s0, 0x8000
	s_nop 0
	global_load_lds_dwordx4 v140, s[22:23]
	s_add_i32 m0, s0, 0xa000
	s_nop 0
	global_load_lds_dwordx4 v144, s[22:23]
	s_add_i32 m0, s0, 0x1c000
	s_nop 0
	global_load_lds_dwordx4 v142, s[24:25]
	s_add_i32 m0, s0, 0x1e000
	s_nop 0
	global_load_lds_dwordx4 v146, s[24:25]
	s_waitcnt lgkmcnt(0)
	v_mfma_f32_16x16x32_bf16 v[116:119], v[180:183], v[196:199], v[116:119]
	v_mfma_f32_16x16x32_bf16 v[112:115], v[188:191], v[196:199], v[112:115]
	v_mfma_f32_16x16x32_bf16 v[100:103], v[180:183], v[204:207], v[100:103]
	v_mfma_f32_16x16x32_bf16 v[96:99], v[188:191], v[204:207], v[96:99]
	v_mfma_f32_16x16x32_bf16 v[84:87], v[180:183], v[212:215], v[84:87]
	v_mfma_f32_16x16x32_bf16 v[80:83], v[188:191], v[212:215], v[80:83]
	v_mfma_f32_16x16x32_bf16 v[68:71], v[180:183], v[220:223], v[68:71]
	v_mfma_f32_16x16x32_bf16 v[64:67], v[188:191], v[220:223], v[64:67]
	v_mfma_f32_16x16x32_bf16 v[116:119], v[184:187], v[200:203], v[116:119]
	v_mfma_f32_16x16x32_bf16 v[112:115], v[192:195], v[200:203], v[112:115]
	v_mfma_f32_16x16x32_bf16 v[100:103], v[184:187], v[208:211], v[100:103]
	v_mfma_f32_16x16x32_bf16 v[96:99], v[192:195], v[208:211], v[96:99]
	v_mfma_f32_16x16x32_bf16 v[84:87], v[184:187], v[216:219], v[84:87]
	v_mfma_f32_16x16x32_bf16 v[80:83], v[192:195], v[216:219], v[80:83]
	v_mfma_f32_16x16x32_bf16 v[68:71], v[184:187], v[224:227], v[68:71]
	v_mfma_f32_16x16x32_bf16 v[64:67], v[192:195], v[224:227], v[64:67]
	s_waitcnt vmcnt(8)
	s_barrier
	ds_read_b128 v[180:183], v163
	ds_read_b128 v[184:187], v163 offset:1024
	ds_read_b128 v[188:191], v163 offset:2048
	ds_read_b128 v[192:195], v163 offset:3072
	ds_read_b128 v[196:199], v162 offset:49152
	ds_read_b128 v[200:203], v162 offset:50176
	ds_read_b128 v[204:207], v162 offset:51200
	ds_read_b128 v[208:211], v162 offset:52224
	ds_read_b128 v[212:215], v162 offset:53248
	ds_read_b128 v[216:219], v162 offset:54272
	ds_read_b128 v[220:223], v162 offset:55296
	ds_read_b128 v[224:227], v162 offset:56320
	s_add_u32 s22, s22, 0x80
	s_addc_u32 s23, s23, 0
	s_add_u32 s24, s24, 0x80
	s_addc_u32 s25, s25, 0
	s_add_i32 m0, s0, 0x4000
	s_nop 0
	global_load_lds_dwordx4 v140, s[22:23]
	s_add_i32 m0, s0, 0x6000
	s_nop 0
	global_load_lds_dwordx4 v144, s[22:23]
	s_add_i32 m0, s0, 0x10000
	s_nop 0
	global_load_lds_dwordx4 v142, s[24:25]
	s_add_i32 m0, s0, 0x12000
	s_nop 0
	global_load_lds_dwordx4 v146, s[24:25]
	s_waitcnt lgkmcnt(0)
	v_mfma_f32_16x16x32_bf16 v[116:119], v[180:183], v[196:199], v[116:119]
	v_mfma_f32_16x16x32_bf16 v[112:115], v[188:191], v[196:199], v[112:115]
	v_mfma_f32_16x16x32_bf16 v[100:103], v[180:183], v[204:207], v[100:103]
	v_mfma_f32_16x16x32_bf16 v[96:99], v[188:191], v[204:207], v[96:99]
	v_mfma_f32_16x16x32_bf16 v[84:87], v[180:183], v[212:215], v[84:87]
	v_mfma_f32_16x16x32_bf16 v[80:83], v[188:191], v[212:215], v[80:83]
	v_mfma_f32_16x16x32_bf16 v[68:71], v[180:183], v[220:223], v[68:71]
	v_mfma_f32_16x16x32_bf16 v[64:67], v[188:191], v[220:223], v[64:67]
	v_mfma_f32_16x16x32_bf16 v[116:119], v[184:187], v[200:203], v[116:119]
	v_mfma_f32_16x16x32_bf16 v[112:115], v[192:195], v[200:203], v[112:115]
	v_mfma_f32_16x16x32_bf16 v[100:103], v[184:187], v[208:211], v[100:103]
	v_mfma_f32_16x16x32_bf16 v[96:99], v[192:195], v[208:211], v[96:99]
	v_mfma_f32_16x16x32_bf16 v[84:87], v[184:187], v[216:219], v[84:87]
	v_mfma_f32_16x16x32_bf16 v[80:83], v[192:195], v[216:219], v[80:83]
	v_mfma_f32_16x16x32_bf16 v[68:71], v[184:187], v[224:227], v[68:71]
	v_mfma_f32_16x16x32_bf16 v[64:67], v[192:195], v[224:227], v[64:67]
	s_waitcnt vmcnt(8)
	s_barrier
	ds_read_b128 v[180:183], v161
	ds_read_b128 v[184:187], v161 offset:1024
	ds_read_b128 v[188:191], v161 offset:2048
	ds_read_b128 v[192:195], v161 offset:3072
	ds_read_b128 v[196:199], v162
	ds_read_b128 v[200:203], v162 offset:1024
	ds_read_b128 v[204:207], v162 offset:2048
	ds_read_b128 v[208:211], v162 offset:3072
	ds_read_b128 v[212:215], v162 offset:4096
	ds_read_b128 v[216:219], v162 offset:5120
	ds_read_b128 v[220:223], v162 offset:6144
	ds_read_b128 v[224:227], v162 offset:7168
	s_add_u32 s22, s22, 0x80
	s_addc_u32 s23, s23, 0
	s_add_u32 s24, s24, 0x80
	s_addc_u32 s25, s25, 0
	s_add_i32 m0, s0, 0xc000
	s_nop 0
	global_load_lds_dwordx4 v140, s[22:23]
	s_add_i32 m0, s0, 0xe000
	s_nop 0
	global_load_lds_dwordx4 v144, s[22:23]
	s_add_i32 m0, s0, 0x18000
	s_nop 0
	global_load_lds_dwordx4 v142, s[24:25]
	s_add_i32 m0, s0, 0x1a000
	s_nop 0
	global_load_lds_dwordx4 v146, s[24:25]
	s_waitcnt lgkmcnt(0)
	v_mfma_f32_16x16x32_bf16 v[116:119], v[180:183], v[196:199], v[116:119]
	v_mfma_f32_16x16x32_bf16 v[112:115], v[188:191], v[196:199], v[112:115]
	v_mfma_f32_16x16x32_bf16 v[100:103], v[180:183], v[204:207], v[100:103]
	v_mfma_f32_16x16x32_bf16 v[96:99], v[188:191], v[204:207], v[96:99]
	v_mfma_f32_16x16x32_bf16 v[84:87], v[180:183], v[212:215], v[84:87]
	v_mfma_f32_16x16x32_bf16 v[80:83], v[188:191], v[212:215], v[80:83]
	v_mfma_f32_16x16x32_bf16 v[68:71], v[180:183], v[220:223], v[68:71]
	v_mfma_f32_16x16x32_bf16 v[64:67], v[188:191], v[220:223], v[64:67]
	v_mfma_f32_16x16x32_bf16 v[116:119], v[184:187], v[200:203], v[116:119]
	v_mfma_f32_16x16x32_bf16 v[112:115], v[192:195], v[200:203], v[112:115]
	v_mfma_f32_16x16x32_bf16 v[100:103], v[184:187], v[208:211], v[100:103]
	v_mfma_f32_16x16x32_bf16 v[96:99], v[192:195], v[208:211], v[96:99]
	v_mfma_f32_16x16x32_bf16 v[84:87], v[184:187], v[216:219], v[84:87]
	v_mfma_f32_16x16x32_bf16 v[80:83], v[192:195], v[216:219], v[80:83]
	v_mfma_f32_16x16x32_bf16 v[68:71], v[184:187], v[224:227], v[68:71]
	v_mfma_f32_16x16x32_bf16 v[64:67], v[192:195], v[224:227], v[64:67]
	s_waitcnt vmcnt(8)
	s_barrier
; #define PG8_STAGE(bufoff, gbase, voff) do { _Pragma("unroll") for (int _i = 0; _i < 2; ++_i) \
;         __builtin_amdgcn_global_load_lds((const unsigned*)((const char*)(gbase) + (voff)[_i]), (PG8_LAS unsigned*)(lds + (bufoff) + ldsw + _i * 8192), 16, 0, 0); } while (0)
; #define PG8_LDA(dst, b, h) do { _Pragma("unroll") for (int m = 0; m < 4; ++m) _Pragma("unroll") for (int k = 0; k < 2; ++k) dst[m][k] = *(const PG8_LAS bf16x8*)(lds + PG8_SA(b, h) + aoff + m * 2048 + k * 1024); } while (0)
; #define PG8_LDB(dst, b, h) do { _Pragma("unroll") for (int n = 0; n < 2; ++n) _Pragma("unroll") for (int k = 0; k < 2; ++k) dst[n][k] = *(const PG8_LAS bf16x8*)(lds + PG8_SB(b, h) + boff + n * 2048 + k * 1024); } while (0)
; #define PG8_MMA(ai, bj, At, Bt) do { __builtin_amdgcn_s_setprio(1); _Pragma("unroll") for (int m = 0; m < 4; ++m) _Pragma("unroll") for (int n = 0; n < 2; ++n) _Pragma("unroll") for (int k = 0; k < 2; ++k) \
;         acc[ai][bj][m][n] = __builtin_amdgcn_mfma_f32_16x16x32_bf16(Bt[n][k], At[m][k], acc[ai][bj][m][n], 0, 0, 0); __builtin_amdgcn_s_setprio(0); } while (0)
; #define PG8_WAIT_V(n) asm volatile("s_waitcnt vmcnt(" #n ")" ::: "memory")
; template <class Epi, class Sched, bool ALIGN_EPI = false, bool SP2 = false>
; __device__ __forceinline__ void gemm_phase(PG8_LAS unsigned char* lds, const Gemm g, const Sched& S, const Epi& E) {
;     ...
;             PG8_LDB(B0, 0, 0); PG8_LDB(B1, 0, 1); PG8_SCHED; PG8_LDA(At, 0, 0); PG8_STAGE(PG8_SA(1, 1), a1 + hstep, voffA);
;             PG8_WAIT_V(8); PG8_WAIT_L(0); PG8_BAR; PG8_MMA(0, 0, At, B0); PG8_MMA(0, 1, At, B1); PG8_BAR; PG8_SCHED;
;             PG8_LDA(At, 0, 1); PG8_STAGE(PG8_SB(0, 0), b2, voffB); PG8_STAGE(PG8_SB(0, 1), b2 + hstep, voffB); PG8_STAGE(PG8_SA(0, 0), a2, voffA);
;             PG8_WAIT_V(8); PG8_WAIT_L(0); PG8_BAR; PG8_MMA(1, 0, At, B0); PG8_MMA(1, 1, At, B1); PG8_BAR; PG8_SCHED;
;             PG8_LDB(B0, 1, 0); PG8_LDB(B1, 1, 1); PG8_SCHED; PG8_LDA(At, 1, 0); PG8_STAGE(PG8_SA(0, 1), a2 + hstep, voffA);
;             PG8_WAIT_V(8); PG8_WAIT_L(0); PG8_BAR; PG8_MMA(0, 0, At, B0); PG8_MMA(0, 1, At, B1); PG8_BAR; PG8_SCHED;
;             PG8_LDA(At, 1, 1); PG8_STAGE(PG8_SB(1, 0), b3, voffB); PG8_STAGE(PG8_SB(1, 1), b3 + hstep, voffB); PG8_STAGE(PG8_SA(1, 0), a3, voffA);
;             PG8_WAIT_V(8); PG8_WAIT_L(0); PG8_BAR; PG8_MMA(1, 0, At, B0); PG8_MMA(1, 1, At, B1); PG8_BAR; PG8_SCHED;
	ds_read_b128 v[180:183], v164
	ds_read_b128 v[184:187], v164 offset:1024
	ds_read_b128 v[188:191], v164 offset:2048
	ds_read_b128 v[192:195], v164 offset:3072
	ds_read_b128 v[196:199], v162 offset:32768
	ds_read_b128 v[200:203], v162 offset:33792
	ds_read_b128 v[204:207], v162 offset:34816
	ds_read_b128 v[208:211], v162 offset:35840
	ds_read_b128 v[212:215], v162 offset:36864
	ds_read_b128 v[216:219], v162 offset:37888
	ds_read_b128 v[220:223], v162 offset:38912
	ds_read_b128 v[224:227], v162 offset:39936
	s_waitcnt lgkmcnt(0)
	v_mfma_f32_16x16x32_bf16 v[116:119], v[180:183], v[196:199], v[116:119]
	v_mfma_f32_16x16x32_bf16 v[112:115], v[188:191], v[196:199], v[112:115]
	v_mfma_f32_16x16x32_bf16 v[100:103], v[180:183], v[204:207], v[100:103]
	v_mfma_f32_16x16x32_bf16 v[96:99], v[188:191], v[204:207], v[96:99]
	v_mfma_f32_16x16x32_bf16 v[84:87], v[180:183], v[212:215], v[84:87]
	v_mfma_f32_16x16x32_bf16 v[80:83], v[188:191], v[212:215], v[80:83]
	v_mfma_f32_16x16x32_bf16 v[68:71], v[180:183], v[220:223], v[68:71]
	v_mfma_f32_16x16x32_bf16 v[64:67], v[188:191], v[220:223], v[64:67]
	v_mfma_f32_16x16x32_bf16 v[116:119], v[184:187], v[200:203], v[116:119]
	v_mfma_f32_16x16x32_bf16 v[112:115], v[192:195], v[200:203], v[112:115]
	v_mfma_f32_16x16x32_bf16 v[100:103], v[184:187], v[208:211], v[100:103]
	v_mfma_f32_16x16x32_bf16 v[96:99], v[192:195], v[208:211], v[96:99]
	v_mfma_f32_16x16x32_bf16 v[84:87], v[184:187], v[216:219], v[84:87]
	v_mfma_f32_16x16x32_bf16 v[80:83], v[192:195], v[216:219], v[80:83]
	v_mfma_f32_16x16x32_bf16 v[68:71], v[184:187], v[224:227], v[68:71]
	v_mfma_f32_16x16x32_bf16 v[64:67], v[192:195], v[224:227], v[64:67]
	s_waitcnt vmcnt(4)
	s_barrier
	ds_read_b128 v[180:183], v160
	ds_read_b128 v[184:187], v160 offset:1024
	ds_read_b128 v[188:191], v160 offset:2048
	ds_read_b128 v[192:195], v160 offset:3072
	ds_read_b128 v[196:199], v162 offset:16384
	ds_read_b128 v[200:203], v162 offset:17408
	ds_read_b128 v[204:207], v162 offset:18432
	ds_read_b128 v[208:211], v162 offset:19456
	ds_read_b128 v[212:215], v162 offset:20480
	ds_read_b128 v[216:219], v162 offset:21504
	ds_read_b128 v[220:223], v162 offset:22528
	ds_read_b128 v[224:227], v162 offset:23552
	s_waitcnt lgkmcnt(0)
	v_mfma_f32_16x16x32_bf16 v[116:119], v[180:183], v[196:199], v[116:119]
	v_mfma_f32_16x16x32_bf16 v[112:115], v[188:191], v[196:199], v[112:115]
	v_mfma_f32_16x16x32_bf16 v[100:103], v[180:183], v[204:207], v[100:103]
	v_mfma_f32_16x16x32_bf16 v[96:99], v[188:191], v[204:207], v[96:99]
	v_mfma_f32_16x16x32_bf16 v[84:87], v[180:183], v[212:215], v[84:87]
	v_mfma_f32_16x16x32_bf16 v[80:83], v[188:191], v[212:215], v[80:83]
	v_mfma_f32_16x16x32_bf16 v[68:71], v[180:183], v[220:223], v[68:71]
	v_mfma_f32_16x16x32_bf16 v[64:67], v[188:191], v[220:223], v[64:67]
	v_mfma_f32_16x16x32_bf16 v[116:119], v[184:187], v[200:203], v[116:119]
	v_mfma_f32_16x16x32_bf16 v[112:115], v[192:195], v[200:203], v[112:115]
	v_mfma_f32_16x16x32_bf16 v[100:103], v[184:187], v[208:211], v[100:103]
	v_mfma_f32_16x16x32_bf16 v[96:99], v[192:195], v[208:211], v[96:99]
	v_mfma_f32_16x16x32_bf16 v[84:87], v[184:187], v[216:219], v[84:87]
	v_mfma_f32_16x16x32_bf16 v[80:83], v[192:195], v[216:219], v[80:83]
	v_mfma_f32_16x16x32_bf16 v[68:71], v[184:187], v[224:227], v[68:71]
	v_mfma_f32_16x16x32_bf16 v[64:67], v[192:195], v[224:227], v[64:67]
	s_waitcnt vmcnt(0)
	s_barrier
	ds_read_b128 v[180:183], v163
	ds_read_b128 v[184:187], v163 offset:1024
	ds_read_b128 v[188:191], v163 offset:2048
	ds_read_b128 v[192:195], v163 offset:3072
	ds_read_b128 v[196:199], v162 offset:49152
	ds_read_b128 v[200:203], v162 offset:50176
	ds_read_b128 v[204:207], v162 offset:51200
	ds_read_b128 v[208:211], v162 offset:52224
	ds_read_b128 v[212:215], v162 offset:53248
	ds_read_b128 v[216:219], v162 offset:54272
	ds_read_b128 v[220:223], v162 offset:55296
	ds_read_b128 v[224:227], v162 offset:56320
	s_waitcnt lgkmcnt(0)
	v_mfma_f32_16x16x32_bf16 v[116:119], v[180:183], v[196:199], v[116:119]
	v_mfma_f32_16x16x32_bf16 v[112:115], v[188:191], v[196:199], v[112:115]
	v_mfma_f32_16x16x32_bf16 v[100:103], v[180:183], v[204:207], v[100:103]
	v_mfma_f32_16x16x32_bf16 v[96:99], v[188:191], v[204:207], v[96:99]
	v_mfma_f32_16x16x32_bf16 v[84:87], v[180:183], v[212:215], v[84:87]
	v_mfma_f32_16x16x32_bf16 v[80:83], v[188:191], v[212:215], v[80:83]
	v_mfma_f32_16x16x32_bf16 v[68:71], v[180:183], v[220:223], v[68:71]
	v_mfma_f32_16x16x32_bf16 v[64:67], v[188:191], v[220:223], v[64:67]
	v_mfma_f32_16x16x32_bf16 v[116:119], v[184:187], v[200:203], v[116:119]
	v_mfma_f32_16x16x32_bf16 v[112:115], v[192:195], v[200:203], v[112:115]
	v_mfma_f32_16x16x32_bf16 v[100:103], v[184:187], v[208:211], v[100:103]
	v_mfma_f32_16x16x32_bf16 v[96:99], v[192:195], v[208:211], v[96:99]
	v_mfma_f32_16x16x32_bf16 v[84:87], v[184:187], v[216:219], v[84:87]
	v_mfma_f32_16x16x32_bf16 v[80:83], v[192:195], v[216:219], v[80:83]
	v_mfma_f32_16x16x32_bf16 v[68:71], v[184:187], v[224:227], v[68:71]
	v_mfma_f32_16x16x32_bf16 v[64:67], v[192:195], v[224:227], v[64:67]
	s_branch .LBB0_620
; #define PG8_STAGE(bufoff, gbase, voff) do { _Pragma("unroll") for (int _i = 0; _i < 2; ++_i) \
;         __builtin_amdgcn_global_load_lds((const unsigned*)((const char*)(gbase) + (voff)[_i]), (PG8_LAS unsigned*)(lds + (bufoff) + ldsw + _i * 8192), 16, 0, 0); } while (0)
; #define PG8_LDA(dst, b, h) do { _Pragma("unroll") for (int m = 0; m < 4; ++m) _Pragma("unroll") for (int k = 0; k < 2; ++k) dst[m][k] = *(const PG8_LAS bf16x8*)(lds + PG8_SA(b, h) + aoff + m * 2048 + k * 1024); } while (0)
; #define PG8_LDB(dst, b, h) do { _Pragma("unroll") for (int n = 0; n < 2; ++n) _Pragma("unroll") for (int k = 0; k < 2; ++k) dst[n][k] = *(const PG8_LAS bf16x8*)(lds + PG8_SB(b, h) + boff + n * 2048 + k * 1024); } while (0)
; #define PG8_MMA(ai, bj, At, Bt) do { __builtin_amdgcn_s_setprio(1); _Pragma("unroll") for (int m = 0; m < 4; ++m) _Pragma("unroll") for (int n = 0; n < 2; ++n) _Pragma("unroll") for (int k = 0; k < 2; ++k) \
;         acc[ai][bj][m][n] = __builtin_amdgcn_mfma_f32_16x16x32_bf16(Bt[n][k], At[m][k], acc[ai][bj][m][n], 0, 0, 0); __builtin_amdgcn_s_setprio(0); } while (0)
; #define PG8_WAIT_V(n) asm volatile("s_waitcnt vmcnt(" #n ")" ::: "memory")
; #define PG8_BAR __builtin_amdgcn_s_barrier()
; template <class Epi, class Sched, bool ALIGN_EPI = false, bool SP2 = false>
; __device__ __forceinline__ void gemm_phase(PG8_LAS unsigned char* lds, const Gemm g, const Sched& S, const Epi& E) {
;     ...
;         for (int t = 0; t < nt; t += 2) {
;             const bool last = (t == nt - 2);
;             const char* a1 = cA + (size_t)(t + 1) * kstep;
;             const char* a2 = last ? nA : cA + (size_t)(t + 2) * kstep; const char* b2 = last ? nB : cB + (size_t)(t + 2) * kstep;
;             const char* a3 = a2 + kstep; const char* b3 = b2 + kstep;
;             if (last && has_next) S.a_ready(nxt);
;             if constexpr (SP2) {
;             PG8_LDB(B0, 0, 0); PG8_LDB(B1, 0, 1); PG8_SCHED; PG8_LDA(At, 0, 0); PG8_STAGE(PG8_SA(1, 1), a1 + hstep, voffA);
;             PG8_WAIT_V(8); PG8_WAIT_L(0); PG8_BAR; PG8_MMA(0, 0, At, B0); PG8_MMA(0, 1, At, B1); PG8_BAR; PG8_SCHED;
;             PG8_LDA(At, 0, 1); PG8_STAGE(PG8_SB(0, 0), b2, voffB); PG8_STAGE(PG8_SB(0, 1), b2 + hstep, voffB); PG8_STAGE(PG8_SA(0, 0), a2, voffA);
;             PG8_WAIT_V(8); PG8_WAIT_L(0); PG8_BAR; PG8_MMA(1, 0, At, B0); PG8_MMA(1, 1, At, B1); PG8_BAR; PG8_SCHED;
.Lp3q_lean_q2:
	s_mov_b32 s22, s94
	s_mov_b32 s23, 0
	s_lshl_b64 s[22:23], s[22:23], 19
	s_add_u32 s22, s22, s70
	s_addc_u32 s23, s23, s71
	s_add_u32 s22, s22, 0x80
	s_addc_u32 s23, s23, 0
	s_add_u32 s22, s22, 0x40000
	s_addc_u32 s23, s23, 0
	s_mov_b32 s24, s42
	s_mov_b32 s25, 0
	s_lshl_b64 s[24:25], s[24:25], 19
	s_add_u32 s24, s24, s64
	s_addc_u32 s25, s25, s65
	s_add_u32 s24, s24, 0x80
	s_addc_u32 s25, s25, 0
	s_waitcnt vmcnt(0) lgkmcnt(0)
	s_barrier
	s_add_i32 m0, s0, 0xc000
	s_nop 0
	global_load_lds_dwordx4 v140, s[22:23]
	s_add_i32 m0, s0, 0xe000
	s_nop 0
	global_load_lds_dwordx4 v144, s[22:23]
	s_add_u32 s22, s22, 0x80
	s_addc_u32 s23, s23, 0
	s_add_u32 s24, s24, 0x80
	s_addc_u32 s25, s25, 0
	s_mov_b32 m0, s0
	s_nop 0
	global_load_lds_dwordx4 v140, s[22:23]
	s_add_i32 m0, s0, 0x2000
	s_nop 0
	global_load_lds_dwordx4 v144, s[22:23]
	s_add_i32 m0, s0, 0x14000
	s_nop 0
	global_load_lds_dwordx4 v142, s[24:25]
	s_add_i32 m0, s0, 0x16000
	s_nop 0
	global_load_lds_dwordx4 v146, s[24:25]
	s_add_u32 s22, s22, 0x80
	s_addc_u32 s23, s23, 0
	s_add_u32 s24, s24, 0x80
	s_addc_u32 s25, s25, 0
	s_add_i32 m0, s0, 0x8000
	s_nop 0
	global_load_lds_dwordx4 v140, s[22:23]
	s_add_i32 m0, s0, 0xa000
	s_nop 0
	global_load_lds_dwordx4 v144, s[22:23]
	s_add_i32 m0, s0, 0x1c000
	s_nop 0
	global_load_lds_dwordx4 v142, s[24:25]
	s_add_i32 m0, s0, 0x1e000
	s_nop 0
	global_load_lds_dwordx4 v146, s[24:25]
	ds_read_b128 v[150:153], v160
	ds_read_b128 v[154:157], v160 offset:1024
	ds_read_b128 v[168:171], v160 offset:2048
	ds_read_b128 v[176:179], v160 offset:3072
	ds_read_b128 v[196:199], v162 offset:16384
	ds_read_b128 v[200:203], v162 offset:17408
	ds_read_b128 v[204:207], v162 offset:18432
	ds_read_b128 v[208:211], v162 offset:19456
	ds_read_b128 v[212:215], v162 offset:20480
	ds_read_b128 v[216:219], v162 offset:21504
	ds_read_b128 v[220:223], v162 offset:22528
	ds_read_b128 v[224:227], v162 offset:23552
	s_waitcnt lgkmcnt(0)
	v_mfma_f32_16x16x32_bf16 v[60:63], v[150:153], v[196:199], v[60:63]
	v_mfma_f32_16x16x32_bf16 v[56:59], v[168:171], v[196:199], v[56:59]
	v_mfma_f32_16x16x32_bf16 v[44:47], v[150:153], v[204:207], v[44:47]
	v_mfma_f32_16x16x32_bf16 v[40:43], v[168:171], v[204:207], v[40:43]
	v_mfma_f32_16x16x32_bf16 v[28:31], v[150:153], v[212:215], v[28:31]
	v_mfma_f32_16x16x32_bf16 v[24:27], v[168:171], v[212:215], v[24:27]
	v_mfma_f32_16x16x32_bf16 v[12:15], v[150:153], v[220:223], v[12:15]
	v_mfma_f32_16x16x32_bf16 v[8:11], v[168:171], v[220:223], v[8:11]
	v_mfma_f32_16x16x32_bf16 v[60:63], v[154:157], v[200:203], v[60:63]
	v_mfma_f32_16x16x32_bf16 v[56:59], v[176:179], v[200:203], v[56:59]
	v_mfma_f32_16x16x32_bf16 v[44:47], v[154:157], v[208:211], v[44:47]
	v_mfma_f32_16x16x32_bf16 v[40:43], v[176:179], v[208:211], v[40:43]
	v_mfma_f32_16x16x32_bf16 v[28:31], v[154:157], v[216:219], v[28:31]
	v_mfma_f32_16x16x32_bf16 v[24:27], v[176:179], v[216:219], v[24:27]
	v_mfma_f32_16x16x32_bf16 v[12:15], v[154:157], v[224:227], v[12:15]
	v_mfma_f32_16x16x32_bf16 v[8:11], v[176:179], v[224:227], v[8:11]
	s_waitcnt vmcnt(8)
	s_barrier
	ds_read_b128 v[150:153], v163
	ds_read_b128 v[154:157], v163 offset:1024
	ds_read_b128 v[168:171], v163 offset:2048
	ds_read_b128 v[176:179], v163 offset:3072
	ds_read_b128 v[196:199], v162 offset:49152
	ds_read_b128 v[200:203], v162 offset:50176
	ds_read_b128 v[204:207], v162 offset:51200
	ds_read_b128 v[208:211], v162 offset:52224
	ds_read_b128 v[212:215], v162 offset:53248
	ds_read_b128 v[216:219], v162 offset:54272
	ds_read_b128 v[220:223], v162 offset:55296
	ds_read_b128 v[224:227], v162 offset:56320
	s_add_u32 s22, s22, 0x80
	s_addc_u32 s23, s23, 0
	s_add_u32 s24, s24, 0x80
	s_addc_u32 s25, s25, 0
	s_add_i32 m0, s0, 0x4000
	s_nop 0
	global_load_lds_dwordx4 v140, s[22:23]
	s_add_i32 m0, s0, 0x6000
	s_nop 0
	global_load_lds_dwordx4 v144, s[22:23]
	s_add_i32 m0, s0, 0x10000
	s_nop 0
	global_load_lds_dwordx4 v142, s[24:25]
	s_add_i32 m0, s0, 0x12000
	s_nop 0
	global_load_lds_dwordx4 v146, s[24:25]
	s_waitcnt lgkmcnt(0)
	v_mfma_f32_16x16x32_bf16 v[60:63], v[150:153], v[196:199], v[60:63]
	v_mfma_f32_16x16x32_bf16 v[56:59], v[168:171], v[196:199], v[56:59]
	v_mfma_f32_16x16x32_bf16 v[44:47], v[150:153], v[204:207], v[44:47]
	v_mfma_f32_16x16x32_bf16 v[40:43], v[168:171], v[204:207], v[40:43]
	v_mfma_f32_16x16x32_bf16 v[28:31], v[150:153], v[212:215], v[28:31]
	v_mfma_f32_16x16x32_bf16 v[24:27], v[168:171], v[212:215], v[24:27]
	v_mfma_f32_16x16x32_bf16 v[12:15], v[150:153], v[220:223], v[12:15]
	v_mfma_f32_16x16x32_bf16 v[8:11], v[168:171], v[220:223], v[8:11]
	v_mfma_f32_16x16x32_bf16 v[60:63], v[154:157], v[200:203], v[60:63]
	v_mfma_f32_16x16x32_bf16 v[56:59], v[176:179], v[200:203], v[56:59]
	v_mfma_f32_16x16x32_bf16 v[44:47], v[154:157], v[208:211], v[44:47]
	v_mfma_f32_16x16x32_bf16 v[40:43], v[176:179], v[208:211], v[40:43]
	v_mfma_f32_16x16x32_bf16 v[28:31], v[154:157], v[216:219], v[28:31]
	v_mfma_f32_16x16x32_bf16 v[24:27], v[176:179], v[216:219], v[24:27]
	v_mfma_f32_16x16x32_bf16 v[12:15], v[154:157], v[224:227], v[12:15]
	v_mfma_f32_16x16x32_bf16 v[8:11], v[176:179], v[224:227], v[8:11]
	s_waitcnt vmcnt(8)
	s_barrier
; #define PG8_STAGE(bufoff, gbase, voff) do { _Pragma("unroll") for (int _i = 0; _i < 2; ++_i) \
;         __builtin_amdgcn_global_load_lds((const unsigned*)((const char*)(gbase) + (voff)[_i]), (PG8_LAS unsigned*)(lds + (bufoff) + ldsw + _i * 8192), 16, 0, 0); } while (0)
; #define PG8_LDA(dst, b, h) do { _Pragma("unroll") for (int m = 0; m < 4; ++m) _Pragma("unroll") for (int k = 0; k < 2; ++k) dst[m][k] = *(const PG8_LAS bf16x8*)(lds + PG8_SA(b, h) + aoff + m * 2048 + k * 1024); } while (0)
; #define PG8_LDB(dst, b, h) do { _Pragma("unroll") for (int n = 0; n < 2; ++n) _Pragma("unroll") for (int k = 0; k < 2; ++k) dst[n][k] = *(const PG8_LAS bf16x8*)(lds + PG8_SB(b, h) + boff + n * 2048 + k * 1024); } while (0)
; #define PG8_MMA(ai, bj, At, Bt) do { __builtin_amdgcn_s_setprio(1); _Pragma("unroll") for (int m = 0; m < 4; ++m) _Pragma("unroll") for (int n = 0; n < 2; ++n) _Pragma("unroll") for (int k = 0; k < 2; ++k) \
;         acc[ai][bj][m][n] = __builtin_amdgcn_mfma_f32_16x16x32_bf16(Bt[n][k], At[m][k], acc[ai][bj][m][n], 0, 0, 0); __builtin_amdgcn_s_setprio(0); } while (0)
; #define PG8_WAIT_V(n) asm volatile("s_waitcnt vmcnt(" #n ")" ::: "memory")
; template <class Epi, class Sched, bool ALIGN_EPI = false, bool SP2 = false>
; __device__ __forceinline__ void gemm_phase(PG8_LAS unsigned char* lds, const Gemm g, const Sched& S, const Epi& E) {
;     ...
;             PG8_LDB(B0, 0, 0); PG8_LDB(B1, 0, 1); PG8_SCHED; PG8_LDA(At, 0, 0); PG8_STAGE(PG8_SA(1, 1), a1 + hstep, voffA);
;             PG8_WAIT_V(8); PG8_WAIT_L(0); PG8_BAR; PG8_MMA(0, 0, At, B0); PG8_MMA(0, 1, At, B1); PG8_BAR; PG8_SCHED;
;             PG8_LDA(At, 0, 1); PG8_STAGE(PG8_SB(0, 0), b2, voffB); PG8_STAGE(PG8_SB(0, 1), b2 + hstep, voffB); PG8_STAGE(PG8_SA(0, 0), a2, voffA);
;             PG8_WAIT_V(8); PG8_WAIT_L(0); PG8_BAR; PG8_MMA(1, 0, At, B0); PG8_MMA(1, 1, At, B1); PG8_BAR; PG8_SCHED;
;             PG8_LDB(B0, 1, 0); PG8_LDB(B1, 1, 1); PG8_SCHED; PG8_LDA(At, 1, 0); PG8_STAGE(PG8_SA(0, 1), a2 + hstep, voffA);
;             PG8_WAIT_V(8); PG8_WAIT_L(0); PG8_BAR; PG8_MMA(0, 0, At, B0); PG8_MMA(0, 1, At, B1); PG8_BAR; PG8_SCHED;
;             PG8_LDA(At, 1, 1); PG8_STAGE(PG8_SB(1, 0), b3, voffB); PG8_STAGE(PG8_SB(1, 1), b3 + hstep, voffB); PG8_STAGE(PG8_SA(1, 0), a3, voffA);
;             PG8_WAIT_V(8); PG8_WAIT_L(0); PG8_BAR; PG8_MMA(1, 0, At, B0); PG8_MMA(1, 1, At, B1); PG8_BAR; PG8_SCHED;
	ds_read_b128 v[150:153], v161
	ds_read_b128 v[154:157], v161 offset:1024
	ds_read_b128 v[168:171], v161 offset:2048
	ds_read_b128 v[176:179], v161 offset:3072
	ds_read_b128 v[196:199], v162
	ds_read_b128 v[200:203], v162 offset:1024
	ds_read_b128 v[204:207], v162 offset:2048
	ds_read_b128 v[208:211], v162 offset:3072
	ds_read_b128 v[212:215], v162 offset:4096
	ds_read_b128 v[216:219], v162 offset:5120
	ds_read_b128 v[220:223], v162 offset:6144
	ds_read_b128 v[224:227], v162 offset:7168
	s_add_u32 s22, s22, 0x80
	s_addc_u32 s23, s23, 0
	s_add_u32 s24, s24, 0x80
	s_addc_u32 s25, s25, 0
	s_add_i32 m0, s0, 0xc000
	s_nop 0
	global_load_lds_dwordx4 v140, s[22:23]
	s_add_i32 m0, s0, 0xe000
	s_nop 0
	global_load_lds_dwordx4 v144, s[22:23]
	s_add_i32 m0, s0, 0x18000
	s_nop 0
	global_load_lds_dwordx4 v142, s[24:25]
	s_add_i32 m0, s0, 0x1a000
	s_nop 0
	global_load_lds_dwordx4 v146, s[24:25]
	s_waitcnt lgkmcnt(0)
	v_mfma_f32_16x16x32_bf16 v[60:63], v[150:153], v[196:199], v[60:63]
	v_mfma_f32_16x16x32_bf16 v[56:59], v[168:171], v[196:199], v[56:59]
	v_mfma_f32_16x16x32_bf16 v[44:47], v[150:153], v[204:207], v[44:47]
	v_mfma_f32_16x16x32_bf16 v[40:43], v[168:171], v[204:207], v[40:43]
	v_mfma_f32_16x16x32_bf16 v[28:31], v[150:153], v[212:215], v[28:31]
	v_mfma_f32_16x16x32_bf16 v[24:27], v[168:171], v[212:215], v[24:27]
	v_mfma_f32_16x16x32_bf16 v[12:15], v[150:153], v[220:223], v[12:15]
	v_mfma_f32_16x16x32_bf16 v[8:11], v[168:171], v[220:223], v[8:11]
	v_mfma_f32_16x16x32_bf16 v[60:63], v[154:157], v[200:203], v[60:63]
	v_mfma_f32_16x16x32_bf16 v[56:59], v[176:179], v[200:203], v[56:59]
	v_mfma_f32_16x16x32_bf16 v[44:47], v[154:157], v[208:211], v[44:47]
	v_mfma_f32_16x16x32_bf16 v[40:43], v[176:179], v[208:211], v[40:43]
	v_mfma_f32_16x16x32_bf16 v[28:31], v[154:157], v[216:219], v[28:31]
	v_mfma_f32_16x16x32_bf16 v[24:27], v[176:179], v[216:219], v[24:27]
	v_mfma_f32_16x16x32_bf16 v[12:15], v[154:157], v[224:227], v[12:15]
	v_mfma_f32_16x16x32_bf16 v[8:11], v[176:179], v[224:227], v[8:11]
	s_waitcnt vmcnt(8)
	s_barrier
	ds_read_b128 v[150:153], v164
	ds_read_b128 v[154:157], v164 offset:1024
	ds_read_b128 v[168:171], v164 offset:2048
	ds_read_b128 v[176:179], v164 offset:3072
	ds_read_b128 v[196:199], v162 offset:32768
	ds_read_b128 v[200:203], v162 offset:33792
	ds_read_b128 v[204:207], v162 offset:34816
	ds_read_b128 v[208:211], v162 offset:35840
	ds_read_b128 v[212:215], v162 offset:36864
	ds_read_b128 v[216:219], v162 offset:37888
	ds_read_b128 v[220:223], v162 offset:38912
	ds_read_b128 v[224:227], v162 offset:39936
	s_add_u32 s22, s22, 0x80
	s_addc_u32 s23, s23, 0
	s_add_u32 s24, s24, 0x80
	s_addc_u32 s25, s25, 0
	s_mov_b32 m0, s0
	s_nop 0
	global_load_lds_dwordx4 v140, s[22:23]
	s_add_i32 m0, s0, 0x2000
	s_nop 0
	global_load_lds_dwordx4 v144, s[22:23]
	s_add_i32 m0, s0, 0x14000
	s_nop 0
	global_load_lds_dwordx4 v142, s[24:25]
	s_add_i32 m0, s0, 0x16000
	s_nop 0
	global_load_lds_dwordx4 v146, s[24:25]
	s_waitcnt lgkmcnt(0)
	v_mfma_f32_16x16x32_bf16 v[60:63], v[150:153], v[196:199], v[60:63]
	v_mfma_f32_16x16x32_bf16 v[56:59], v[168:171], v[196:199], v[56:59]
	v_mfma_f32_16x16x32_bf16 v[44:47], v[150:153], v[204:207], v[44:47]
	v_mfma_f32_16x16x32_bf16 v[40:43], v[168:171], v[204:207], v[40:43]
	v_mfma_f32_16x16x32_bf16 v[28:31], v[150:153], v[212:215], v[28:31]
	v_mfma_f32_16x16x32_bf16 v[24:27], v[168:171], v[212:215], v[24:27]
	v_mfma_f32_16x16x32_bf16 v[12:15], v[150:153], v[220:223], v[12:15]
	v_mfma_f32_16x16x32_bf16 v[8:11], v[168:171], v[220:223], v[8:11]
	v_mfma_f32_16x16x32_bf16 v[60:63], v[154:157], v[200:203], v[60:63]
	v_mfma_f32_16x16x32_bf16 v[56:59], v[176:179], v[200:203], v[56:59]
	v_mfma_f32_16x16x32_bf16 v[44:47], v[154:157], v[208:211], v[44:47]
	v_mfma_f32_16x16x32_bf16 v[40:43], v[176:179], v[208:211], v[40:43]
	v_mfma_f32_16x16x32_bf16 v[28:31], v[154:157], v[216:219], v[28:31]
	v_mfma_f32_16x16x32_bf16 v[24:27], v[176:179], v[216:219], v[24:27]
	v_mfma_f32_16x16x32_bf16 v[12:15], v[154:157], v[224:227], v[12:15]
	v_mfma_f32_16x16x32_bf16 v[8:11], v[176:179], v[224:227], v[8:11]
	s_waitcnt vmcnt(8)
	s_barrier
	ds_read_b128 v[150:153], v160
	ds_read_b128 v[154:157], v160 offset:1024
	ds_read_b128 v[168:171], v160 offset:2048
	ds_read_b128 v[176:179], v160 offset:3072
	ds_read_b128 v[196:199], v162 offset:16384
	ds_read_b128 v[200:203], v162 offset:17408
	ds_read_b128 v[204:207], v162 offset:18432
	ds_read_b128 v[208:211], v162 offset:19456
	ds_read_b128 v[212:215], v162 offset:20480
	ds_read_b128 v[216:219], v162 offset:21504
	ds_read_b128 v[220:223], v162 offset:22528
	ds_read_b128 v[224:227], v162 offset:23552
	s_add_u32 s22, s22, 0x80
	s_addc_u32 s23, s23, 0
	s_add_u32 s24, s24, 0x80
	s_addc_u32 s25, s25, 0
	s_add_i32 m0, s0, 0x8000
	s_nop 0
	global_load_lds_dwordx4 v140, s[22:23]
	s_add_i32 m0, s0, 0xa000
	s_nop 0
	global_load_lds_dwordx4 v144, s[22:23]
	s_add_i32 m0, s0, 0x1c000
	s_nop 0
	global_load_lds_dwordx4 v142, s[24:25]
	s_add_i32 m0, s0, 0x1e000
	s_nop 0
	global_load_lds_dwordx4 v146, s[24:25]
	s_waitcnt lgkmcnt(0)
	v_mfma_f32_16x16x32_bf16 v[60:63], v[150:153], v[196:199], v[60:63]
	v_mfma_f32_16x16x32_bf16 v[56:59], v[168:171], v[196:199], v[56:59]
	v_mfma_f32_16x16x32_bf16 v[44:47], v[150:153], v[204:207], v[44:47]
	v_mfma_f32_16x16x32_bf16 v[40:43], v[168:171], v[204:207], v[40:43]
	v_mfma_f32_16x16x32_bf16 v[28:31], v[150:153], v[212:215], v[28:31]
	v_mfma_f32_16x16x32_bf16 v[24:27], v[168:171], v[212:215], v[24:27]
	v_mfma_f32_16x16x32_bf16 v[12:15], v[150:153], v[220:223], v[12:15]
	v_mfma_f32_16x16x32_bf16 v[8:11], v[168:171], v[220:223], v[8:11]
	v_mfma_f32_16x16x32_bf16 v[60:63], v[154:157], v[200:203], v[60:63]
	v_mfma_f32_16x16x32_bf16 v[56:59], v[176:179], v[200:203], v[56:59]
	v_mfma_f32_16x16x32_bf16 v[44:47], v[154:157], v[208:211], v[44:47]
	v_mfma_f32_16x16x32_bf16 v[40:43], v[176:179], v[208:211], v[40:43]
	v_mfma_f32_16x16x32_bf16 v[28:31], v[154:157], v[216:219], v[28:31]
	v_mfma_f32_16x16x32_bf16 v[24:27], v[176:179], v[216:219], v[24:27]
	v_mfma_f32_16x16x32_bf16 v[12:15], v[154:157], v[224:227], v[12:15]
	v_mfma_f32_16x16x32_bf16 v[8:11], v[176:179], v[224:227], v[8:11]
	s_waitcnt vmcnt(8)
	s_barrier
; #define PG8_STAGE(bufoff, gbase, voff) do { _Pragma("unroll") for (int _i = 0; _i < 2; ++_i) \
;         __builtin_amdgcn_global_load_lds((const unsigned*)((const char*)(gbase) + (voff)[_i]), (PG8_LAS unsigned*)(lds + (bufoff) + ldsw + _i * 8192), 16, 0, 0); } while (0)
; #define PG8_LDA(dst, b, h) do { _Pragma("unroll") for (int m = 0; m < 4; ++m) _Pragma("unroll") for (int k = 0; k < 2; ++k) dst[m][k] = *(const PG8_LAS bf16x8*)(lds + PG8_SA(b, h) + aoff + m * 2048 + k * 1024); } while (0)
; #define PG8_LDB(dst, b, h) do { _Pragma("unroll") for (int n = 0; n < 2; ++n) _Pragma("unroll") for (int k = 0; k < 2; ++k) dst[n][k] = *(const PG8_LAS bf16x8*)(lds + PG8_SB(b, h) + boff + n * 2048 + k * 1024); } while (0)
; #define PG8_MMA(ai, bj, At, Bt) do { __builtin_amdgcn_s_setprio(1); _Pragma("unroll") for (int m = 0; m < 4; ++m) _Pragma("unroll") for (int n = 0; n < 2; ++n) _Pragma("unroll") for (int k = 0; k < 2; ++k) \
;         acc[ai][bj][m][n] = __builtin_amdgcn_mfma_f32_16x16x32_bf16(Bt[n][k], At[m][k], acc[ai][bj][m][n], 0, 0, 0); __builtin_amdgcn_s_setprio(0); } while (0)
; #define PG8_WAIT_V(n) asm volatile("s_waitcnt vmcnt(" #n ")" ::: "memory")
; template <class Epi, class Sched, bool ALIGN_EPI = false, bool SP2 = false>
; __device__ __forceinline__ void gemm_phase(PG8_LAS unsigned char* lds, const Gemm g, const Sched& S, const Epi& E) {
;     ...
;             PG8_LDB(B0, 0, 0); PG8_LDB(B1, 0, 1); PG8_SCHED; PG8_LDA(At, 0, 0); PG8_STAGE(PG8_SA(1, 1), a1 + hstep, voffA);
;             PG8_WAIT_V(8); PG8_WAIT_L(0); PG8_BAR; PG8_MMA(0, 0, At, B0); PG8_MMA(0, 1, At, B1); PG8_BAR; PG8_SCHED;
;             PG8_LDA(At, 0, 1); PG8_STAGE(PG8_SB(0, 0), b2, voffB); PG8_STAGE(PG8_SB(0, 1), b2 + hstep, voffB); PG8_STAGE(PG8_SA(0, 0), a2, voffA);
;             PG8_WAIT_V(8); PG8_WAIT_L(0); PG8_BAR; PG8_MMA(1, 0, At, B0); PG8_MMA(1, 1, At, B1); PG8_BAR; PG8_SCHED;
;             PG8_LDB(B0, 1, 0); PG8_LDB(B1, 1, 1); PG8_SCHED; PG8_LDA(At, 1, 0); PG8_STAGE(PG8_SA(0, 1), a2 + hstep, voffA);
;             PG8_WAIT_V(8); PG8_WAIT_L(0); PG8_BAR; PG8_MMA(0, 0, At, B0); PG8_MMA(0, 1, At, B1); PG8_BAR; PG8_SCHED;
;             PG8_LDA(At, 1, 1); PG8_STAGE(PG8_SB(1, 0), b3, voffB); PG8_STAGE(PG8_SB(1, 1), b3 + hstep, voffB); PG8_STAGE(PG8_SA(1, 0), a3, voffA);
;             PG8_WAIT_V(8); PG8_WAIT_L(0); PG8_BAR; PG8_MMA(1, 0, At, B0); PG8_MMA(1, 1, At, B1); PG8_BAR; PG8_SCHED;
	ds_read_b128 v[150:153], v163
	ds_read_b128 v[154:157], v163 offset:1024
	ds_read_b128 v[168:171], v163 offset:2048
	ds_read_b128 v[176:179], v163 offset:3072
	ds_read_b128 v[196:199], v162 offset:49152
	ds_read_b128 v[200:203], v162 offset:50176
	ds_read_b128 v[204:207], v162 offset:51200
	ds_read_b128 v[208:211], v162 offset:52224
	ds_read_b128 v[212:215], v162 offset:53248
	ds_read_b128 v[216:219], v162 offset:54272
	ds_read_b128 v[220:223], v162 offset:55296
	ds_read_b128 v[224:227], v162 offset:56320
	s_add_u32 s22, s22, 0x80
	s_addc_u32 s23, s23, 0
	s_add_u32 s24, s24, 0x80
	s_addc_u32 s25, s25, 0
	s_add_i32 m0, s0, 0x4000
	s_nop 0
	global_load_lds_dwordx4 v140, s[22:23]
	s_add_i32 m0, s0, 0x6000
	s_nop 0
	global_load_lds_dwordx4 v144, s[22:23]
	s_add_i32 m0, s0, 0x10000
	s_nop 0
	global_load_lds_dwordx4 v142, s[24:25]
	s_add_i32 m0, s0, 0x12000
	s_nop 0
	global_load_lds_dwordx4 v146, s[24:25]
	s_waitcnt lgkmcnt(0)
	v_mfma_f32_16x16x32_bf16 v[60:63], v[150:153], v[196:199], v[60:63]
	v_mfma_f32_16x16x32_bf16 v[56:59], v[168:171], v[196:199], v[56:59]
	v_mfma_f32_16x16x32_bf16 v[44:47], v[150:153], v[204:207], v[44:47]
	v_mfma_f32_16x16x32_bf16 v[40:43], v[168:171], v[204:207], v[40:43]
	v_mfma_f32_16x16x32_bf16 v[28:31], v[150:153], v[212:215], v[28:31]
	v_mfma_f32_16x16x32_bf16 v[24:27], v[168:171], v[212:215], v[24:27]
	v_mfma_f32_16x16x32_bf16 v[12:15], v[150:153], v[220:223], v[12:15]
	v_mfma_f32_16x16x32_bf16 v[8:11], v[168:171], v[220:223], v[8:11]
	v_mfma_f32_16x16x32_bf16 v[60:63], v[154:157], v[200:203], v[60:63]
	v_mfma_f32_16x16x32_bf16 v[56:59], v[176:179], v[200:203], v[56:59]
	v_mfma_f32_16x16x32_bf16 v[44:47], v[154:157], v[208:211], v[44:47]
	v_mfma_f32_16x16x32_bf16 v[40:43], v[176:179], v[208:211], v[40:43]
	v_mfma_f32_16x16x32_bf16 v[28:31], v[154:157], v[216:219], v[28:31]
	v_mfma_f32_16x16x32_bf16 v[24:27], v[176:179], v[216:219], v[24:27]
	v_mfma_f32_16x16x32_bf16 v[12:15], v[154:157], v[224:227], v[12:15]
	v_mfma_f32_16x16x32_bf16 v[8:11], v[176:179], v[224:227], v[8:11]
	s_waitcnt vmcnt(8)
	s_barrier
	ds_read_b128 v[150:153], v161
	ds_read_b128 v[154:157], v161 offset:1024
	ds_read_b128 v[168:171], v161 offset:2048
	ds_read_b128 v[176:179], v161 offset:3072
	ds_read_b128 v[196:199], v162
	ds_read_b128 v[200:203], v162 offset:1024
	ds_read_b128 v[204:207], v162 offset:2048
	ds_read_b128 v[208:211], v162 offset:3072
	ds_read_b128 v[212:215], v162 offset:4096
	ds_read_b128 v[216:219], v162 offset:5120
	ds_read_b128 v[220:223], v162 offset:6144
	ds_read_b128 v[224:227], v162 offset:7168
	s_add_u32 s22, s22, 0x80
	s_addc_u32 s23, s23, 0
	s_add_u32 s24, s24, 0x80
	s_addc_u32 s25, s25, 0
	s_add_i32 m0, s0, 0xc000
	s_nop 0
	global_load_lds_dwordx4 v140, s[22:23]
	s_add_i32 m0, s0, 0xe000
	s_nop 0
	global_load_lds_dwordx4 v144, s[22:23]
	s_add_i32 m0, s0, 0x18000
	s_nop 0
	global_load_lds_dwordx4 v142, s[24:25]
	s_add_i32 m0, s0, 0x1a000
	s_nop 0
	global_load_lds_dwordx4 v146, s[24:25]
	s_waitcnt lgkmcnt(0)
	v_mfma_f32_16x16x32_bf16 v[60:63], v[150:153], v[196:199], v[60:63]
	v_mfma_f32_16x16x32_bf16 v[56:59], v[168:171], v[196:199], v[56:59]
	v_mfma_f32_16x16x32_bf16 v[44:47], v[150:153], v[204:207], v[44:47]
	v_mfma_f32_16x16x32_bf16 v[40:43], v[168:171], v[204:207], v[40:43]
	v_mfma_f32_16x16x32_bf16 v[28:31], v[150:153], v[212:215], v[28:31]
	v_mfma_f32_16x16x32_bf16 v[24:27], v[168:171], v[212:215], v[24:27]
	v_mfma_f32_16x16x32_bf16 v[12:15], v[150:153], v[220:223], v[12:15]
	v_mfma_f32_16x16x32_bf16 v[8:11], v[168:171], v[220:223], v[8:11]
	v_mfma_f32_16x16x32_bf16 v[60:63], v[154:157], v[200:203], v[60:63]
	v_mfma_f32_16x16x32_bf16 v[56:59], v[176:179], v[200:203], v[56:59]
	v_mfma_f32_16x16x32_bf16 v[44:47], v[154:157], v[208:211], v[44:47]
	v_mfma_f32_16x16x32_bf16 v[40:43], v[176:179], v[208:211], v[40:43]
	v_mfma_f32_16x16x32_bf16 v[28:31], v[154:157], v[216:219], v[28:31]
	v_mfma_f32_16x16x32_bf16 v[24:27], v[176:179], v[216:219], v[24:27]
	v_mfma_f32_16x16x32_bf16 v[12:15], v[154:157], v[224:227], v[12:15]
	v_mfma_f32_16x16x32_bf16 v[8:11], v[176:179], v[224:227], v[8:11]
	s_waitcnt vmcnt(8)
	s_barrier
	ds_read_b128 v[150:153], v164
	ds_read_b128 v[154:157], v164 offset:1024
	ds_read_b128 v[168:171], v164 offset:2048
	ds_read_b128 v[176:179], v164 offset:3072
	ds_read_b128 v[196:199], v162 offset:32768
	ds_read_b128 v[200:203], v162 offset:33792
	ds_read_b128 v[204:207], v162 offset:34816
	ds_read_b128 v[208:211], v162 offset:35840
	ds_read_b128 v[212:215], v162 offset:36864
	ds_read_b128 v[216:219], v162 offset:37888
	ds_read_b128 v[220:223], v162 offset:38912
	ds_read_b128 v[224:227], v162 offset:39936
	s_add_u32 s22, s22, 0x80
	s_addc_u32 s23, s23, 0
	s_add_u32 s24, s24, 0x80
	s_addc_u32 s25, s25, 0
	s_mov_b32 m0, s0
	s_nop 0
	global_load_lds_dwordx4 v140, s[22:23]
	s_add_i32 m0, s0, 0x2000
	s_nop 0
	global_load_lds_dwordx4 v144, s[22:23]
	s_add_i32 m0, s0, 0x14000
	s_nop 0
	global_load_lds_dwordx4 v142, s[24:25]
	s_add_i32 m0, s0, 0x16000
	s_nop 0
	global_load_lds_dwordx4 v146, s[24:25]
	s_waitcnt lgkmcnt(0)
	v_mfma_f32_16x16x32_bf16 v[60:63], v[150:153], v[196:199], v[60:63]
	v_mfma_f32_16x16x32_bf16 v[56:59], v[168:171], v[196:199], v[56:59]
	v_mfma_f32_16x16x32_bf16 v[44:47], v[150:153], v[204:207], v[44:47]
	v_mfma_f32_16x16x32_bf16 v[40:43], v[168:171], v[204:207], v[40:43]
	v_mfma_f32_16x16x32_bf16 v[28:31], v[150:153], v[212:215], v[28:31]
	v_mfma_f32_16x16x32_bf16 v[24:27], v[168:171], v[212:215], v[24:27]
	v_mfma_f32_16x16x32_bf16 v[12:15], v[150:153], v[220:223], v[12:15]
	v_mfma_f32_16x16x32_bf16 v[8:11], v[168:171], v[220:223], v[8:11]
	v_mfma_f32_16x16x32_bf16 v[60:63], v[154:157], v[200:203], v[60:63]
	v_mfma_f32_16x16x32_bf16 v[56:59], v[176:179], v[200:203], v[56:59]
	v_mfma_f32_16x16x32_bf16 v[44:47], v[154:157], v[208:211], v[44:47]
	v_mfma_f32_16x16x32_bf16 v[40:43], v[176:179], v[208:211], v[40:43]
	v_mfma_f32_16x16x32_bf16 v[28:31], v[154:157], v[216:219], v[28:31]
	v_mfma_f32_16x16x32_bf16 v[24:27], v[176:179], v[216:219], v[24:27]
	v_mfma_f32_16x16x32_bf16 v[12:15], v[154:157], v[224:227], v[12:15]
	v_mfma_f32_16x16x32_bf16 v[8:11], v[176:179], v[224:227], v[8:11]
	s_waitcnt vmcnt(8)
	s_barrier
; #define PG8_STAGE(bufoff, gbase, voff) do { _Pragma("unroll") for (int _i = 0; _i < 2; ++_i) \
;         __builtin_amdgcn_global_load_lds((const unsigned*)((const char*)(gbase) + (voff)[_i]), (PG8_LAS unsigned*)(lds + (bufoff) + ldsw + _i * 8192), 16, 0, 0); } while (0)
; #define PG8_LDA(dst, b, h) do { _Pragma("unroll") for (int m = 0; m < 4; ++m) _Pragma("unroll") for (int k = 0; k < 2; ++k) dst[m][k] = *(const PG8_LAS bf16x8*)(lds + PG8_SA(b, h) + aoff + m * 2048 + k * 1024); } while (0)
; #define PG8_LDB(dst, b, h) do { _Pragma("unroll") for (int n = 0; n < 2; ++n) _Pragma("unroll") for (int k = 0; k < 2; ++k) dst[n][k] = *(const PG8_LAS bf16x8*)(lds + PG8_SB(b, h) + boff + n * 2048 + k * 1024); } while (0)
; #define PG8_MMA(ai, bj, At, Bt) do { __builtin_amdgcn_s_setprio(1); _Pragma("unroll") for (int m = 0; m < 4; ++m) _Pragma("unroll") for (int n = 0; n < 2; ++n) _Pragma("unroll") for (int k = 0; k < 2; ++k) \
;         acc[ai][bj][m][n] = __builtin_amdgcn_mfma_f32_16x16x32_bf16(Bt[n][k], At[m][k], acc[ai][bj][m][n], 0, 0, 0); __builtin_amdgcn_s_setprio(0); } while (0)
; #define PG8_WAIT_V(n) asm volatile("s_waitcnt vmcnt(" #n ")" ::: "memory")
; template <class Epi, class Sched, bool ALIGN_EPI = false, bool SP2 = false>
; __device__ __forceinline__ void gemm_phase(PG8_LAS unsigned char* lds, const Gemm g, const Sched& S, const Epi& E) {
;     ...
;             PG8_LDB(B0, 0, 0); PG8_LDB(B1, 0, 1); PG8_SCHED; PG8_LDA(At, 0, 0); PG8_STAGE(PG8_SA(1, 1), a1 + hstep, voffA);
;             PG8_WAIT_V(8); PG8_WAIT_L(0); PG8_BAR; PG8_MMA(0, 0, At, B0); PG8_MMA(0, 1, At, B1); PG8_BAR; PG8_SCHED;
;             PG8_LDA(At, 0, 1); PG8_STAGE(PG8_SB(0, 0), b2, voffB); PG8_STAGE(PG8_SB(0, 1), b2 + hstep, voffB); PG8_STAGE(PG8_SA(0, 0), a2, voffA);
;             PG8_WAIT_V(8); PG8_WAIT_L(0); PG8_BAR; PG8_MMA(1, 0, At, B0); PG8_MMA(1, 1, At, B1); PG8_BAR; PG8_SCHED;
;             PG8_LDB(B0, 1, 0); PG8_LDB(B1, 1, 1); PG8_SCHED; PG8_LDA(At, 1, 0); PG8_STAGE(PG8_SA(0, 1), a2 + hstep, voffA);
;             PG8_WAIT_V(8); PG8_WAIT_L(0); PG8_BAR; PG8_MMA(0, 0, At, B0); PG8_MMA(0, 1, At, B1); PG8_BAR; PG8_SCHED;
;             PG8_LDA(At, 1, 1); PG8_STAGE(PG8_SB(1, 0), b3, voffB); PG8_STAGE(PG8_SB(1, 1), b3 + hstep, voffB); PG8_STAGE(PG8_SA(1, 0), a3, voffA);
;             PG8_WAIT_V(8); PG8_WAIT_L(0); PG8_BAR; PG8_MMA(1, 0, At, B0); PG8_MMA(1, 1, At, B1); PG8_BAR; PG8_SCHED;
	ds_read_b128 v[150:153], v160
	ds_read_b128 v[154:157], v160 offset:1024
	ds_read_b128 v[168:171], v160 offset:2048
	ds_read_b128 v[176:179], v160 offset:3072
	ds_read_b128 v[196:199], v162 offset:16384
	ds_read_b128 v[200:203], v162 offset:17408
	ds_read_b128 v[204:207], v162 offset:18432
	ds_read_b128 v[208:211], v162 offset:19456
	ds_read_b128 v[212:215], v162 offset:20480
	ds_read_b128 v[216:219], v162 offset:21504
	ds_read_b128 v[220:223], v162 offset:22528
	ds_read_b128 v[224:227], v162 offset:23552
	s_add_u32 s22, s22, 0x80
	s_addc_u32 s23, s23, 0
	s_add_u32 s24, s24, 0x80
	s_addc_u32 s25, s25, 0
	s_add_i32 m0, s0, 0x8000
	s_nop 0
	global_load_lds_dwordx4 v140, s[22:23]
	s_add_i32 m0, s0, 0xa000
	s_nop 0
	global_load_lds_dwordx4 v144, s[22:23]
	s_add_i32 m0, s0, 0x1c000
	s_nop 0
	global_load_lds_dwordx4 v142, s[24:25]
	s_add_i32 m0, s0, 0x1e000
	s_nop 0
	global_load_lds_dwordx4 v146, s[24:25]
	s_waitcnt lgkmcnt(0)
	v_mfma_f32_16x16x32_bf16 v[60:63], v[150:153], v[196:199], v[60:63]
	v_mfma_f32_16x16x32_bf16 v[56:59], v[168:171], v[196:199], v[56:59]
	v_mfma_f32_16x16x32_bf16 v[44:47], v[150:153], v[204:207], v[44:47]
	v_mfma_f32_16x16x32_bf16 v[40:43], v[168:171], v[204:207], v[40:43]
	v_mfma_f32_16x16x32_bf16 v[28:31], v[150:153], v[212:215], v[28:31]
	v_mfma_f32_16x16x32_bf16 v[24:27], v[168:171], v[212:215], v[24:27]
	v_mfma_f32_16x16x32_bf16 v[12:15], v[150:153], v[220:223], v[12:15]
	v_mfma_f32_16x16x32_bf16 v[8:11], v[168:171], v[220:223], v[8:11]
	v_mfma_f32_16x16x32_bf16 v[60:63], v[154:157], v[200:203], v[60:63]
	v_mfma_f32_16x16x32_bf16 v[56:59], v[176:179], v[200:203], v[56:59]
	v_mfma_f32_16x16x32_bf16 v[44:47], v[154:157], v[208:211], v[44:47]
	v_mfma_f32_16x16x32_bf16 v[40:43], v[176:179], v[208:211], v[40:43]
	v_mfma_f32_16x16x32_bf16 v[28:31], v[154:157], v[216:219], v[28:31]
	v_mfma_f32_16x16x32_bf16 v[24:27], v[176:179], v[216:219], v[24:27]
	v_mfma_f32_16x16x32_bf16 v[12:15], v[154:157], v[224:227], v[12:15]
	v_mfma_f32_16x16x32_bf16 v[8:11], v[176:179], v[224:227], v[8:11]
	s_waitcnt vmcnt(8)
	s_barrier
	ds_read_b128 v[150:153], v163
	ds_read_b128 v[154:157], v163 offset:1024
	ds_read_b128 v[168:171], v163 offset:2048
	ds_read_b128 v[176:179], v163 offset:3072
	ds_read_b128 v[196:199], v162 offset:49152
	ds_read_b128 v[200:203], v162 offset:50176
	ds_read_b128 v[204:207], v162 offset:51200
	ds_read_b128 v[208:211], v162 offset:52224
	ds_read_b128 v[212:215], v162 offset:53248
	ds_read_b128 v[216:219], v162 offset:54272
	ds_read_b128 v[220:223], v162 offset:55296
	ds_read_b128 v[224:227], v162 offset:56320
	s_add_u32 s22, s22, 0x80
	s_addc_u32 s23, s23, 0
	s_add_u32 s24, s24, 0x80
	s_addc_u32 s25, s25, 0
	s_add_i32 m0, s0, 0x4000
	s_nop 0
	global_load_lds_dwordx4 v140, s[22:23]
	s_add_i32 m0, s0, 0x6000
	s_nop 0
	global_load_lds_dwordx4 v144, s[22:23]
	s_add_i32 m0, s0, 0x10000
	s_nop 0
	global_load_lds_dwordx4 v142, s[24:25]
	s_add_i32 m0, s0, 0x12000
	s_nop 0
	global_load_lds_dwordx4 v146, s[24:25]
	s_waitcnt lgkmcnt(0)
	v_mfma_f32_16x16x32_bf16 v[60:63], v[150:153], v[196:199], v[60:63]
	v_mfma_f32_16x16x32_bf16 v[56:59], v[168:171], v[196:199], v[56:59]
	v_mfma_f32_16x16x32_bf16 v[44:47], v[150:153], v[204:207], v[44:47]
	v_mfma_f32_16x16x32_bf16 v[40:43], v[168:171], v[204:207], v[40:43]
	v_mfma_f32_16x16x32_bf16 v[28:31], v[150:153], v[212:215], v[28:31]
	v_mfma_f32_16x16x32_bf16 v[24:27], v[168:171], v[212:215], v[24:27]
	v_mfma_f32_16x16x32_bf16 v[12:15], v[150:153], v[220:223], v[12:15]
	v_mfma_f32_16x16x32_bf16 v[8:11], v[168:171], v[220:223], v[8:11]
	v_mfma_f32_16x16x32_bf16 v[60:63], v[154:157], v[200:203], v[60:63]
	v_mfma_f32_16x16x32_bf16 v[56:59], v[176:179], v[200:203], v[56:59]
	v_mfma_f32_16x16x32_bf16 v[44:47], v[154:157], v[208:211], v[44:47]
	v_mfma_f32_16x16x32_bf16 v[40:43], v[176:179], v[208:211], v[40:43]
	v_mfma_f32_16x16x32_bf16 v[28:31], v[154:157], v[216:219], v[28:31]
	v_mfma_f32_16x16x32_bf16 v[24:27], v[176:179], v[216:219], v[24:27]
	v_mfma_f32_16x16x32_bf16 v[12:15], v[154:157], v[224:227], v[12:15]
	v_mfma_f32_16x16x32_bf16 v[8:11], v[176:179], v[224:227], v[8:11]
	s_waitcnt vmcnt(8)
	s_barrier
	ds_read_b128 v[150:153], v161
	ds_read_b128 v[154:157], v161 offset:1024
	ds_read_b128 v[168:171], v161 offset:2048
	ds_read_b128 v[176:179], v161 offset:3072
	ds_read_b128 v[196:199], v162
	ds_read_b128 v[200:203], v162 offset:1024
	ds_read_b128 v[204:207], v162 offset:2048
	ds_read_b128 v[208:211], v162 offset:3072
	ds_read_b128 v[212:215], v162 offset:4096
	ds_read_b128 v[216:219], v162 offset:5120
	ds_read_b128 v[220:223], v162 offset:6144
	ds_read_b128 v[224:227], v162 offset:7168
	s_add_u32 s22, s22, 0x80
	s_addc_u32 s23, s23, 0
	s_add_u32 s24, s24, 0x80
	s_addc_u32 s25, s25, 0
	s_add_i32 m0, s0, 0xc000
	s_nop 0
	global_load_lds_dwordx4 v140, s[22:23]
	s_add_i32 m0, s0, 0xe000
	s_nop 0
	global_load_lds_dwordx4 v144, s[22:23]
	s_add_i32 m0, s0, 0x18000
	s_nop 0
	global_load_lds_dwordx4 v142, s[24:25]
	s_add_i32 m0, s0, 0x1a000
	s_nop 0
	global_load_lds_dwordx4 v146, s[24:25]
	s_waitcnt lgkmcnt(0)
	v_mfma_f32_16x16x32_bf16 v[60:63], v[150:153], v[196:199], v[60:63]
	v_mfma_f32_16x16x32_bf16 v[56:59], v[168:171], v[196:199], v[56:59]
	v_mfma_f32_16x16x32_bf16 v[44:47], v[150:153], v[204:207], v[44:47]
	v_mfma_f32_16x16x32_bf16 v[40:43], v[168:171], v[204:207], v[40:43]
	v_mfma_f32_16x16x32_bf16 v[28:31], v[150:153], v[212:215], v[28:31]
	v_mfma_f32_16x16x32_bf16 v[24:27], v[168:171], v[212:215], v[24:27]
	v_mfma_f32_16x16x32_bf16 v[12:15], v[150:153], v[220:223], v[12:15]
	v_mfma_f32_16x16x32_bf16 v[8:11], v[168:171], v[220:223], v[8:11]
	v_mfma_f32_16x16x32_bf16 v[60:63], v[154:157], v[200:203], v[60:63]
	v_mfma_f32_16x16x32_bf16 v[56:59], v[176:179], v[200:203], v[56:59]
	v_mfma_f32_16x16x32_bf16 v[44:47], v[154:157], v[208:211], v[44:47]
	v_mfma_f32_16x16x32_bf16 v[40:43], v[176:179], v[208:211], v[40:43]
	v_mfma_f32_16x16x32_bf16 v[28:31], v[154:157], v[216:219], v[28:31]
	v_mfma_f32_16x16x32_bf16 v[24:27], v[176:179], v[216:219], v[24:27]
	v_mfma_f32_16x16x32_bf16 v[12:15], v[154:157], v[224:227], v[12:15]
	v_mfma_f32_16x16x32_bf16 v[8:11], v[176:179], v[224:227], v[8:11]
	s_waitcnt vmcnt(8)
	s_barrier
; #define PG8_STAGE(bufoff, gbase, voff) do { _Pragma("unroll") for (int _i = 0; _i < 2; ++_i) \
;         __builtin_amdgcn_global_load_lds((const unsigned*)((const char*)(gbase) + (voff)[_i]), (PG8_LAS unsigned*)(lds + (bufoff) + ldsw + _i * 8192), 16, 0, 0); } while (0)
; #define PG8_LDA(dst, b, h) do { _Pragma("unroll") for (int m = 0; m < 4; ++m) _Pragma("unroll") for (int k = 0; k < 2; ++k) dst[m][k] = *(const PG8_LAS bf16x8*)(lds + PG8_SA(b, h) + aoff + m * 2048 + k * 1024); } while (0)
; #define PG8_LDB(dst, b, h) do { _Pragma("unroll") for (int n = 0; n < 2; ++n) _Pragma("unroll") for (int k = 0; k < 2; ++k) dst[n][k] = *(const PG8_LAS bf16x8*)(lds + PG8_SB(b, h) + boff + n * 2048 + k * 1024); } while (0)
; #define PG8_MMA(ai, bj, At, Bt) do { __builtin_amdgcn_s_setprio(1); _Pragma("unroll") for (int m = 0; m < 4; ++m) _Pragma("unroll") for (int n = 0; n < 2; ++n) _Pragma("unroll") for (int k = 0; k < 2; ++k) \
;         acc[ai][bj][m][n] = __builtin_amdgcn_mfma_f32_16x16x32_bf16(Bt[n][k], At[m][k], acc[ai][bj][m][n], 0, 0, 0); __builtin_amdgcn_s_setprio(0); } while (0)
; #define PG8_WAIT_V(n) asm volatile("s_waitcnt vmcnt(" #n ")" ::: "memory")
; template <class Epi, class Sched, bool ALIGN_EPI = false, bool SP2 = false>
; __device__ __forceinline__ void gemm_phase(PG8_LAS unsigned char* lds, const Gemm g, const Sched& S, const Epi& E) {
;     ...
;             PG8_LDB(B0, 0, 0); PG8_LDB(B1, 0, 1); PG8_SCHED; PG8_LDA(At, 0, 0); PG8_STAGE(PG8_SA(1, 1), a1 + hstep, voffA);
;             PG8_WAIT_V(8); PG8_WAIT_L(0); PG8_BAR; PG8_MMA(0, 0, At, B0); PG8_MMA(0, 1, At, B1); PG8_BAR; PG8_SCHED;
;             PG8_LDA(At, 0, 1); PG8_STAGE(PG8_SB(0, 0), b2, voffB); PG8_STAGE(PG8_SB(0, 1), b2 + hstep, voffB); PG8_STAGE(PG8_SA(0, 0), a2, voffA);
;             PG8_WAIT_V(8); PG8_WAIT_L(0); PG8_BAR; PG8_MMA(1, 0, At, B0); PG8_MMA(1, 1, At, B1); PG8_BAR; PG8_SCHED;
;             PG8_LDB(B0, 1, 0); PG8_LDB(B1, 1, 1); PG8_SCHED; PG8_LDA(At, 1, 0); PG8_STAGE(PG8_SA(0, 1), a2 + hstep, voffA);
;             PG8_WAIT_V(8); PG8_WAIT_L(0); PG8_BAR; PG8_MMA(0, 0, At, B0); PG8_MMA(0, 1, At, B1); PG8_BAR; PG8_SCHED;
;             PG8_LDA(At, 1, 1); PG8_STAGE(PG8_SB(1, 0), b3, voffB); PG8_STAGE(PG8_SB(1, 1), b3 + hstep, voffB); PG8_STAGE(PG8_SA(1, 0), a3, voffA);
;             PG8_WAIT_V(8); PG8_WAIT_L(0); PG8_BAR; PG8_MMA(1, 0, At, B0); PG8_MMA(1, 1, At, B1); PG8_BAR; PG8_SCHED;
	ds_read_b128 v[150:153], v164
	ds_read_b128 v[154:157], v164 offset:1024
	ds_read_b128 v[168:171], v164 offset:2048
	ds_read_b128 v[176:179], v164 offset:3072
	ds_read_b128 v[196:199], v162 offset:32768
	ds_read_b128 v[200:203], v162 offset:33792
	ds_read_b128 v[204:207], v162 offset:34816
	ds_read_b128 v[208:211], v162 offset:35840
	ds_read_b128 v[212:215], v162 offset:36864
	ds_read_b128 v[216:219], v162 offset:37888
	ds_read_b128 v[220:223], v162 offset:38912
	ds_read_b128 v[224:227], v162 offset:39936
	s_add_u32 s22, s22, 0x80
	s_addc_u32 s23, s23, 0
	s_add_u32 s24, s24, 0x80
	s_addc_u32 s25, s25, 0
	s_mov_b32 m0, s0
	s_nop 0
	global_load_lds_dwordx4 v140, s[22:23]
	s_add_i32 m0, s0, 0x2000
	s_nop 0
	global_load_lds_dwordx4 v144, s[22:23]
	s_add_i32 m0, s0, 0x14000
	s_nop 0
	global_load_lds_dwordx4 v142, s[24:25]
	s_add_i32 m0, s0, 0x16000
	s_nop 0
	global_load_lds_dwordx4 v146, s[24:25]
	s_waitcnt lgkmcnt(0)
	v_mfma_f32_16x16x32_bf16 v[60:63], v[150:153], v[196:199], v[60:63]
	v_mfma_f32_16x16x32_bf16 v[56:59], v[168:171], v[196:199], v[56:59]
	v_mfma_f32_16x16x32_bf16 v[44:47], v[150:153], v[204:207], v[44:47]
	v_mfma_f32_16x16x32_bf16 v[40:43], v[168:171], v[204:207], v[40:43]
	v_mfma_f32_16x16x32_bf16 v[28:31], v[150:153], v[212:215], v[28:31]
	v_mfma_f32_16x16x32_bf16 v[24:27], v[168:171], v[212:215], v[24:27]
	v_mfma_f32_16x16x32_bf16 v[12:15], v[150:153], v[220:223], v[12:15]
	v_mfma_f32_16x16x32_bf16 v[8:11], v[168:171], v[220:223], v[8:11]
	v_mfma_f32_16x16x32_bf16 v[60:63], v[154:157], v[200:203], v[60:63]
	v_mfma_f32_16x16x32_bf16 v[56:59], v[176:179], v[200:203], v[56:59]
	v_mfma_f32_16x16x32_bf16 v[44:47], v[154:157], v[208:211], v[44:47]
	v_mfma_f32_16x16x32_bf16 v[40:43], v[176:179], v[208:211], v[40:43]
	v_mfma_f32_16x16x32_bf16 v[28:31], v[154:157], v[216:219], v[28:31]
	v_mfma_f32_16x16x32_bf16 v[24:27], v[176:179], v[216:219], v[24:27]
	v_mfma_f32_16x16x32_bf16 v[12:15], v[154:157], v[224:227], v[12:15]
	v_mfma_f32_16x16x32_bf16 v[8:11], v[176:179], v[224:227], v[8:11]
	s_waitcnt vmcnt(8)
	s_barrier
	ds_read_b128 v[150:153], v160
	ds_read_b128 v[154:157], v160 offset:1024
	ds_read_b128 v[168:171], v160 offset:2048
	ds_read_b128 v[176:179], v160 offset:3072
	ds_read_b128 v[196:199], v162 offset:16384
	ds_read_b128 v[200:203], v162 offset:17408
	ds_read_b128 v[204:207], v162 offset:18432
	ds_read_b128 v[208:211], v162 offset:19456
	ds_read_b128 v[212:215], v162 offset:20480
	ds_read_b128 v[216:219], v162 offset:21504
	ds_read_b128 v[220:223], v162 offset:22528
	ds_read_b128 v[224:227], v162 offset:23552
	s_add_u32 s22, s22, 0x80
	s_addc_u32 s23, s23, 0
	s_add_u32 s24, s24, 0x80
	s_addc_u32 s25, s25, 0
	s_add_i32 m0, s0, 0x8000
	s_nop 0
	global_load_lds_dwordx4 v140, s[22:23]
	s_add_i32 m0, s0, 0xa000
	s_nop 0
	global_load_lds_dwordx4 v144, s[22:23]
	s_add_i32 m0, s0, 0x1c000
	s_nop 0
	global_load_lds_dwordx4 v142, s[24:25]
	s_add_i32 m0, s0, 0x1e000
	s_nop 0
	global_load_lds_dwordx4 v146, s[24:25]
	s_waitcnt lgkmcnt(0)
	v_mfma_f32_16x16x32_bf16 v[60:63], v[150:153], v[196:199], v[60:63]
	v_mfma_f32_16x16x32_bf16 v[56:59], v[168:171], v[196:199], v[56:59]
	v_mfma_f32_16x16x32_bf16 v[44:47], v[150:153], v[204:207], v[44:47]
	v_mfma_f32_16x16x32_bf16 v[40:43], v[168:171], v[204:207], v[40:43]
	v_mfma_f32_16x16x32_bf16 v[28:31], v[150:153], v[212:215], v[28:31]
	v_mfma_f32_16x16x32_bf16 v[24:27], v[168:171], v[212:215], v[24:27]
	v_mfma_f32_16x16x32_bf16 v[12:15], v[150:153], v[220:223], v[12:15]
	v_mfma_f32_16x16x32_bf16 v[8:11], v[168:171], v[220:223], v[8:11]
	v_mfma_f32_16x16x32_bf16 v[60:63], v[154:157], v[200:203], v[60:63]
	v_mfma_f32_16x16x32_bf16 v[56:59], v[176:179], v[200:203], v[56:59]
	v_mfma_f32_16x16x32_bf16 v[44:47], v[154:157], v[208:211], v[44:47]
	v_mfma_f32_16x16x32_bf16 v[40:43], v[176:179], v[208:211], v[40:43]
	v_mfma_f32_16x16x32_bf16 v[28:31], v[154:157], v[216:219], v[28:31]
	v_mfma_f32_16x16x32_bf16 v[24:27], v[176:179], v[216:219], v[24:27]
	v_mfma_f32_16x16x32_bf16 v[12:15], v[154:157], v[224:227], v[12:15]
	v_mfma_f32_16x16x32_bf16 v[8:11], v[176:179], v[224:227], v[8:11]
	s_waitcnt vmcnt(8)
	s_barrier
	ds_read_b128 v[150:153], v163
	ds_read_b128 v[154:157], v163 offset:1024
	ds_read_b128 v[168:171], v163 offset:2048
	ds_read_b128 v[176:179], v163 offset:3072
	ds_read_b128 v[196:199], v162 offset:49152
	ds_read_b128 v[200:203], v162 offset:50176
	ds_read_b128 v[204:207], v162 offset:51200
	ds_read_b128 v[208:211], v162 offset:52224
	ds_read_b128 v[212:215], v162 offset:53248
	ds_read_b128 v[216:219], v162 offset:54272
	ds_read_b128 v[220:223], v162 offset:55296
	ds_read_b128 v[224:227], v162 offset:56320
	s_waitcnt lgkmcnt(0)
	v_mfma_f32_16x16x32_bf16 v[60:63], v[150:153], v[196:199], v[60:63]
	v_mfma_f32_16x16x32_bf16 v[56:59], v[168:171], v[196:199], v[56:59]
	v_mfma_f32_16x16x32_bf16 v[44:47], v[150:153], v[204:207], v[44:47]
	v_mfma_f32_16x16x32_bf16 v[40:43], v[168:171], v[204:207], v[40:43]
	v_mfma_f32_16x16x32_bf16 v[28:31], v[150:153], v[212:215], v[28:31]
	v_mfma_f32_16x16x32_bf16 v[24:27], v[168:171], v[212:215], v[24:27]
	v_mfma_f32_16x16x32_bf16 v[12:15], v[150:153], v[220:223], v[12:15]
	v_mfma_f32_16x16x32_bf16 v[8:11], v[168:171], v[220:223], v[8:11]
	v_mfma_f32_16x16x32_bf16 v[60:63], v[154:157], v[200:203], v[60:63]
	v_mfma_f32_16x16x32_bf16 v[56:59], v[176:179], v[200:203], v[56:59]
	v_mfma_f32_16x16x32_bf16 v[44:47], v[154:157], v[208:211], v[44:47]
	v_mfma_f32_16x16x32_bf16 v[40:43], v[176:179], v[208:211], v[40:43]
	v_mfma_f32_16x16x32_bf16 v[28:31], v[154:157], v[216:219], v[28:31]
	v_mfma_f32_16x16x32_bf16 v[24:27], v[176:179], v[216:219], v[24:27]
	v_mfma_f32_16x16x32_bf16 v[12:15], v[154:157], v[224:227], v[12:15]
	v_mfma_f32_16x16x32_bf16 v[8:11], v[176:179], v[224:227], v[8:11]
	s_waitcnt vmcnt(4)
	s_barrier
; #define PG8_STAGE(bufoff, gbase, voff) do { _Pragma("unroll") for (int _i = 0; _i < 2; ++_i) \
;         __builtin_amdgcn_global_load_lds((const unsigned*)((const char*)(gbase) + (voff)[_i]), (PG8_LAS unsigned*)(lds + (bufoff) + ldsw + _i * 8192), 16, 0, 0); } while (0)
; #define PG8_LDA(dst, b, h) do { _Pragma("unroll") for (int m = 0; m < 4; ++m) _Pragma("unroll") for (int k = 0; k < 2; ++k) dst[m][k] = *(const PG8_LAS bf16x8*)(lds + PG8_SA(b, h) + aoff + m * 2048 + k * 1024); } while (0)
; #define PG8_LDB(dst, b, h) do { _Pragma("unroll") for (int n = 0; n < 2; ++n) _Pragma("unroll") for (int k = 0; k < 2; ++k) dst[n][k] = *(const PG8_LAS bf16x8*)(lds + PG8_SB(b, h) + boff + n * 2048 + k * 1024); } while (0)
; #define PG8_MMA(ai, bj, At, Bt) do { __builtin_amdgcn_s_setprio(1); _Pragma("unroll") for (int m = 0; m < 4; ++m) _Pragma("unroll") for (int n = 0; n < 2; ++n) _Pragma("unroll") for (int k = 0; k < 2; ++k) \
;         acc[ai][bj][m][n] = __builtin_amdgcn_mfma_f32_16x16x32_bf16(Bt[n][k], At[m][k], acc[ai][bj][m][n], 0, 0, 0); __builtin_amdgcn_s_setprio(0); } while (0)
; #define PG8_WAIT_V(n) asm volatile("s_waitcnt vmcnt(" #n ")" ::: "memory")
; template <class Epi, class Sched, bool ALIGN_EPI = false, bool SP2 = false>
; __device__ __forceinline__ void gemm_phase(PG8_LAS unsigned char* lds, const Gemm g, const Sched& S, const Epi& E) {
;     ...
;             PG8_LDB(B0, 0, 0); PG8_LDB(B1, 0, 1); PG8_SCHED; PG8_LDA(At, 0, 0); PG8_STAGE(PG8_SA(1, 1), a1 + hstep, voffA);
;             PG8_WAIT_V(8); PG8_WAIT_L(0); PG8_BAR; PG8_MMA(0, 0, At, B0); PG8_MMA(0, 1, At, B1); PG8_BAR; PG8_SCHED;
;             PG8_LDA(At, 0, 1); PG8_STAGE(PG8_SB(0, 0), b2, voffB); PG8_STAGE(PG8_SB(0, 1), b2 + hstep, voffB); PG8_STAGE(PG8_SA(0, 0), a2, voffA);
;             PG8_WAIT_V(8); PG8_WAIT_L(0); PG8_BAR; PG8_MMA(1, 0, At, B0); PG8_MMA(1, 1, At, B1); PG8_BAR; PG8_SCHED;
;             PG8_LDB(B0, 1, 0); PG8_LDB(B1, 1, 1); PG8_SCHED; PG8_LDA(At, 1, 0); PG8_STAGE(PG8_SA(0, 1), a2 + hstep, voffA);
;             PG8_WAIT_V(8); PG8_WAIT_L(0); PG8_BAR; PG8_MMA(0, 0, At, B0); PG8_MMA(0, 1, At, B1); PG8_BAR; PG8_SCHED;
;             PG8_LDA(At, 1, 1); PG8_STAGE(PG8_SB(1, 0), b3, voffB); PG8_STAGE(PG8_SB(1, 1), b3 + hstep, voffB); PG8_STAGE(PG8_SA(1, 0), a3, voffA);
;             PG8_WAIT_V(8); PG8_WAIT_L(0); PG8_BAR; PG8_MMA(1, 0, At, B0); PG8_MMA(1, 1, At, B1); PG8_BAR; PG8_SCHED;
	ds_read_b128 v[150:153], v161
	ds_read_b128 v[154:157], v161 offset:1024
	ds_read_b128 v[168:171], v161 offset:2048
	ds_read_b128 v[176:179], v161 offset:3072
	ds_read_b128 v[196:199], v162
	ds_read_b128 v[200:203], v162 offset:1024
	ds_read_b128 v[204:207], v162 offset:2048
	ds_read_b128 v[208:211], v162 offset:3072
	ds_read_b128 v[212:215], v162 offset:4096
	ds_read_b128 v[216:219], v162 offset:5120
	ds_read_b128 v[220:223], v162 offset:6144
	ds_read_b128 v[224:227], v162 offset:7168
	s_waitcnt lgkmcnt(0)
	v_mfma_f32_16x16x32_bf16 v[60:63], v[150:153], v[196:199], v[60:63]
	v_mfma_f32_16x16x32_bf16 v[56:59], v[168:171], v[196:199], v[56:59]
	v_mfma_f32_16x16x32_bf16 v[44:47], v[150:153], v[204:207], v[44:47]
	v_mfma_f32_16x16x32_bf16 v[40:43], v[168:171], v[204:207], v[40:43]
	v_mfma_f32_16x16x32_bf16 v[28:31], v[150:153], v[212:215], v[28:31]
	v_mfma_f32_16x16x32_bf16 v[24:27], v[168:171], v[212:215], v[24:27]
	v_mfma_f32_16x16x32_bf16 v[12:15], v[150:153], v[220:223], v[12:15]
	v_mfma_f32_16x16x32_bf16 v[8:11], v[168:171], v[220:223], v[8:11]
	v_mfma_f32_16x16x32_bf16 v[60:63], v[154:157], v[200:203], v[60:63]
	v_mfma_f32_16x16x32_bf16 v[56:59], v[176:179], v[200:203], v[56:59]
	v_mfma_f32_16x16x32_bf16 v[44:47], v[154:157], v[208:211], v[44:47]
	v_mfma_f32_16x16x32_bf16 v[40:43], v[176:179], v[208:211], v[40:43]
	v_mfma_f32_16x16x32_bf16 v[28:31], v[154:157], v[216:219], v[28:31]
	v_mfma_f32_16x16x32_bf16 v[24:27], v[176:179], v[216:219], v[24:27]
	v_mfma_f32_16x16x32_bf16 v[12:15], v[154:157], v[224:227], v[12:15]
	v_mfma_f32_16x16x32_bf16 v[8:11], v[176:179], v[224:227], v[8:11]
	s_waitcnt vmcnt(0)
	s_barrier
	ds_read_b128 v[150:153], v164
	ds_read_b128 v[154:157], v164 offset:1024
	ds_read_b128 v[168:171], v164 offset:2048
	ds_read_b128 v[176:179], v164 offset:3072
	ds_read_b128 v[196:199], v162 offset:32768
	ds_read_b128 v[200:203], v162 offset:33792
	ds_read_b128 v[204:207], v162 offset:34816
	ds_read_b128 v[208:211], v162 offset:35840
	ds_read_b128 v[212:215], v162 offset:36864
	ds_read_b128 v[216:219], v162 offset:37888
	ds_read_b128 v[220:223], v162 offset:38912
	ds_read_b128 v[224:227], v162 offset:39936
	s_waitcnt lgkmcnt(0)
	v_mfma_f32_16x16x32_bf16 v[60:63], v[150:153], v[196:199], v[60:63]
	v_mfma_f32_16x16x32_bf16 v[56:59], v[168:171], v[196:199], v[56:59]
	v_mfma_f32_16x16x32_bf16 v[44:47], v[150:153], v[204:207], v[44:47]
	v_mfma_f32_16x16x32_bf16 v[40:43], v[168:171], v[204:207], v[40:43]
	v_mfma_f32_16x16x32_bf16 v[28:31], v[150:153], v[212:215], v[28:31]
	v_mfma_f32_16x16x32_bf16 v[24:27], v[168:171], v[212:215], v[24:27]
	v_mfma_f32_16x16x32_bf16 v[12:15], v[150:153], v[220:223], v[12:15]
	v_mfma_f32_16x16x32_bf16 v[8:11], v[168:171], v[220:223], v[8:11]
	v_mfma_f32_16x16x32_bf16 v[60:63], v[154:157], v[200:203], v[60:63]
	v_mfma_f32_16x16x32_bf16 v[56:59], v[176:179], v[200:203], v[56:59]
	v_mfma_f32_16x16x32_bf16 v[44:47], v[154:157], v[208:211], v[44:47]
	v_mfma_f32_16x16x32_bf16 v[40:43], v[176:179], v[208:211], v[40:43]
	v_mfma_f32_16x16x32_bf16 v[28:31], v[154:157], v[216:219], v[28:31]
	v_mfma_f32_16x16x32_bf16 v[24:27], v[176:179], v[216:219], v[24:27]
	v_mfma_f32_16x16x32_bf16 v[12:15], v[154:157], v[224:227], v[12:15]
	v_mfma_f32_16x16x32_bf16 v[8:11], v[176:179], v[224:227], v[8:11]
	s_branch .LBB0_620
.Lp3q_lean_q3:
	s_mov_b32 s22, s94
	s_mov_b32 s23, 0
	s_lshl_b64 s[22:23], s[22:23], 19
	s_add_u32 s22, s22, s70
	s_addc_u32 s23, s23, s71
	s_add_u32 s22, s22, 0x80
	s_addc_u32 s23, s23, 0
	s_add_u32 s22, s22, 0x40000
	s_addc_u32 s23, s23, 0
	s_mov_b32 s24, s42
	s_mov_b32 s25, 0
	s_lshl_b64 s[24:25], s[24:25], 19
	s_add_u32 s24, s24, s64
	s_addc_u32 s25, s25, s65
	s_add_u32 s24, s24, 0x80
	s_addc_u32 s25, s25, 0
	s_add_u32 s24, s24, 0x40000
	s_addc_u32 s25, s25, 0
	s_waitcnt vmcnt(0) lgkmcnt(0)
	s_barrier
	s_add_i32 m0, s0, 0xc000
	s_nop 0
	global_load_lds_dwordx4 v140, s[22:23]
	s_add_i32 m0, s0, 0xe000
	s_nop 0
	global_load_lds_dwordx4 v144, s[22:23]
	s_add_u32 s22, s22, 0x80
	s_addc_u32 s23, s23, 0
	s_add_u32 s24, s24, 0x80
	s_addc_u32 s25, s25, 0
	s_mov_b32 m0, s0
	s_nop 0
	global_load_lds_dwordx4 v140, s[22:23]
	s_add_i32 m0, s0, 0x2000
	s_nop 0
	global_load_lds_dwordx4 v144, s[22:23]
	s_add_i32 m0, s0, 0x10000
	s_nop 0
	global_load_lds_dwordx4 v142, s[24:25]
	s_add_i32 m0, s0, 0x12000
	s_nop 0
	global_load_lds_dwordx4 v146, s[24:25]
	s_add_u32 s22, s22, 0x80
	s_addc_u32 s23, s23, 0
	s_add_u32 s24, s24, 0x80
	s_addc_u32 s25, s25, 0
	s_add_i32 m0, s0, 0x8000
	s_nop 0
	global_load_lds_dwordx4 v140, s[22:23]
	s_add_i32 m0, s0, 0xa000
	s_nop 0
	global_load_lds_dwordx4 v144, s[22:23]
	s_add_i32 m0, s0, 0x18000
	s_nop 0
	global_load_lds_dwordx4 v142, s[24:25]
	s_add_i32 m0, s0, 0x1a000
	s_nop 0
	global_load_lds_dwordx4 v146, s[24:25]
	ds_read_b128 v[180:183], v161
	ds_read_b128 v[184:187], v161 offset:1024
	ds_read_b128 v[188:191], v161 offset:2048
	ds_read_b128 v[192:195], v161 offset:3072
	ds_read_b128 v[196:199], v162 offset:16384
	ds_read_b128 v[200:203], v162 offset:17408
	ds_read_b128 v[204:207], v162 offset:18432
	ds_read_b128 v[208:211], v162 offset:19456
	ds_read_b128 v[212:215], v162 offset:20480
	ds_read_b128 v[216:219], v162 offset:21504
	ds_read_b128 v[220:223], v162 offset:22528
	ds_read_b128 v[224:227], v162 offset:23552
	s_waitcnt lgkmcnt(0)
	v_mfma_f32_16x16x32_bf16 v[52:55], v[180:183], v[196:199], v[52:55]
	v_mfma_f32_16x16x32_bf16 v[48:51], v[188:191], v[196:199], v[48:51]
	v_mfma_f32_16x16x32_bf16 v[36:39], v[180:183], v[204:207], v[36:39]
	v_mfma_f32_16x16x32_bf16 v[32:35], v[188:191], v[204:207], v[32:35]
	v_mfma_f32_16x16x32_bf16 v[20:23], v[180:183], v[212:215], v[20:23]
	v_mfma_f32_16x16x32_bf16 v[16:19], v[188:191], v[212:215], v[16:19]
	v_mfma_f32_16x16x32_bf16 v[4:7], v[180:183], v[220:223], v[4:7]
	v_mfma_f32_16x16x32_bf16 v[0:3], v[188:191], v[220:223], v[0:3]
	v_mfma_f32_16x16x32_bf16 v[52:55], v[184:187], v[200:203], v[52:55]
	v_mfma_f32_16x16x32_bf16 v[48:51], v[192:195], v[200:203], v[48:51]
	v_mfma_f32_16x16x32_bf16 v[36:39], v[184:187], v[208:211], v[36:39]
	v_mfma_f32_16x16x32_bf16 v[32:35], v[192:195], v[208:211], v[32:35]
	v_mfma_f32_16x16x32_bf16 v[20:23], v[184:187], v[216:219], v[20:23]
	v_mfma_f32_16x16x32_bf16 v[16:19], v[192:195], v[216:219], v[16:19]
	v_mfma_f32_16x16x32_bf16 v[4:7], v[184:187], v[224:227], v[4:7]
	v_mfma_f32_16x16x32_bf16 v[0:3], v[192:195], v[224:227], v[0:3]
	s_waitcnt vmcnt(8)
	s_barrier
; #define PG8_STAGE(bufoff, gbase, voff) do { _Pragma("unroll") for (int _i = 0; _i < 2; ++_i) \
;         __builtin_amdgcn_global_load_lds((const unsigned*)((const char*)(gbase) + (voff)[_i]), (PG8_LAS unsigned*)(lds + (bufoff) + ldsw + _i * 8192), 16, 0, 0); } while (0)
; #define PG8_LDA(dst, b, h) do { _Pragma("unroll") for (int m = 0; m < 4; ++m) _Pragma("unroll") for (int k = 0; k < 2; ++k) dst[m][k] = *(const PG8_LAS bf16x8*)(lds + PG8_SA(b, h) + aoff + m * 2048 + k * 1024); } while (0)
; #define PG8_LDB(dst, b, h) do { _Pragma("unroll") for (int n = 0; n < 2; ++n) _Pragma("unroll") for (int k = 0; k < 2; ++k) dst[n][k] = *(const PG8_LAS bf16x8*)(lds + PG8_SB(b, h) + boff + n * 2048 + k * 1024); } while (0)
; #define PG8_MMA(ai, bj, At, Bt) do { __builtin_amdgcn_s_setprio(1); _Pragma("unroll") for (int m = 0; m < 4; ++m) _Pragma("unroll") for (int n = 0; n < 2; ++n) _Pragma("unroll") for (int k = 0; k < 2; ++k) \
;         acc[ai][bj][m][n] = __builtin_amdgcn_mfma_f32_16x16x32_bf16(Bt[n][k], At[m][k], acc[ai][bj][m][n], 0, 0, 0); __builtin_amdgcn_s_setprio(0); } while (0)
; #define PG8_WAIT_V(n) asm volatile("s_waitcnt vmcnt(" #n ")" ::: "memory")
; template <class Epi, class Sched, bool ALIGN_EPI = false, bool SP2 = false>
; __device__ __forceinline__ void gemm_phase(PG8_LAS unsigned char* lds, const Gemm g, const Sched& S, const Epi& E) {
;     ...
;             PG8_LDB(B0, 0, 0); PG8_LDB(B1, 0, 1); PG8_SCHED; PG8_LDA(At, 0, 0); PG8_STAGE(PG8_SA(1, 1), a1 + hstep, voffA);
;             PG8_WAIT_V(8); PG8_WAIT_L(0); PG8_BAR; PG8_MMA(0, 0, At, B0); PG8_MMA(0, 1, At, B1); PG8_BAR; PG8_SCHED;
;             PG8_LDA(At, 0, 1); PG8_STAGE(PG8_SB(0, 0), b2, voffB); PG8_STAGE(PG8_SB(0, 1), b2 + hstep, voffB); PG8_STAGE(PG8_SA(0, 0), a2, voffA);
;             PG8_WAIT_V(8); PG8_WAIT_L(0); PG8_BAR; PG8_MMA(1, 0, At, B0); PG8_MMA(1, 1, At, B1); PG8_BAR; PG8_SCHED;
;             PG8_LDB(B0, 1, 0); PG8_LDB(B1, 1, 1); PG8_SCHED; PG8_LDA(At, 1, 0); PG8_STAGE(PG8_SA(0, 1), a2 + hstep, voffA);
;             PG8_WAIT_V(8); PG8_WAIT_L(0); PG8_BAR; PG8_MMA(0, 0, At, B0); PG8_MMA(0, 1, At, B1); PG8_BAR; PG8_SCHED;
;             PG8_LDA(At, 1, 1); PG8_STAGE(PG8_SB(1, 0), b3, voffB); PG8_STAGE(PG8_SB(1, 1), b3 + hstep, voffB); PG8_STAGE(PG8_SA(1, 0), a3, voffA);
;             PG8_WAIT_V(8); PG8_WAIT_L(0); PG8_BAR; PG8_MMA(1, 0, At, B0); PG8_MMA(1, 1, At, B1); PG8_BAR; PG8_SCHED;
	ds_read_b128 v[180:183], v164
	ds_read_b128 v[184:187], v164 offset:1024
	ds_read_b128 v[188:191], v164 offset:2048
	ds_read_b128 v[192:195], v164 offset:3072
	ds_read_b128 v[196:199], v162 offset:49152
	ds_read_b128 v[200:203], v162 offset:50176
	ds_read_b128 v[204:207], v162 offset:51200
	ds_read_b128 v[208:211], v162 offset:52224
	ds_read_b128 v[212:215], v162 offset:53248
	ds_read_b128 v[216:219], v162 offset:54272
	ds_read_b128 v[220:223], v162 offset:55296
	ds_read_b128 v[224:227], v162 offset:56320
	s_add_u32 s22, s22, 0x80
	s_addc_u32 s23, s23, 0
	s_add_u32 s24, s24, 0x80
	s_addc_u32 s25, s25, 0
	s_add_i32 m0, s0, 0x4000
	s_nop 0
	global_load_lds_dwordx4 v140, s[22:23]
	s_add_i32 m0, s0, 0x6000
	s_nop 0
	global_load_lds_dwordx4 v144, s[22:23]
	s_add_i32 m0, s0, 0x14000
	s_nop 0
	global_load_lds_dwordx4 v142, s[24:25]
	s_add_i32 m0, s0, 0x16000
	s_nop 0
	global_load_lds_dwordx4 v146, s[24:25]
	s_waitcnt lgkmcnt(0)
	v_mfma_f32_16x16x32_bf16 v[52:55], v[180:183], v[196:199], v[52:55]
	v_mfma_f32_16x16x32_bf16 v[48:51], v[188:191], v[196:199], v[48:51]
	v_mfma_f32_16x16x32_bf16 v[36:39], v[180:183], v[204:207], v[36:39]
	v_mfma_f32_16x16x32_bf16 v[32:35], v[188:191], v[204:207], v[32:35]
	v_mfma_f32_16x16x32_bf16 v[20:23], v[180:183], v[212:215], v[20:23]
	v_mfma_f32_16x16x32_bf16 v[16:19], v[188:191], v[212:215], v[16:19]
	v_mfma_f32_16x16x32_bf16 v[4:7], v[180:183], v[220:223], v[4:7]
	v_mfma_f32_16x16x32_bf16 v[0:3], v[188:191], v[220:223], v[0:3]
	v_mfma_f32_16x16x32_bf16 v[52:55], v[184:187], v[200:203], v[52:55]
	v_mfma_f32_16x16x32_bf16 v[48:51], v[192:195], v[200:203], v[48:51]
	v_mfma_f32_16x16x32_bf16 v[36:39], v[184:187], v[208:211], v[36:39]
	v_mfma_f32_16x16x32_bf16 v[32:35], v[192:195], v[208:211], v[32:35]
	v_mfma_f32_16x16x32_bf16 v[20:23], v[184:187], v[216:219], v[20:23]
	v_mfma_f32_16x16x32_bf16 v[16:19], v[192:195], v[216:219], v[16:19]
	v_mfma_f32_16x16x32_bf16 v[4:7], v[184:187], v[224:227], v[4:7]
	v_mfma_f32_16x16x32_bf16 v[0:3], v[192:195], v[224:227], v[0:3]
	s_waitcnt vmcnt(8)
	s_barrier
	ds_read_b128 v[180:183], v160
	ds_read_b128 v[184:187], v160 offset:1024
	ds_read_b128 v[188:191], v160 offset:2048
	ds_read_b128 v[192:195], v160 offset:3072
	ds_read_b128 v[196:199], v162
	ds_read_b128 v[200:203], v162 offset:1024
	ds_read_b128 v[204:207], v162 offset:2048
	ds_read_b128 v[208:211], v162 offset:3072
	ds_read_b128 v[212:215], v162 offset:4096
	ds_read_b128 v[216:219], v162 offset:5120
	ds_read_b128 v[220:223], v162 offset:6144
	ds_read_b128 v[224:227], v162 offset:7168
	s_add_u32 s22, s22, 0x80
	s_addc_u32 s23, s23, 0
	s_add_u32 s24, s24, 0x80
	s_addc_u32 s25, s25, 0
	s_add_i32 m0, s0, 0xc000
	s_nop 0
	global_load_lds_dwordx4 v140, s[22:23]
	s_add_i32 m0, s0, 0xe000
	s_nop 0
	global_load_lds_dwordx4 v144, s[22:23]
	s_add_i32 m0, s0, 0x1c000
	s_nop 0
	global_load_lds_dwordx4 v142, s[24:25]
	s_add_i32 m0, s0, 0x1e000
	s_nop 0
	global_load_lds_dwordx4 v146, s[24:25]
	s_waitcnt lgkmcnt(0)
	v_mfma_f32_16x16x32_bf16 v[52:55], v[180:183], v[196:199], v[52:55]
	v_mfma_f32_16x16x32_bf16 v[48:51], v[188:191], v[196:199], v[48:51]
	v_mfma_f32_16x16x32_bf16 v[36:39], v[180:183], v[204:207], v[36:39]
	v_mfma_f32_16x16x32_bf16 v[32:35], v[188:191], v[204:207], v[32:35]
	v_mfma_f32_16x16x32_bf16 v[20:23], v[180:183], v[212:215], v[20:23]
	v_mfma_f32_16x16x32_bf16 v[16:19], v[188:191], v[212:215], v[16:19]
	v_mfma_f32_16x16x32_bf16 v[4:7], v[180:183], v[220:223], v[4:7]
	v_mfma_f32_16x16x32_bf16 v[0:3], v[188:191], v[220:223], v[0:3]
	v_mfma_f32_16x16x32_bf16 v[52:55], v[184:187], v[200:203], v[52:55]
	v_mfma_f32_16x16x32_bf16 v[48:51], v[192:195], v[200:203], v[48:51]
	v_mfma_f32_16x16x32_bf16 v[36:39], v[184:187], v[208:211], v[36:39]
	v_mfma_f32_16x16x32_bf16 v[32:35], v[192:195], v[208:211], v[32:35]
	v_mfma_f32_16x16x32_bf16 v[20:23], v[184:187], v[216:219], v[20:23]
	v_mfma_f32_16x16x32_bf16 v[16:19], v[192:195], v[216:219], v[16:19]
	v_mfma_f32_16x16x32_bf16 v[4:7], v[184:187], v[224:227], v[4:7]
	v_mfma_f32_16x16x32_bf16 v[0:3], v[192:195], v[224:227], v[0:3]
	s_waitcnt vmcnt(8)
	s_barrier
	ds_read_b128 v[180:183], v163
	ds_read_b128 v[184:187], v163 offset:1024
	ds_read_b128 v[188:191], v163 offset:2048
	ds_read_b128 v[192:195], v163 offset:3072
	ds_read_b128 v[196:199], v162 offset:32768
	ds_read_b128 v[200:203], v162 offset:33792
	ds_read_b128 v[204:207], v162 offset:34816
	ds_read_b128 v[208:211], v162 offset:35840
	ds_read_b128 v[212:215], v162 offset:36864
	ds_read_b128 v[216:219], v162 offset:37888
	ds_read_b128 v[220:223], v162 offset:38912
	ds_read_b128 v[224:227], v162 offset:39936
	s_add_u32 s22, s22, 0x80
	s_addc_u32 s23, s23, 0
	s_add_u32 s24, s24, 0x80
	s_addc_u32 s25, s25, 0
	s_mov_b32 m0, s0
	s_nop 0
	global_load_lds_dwordx4 v140, s[22:23]
	s_add_i32 m0, s0, 0x2000
	s_nop 0
	global_load_lds_dwordx4 v144, s[22:23]
	s_add_i32 m0, s0, 0x10000
	s_nop 0
	global_load_lds_dwordx4 v142, s[24:25]
	s_add_i32 m0, s0, 0x12000
	s_nop 0
	global_load_lds_dwordx4 v146, s[24:25]
	s_waitcnt lgkmcnt(0)
	v_mfma_f32_16x16x32_bf16 v[52:55], v[180:183], v[196:199], v[52:55]
	v_mfma_f32_16x16x32_bf16 v[48:51], v[188:191], v[196:199], v[48:51]
	v_mfma_f32_16x16x32_bf16 v[36:39], v[180:183], v[204:207], v[36:39]
	v_mfma_f32_16x16x32_bf16 v[32:35], v[188:191], v[204:207], v[32:35]
	v_mfma_f32_16x16x32_bf16 v[20:23], v[180:183], v[212:215], v[20:23]
	v_mfma_f32_16x16x32_bf16 v[16:19], v[188:191], v[212:215], v[16:19]
	v_mfma_f32_16x16x32_bf16 v[4:7], v[180:183], v[220:223], v[4:7]
	v_mfma_f32_16x16x32_bf16 v[0:3], v[188:191], v[220:223], v[0:3]
	v_mfma_f32_16x16x32_bf16 v[52:55], v[184:187], v[200:203], v[52:55]
	v_mfma_f32_16x16x32_bf16 v[48:51], v[192:195], v[200:203], v[48:51]
	v_mfma_f32_16x16x32_bf16 v[36:39], v[184:187], v[208:211], v[36:39]
	v_mfma_f32_16x16x32_bf16 v[32:35], v[192:195], v[208:211], v[32:35]
	v_mfma_f32_16x16x32_bf16 v[20:23], v[184:187], v[216:219], v[20:23]
	v_mfma_f32_16x16x32_bf16 v[16:19], v[192:195], v[216:219], v[16:19]
	v_mfma_f32_16x16x32_bf16 v[4:7], v[184:187], v[224:227], v[4:7]
	v_mfma_f32_16x16x32_bf16 v[0:3], v[192:195], v[224:227], v[0:3]
	s_waitcnt vmcnt(8)
	s_barrier
; #define PG8_STAGE(bufoff, gbase, voff) do { _Pragma("unroll") for (int _i = 0; _i < 2; ++_i) \
;         __builtin_amdgcn_global_load_lds((const unsigned*)((const char*)(gbase) + (voff)[_i]), (PG8_LAS unsigned*)(lds + (bufoff) + ldsw + _i * 8192), 16, 0, 0); } while (0)
; #define PG8_LDA(dst, b, h) do { _Pragma("unroll") for (int m = 0; m < 4; ++m) _Pragma("unroll") for (int k = 0; k < 2; ++k) dst[m][k] = *(const PG8_LAS bf16x8*)(lds + PG8_SA(b, h) + aoff + m * 2048 + k * 1024); } while (0)
; #define PG8_LDB(dst, b, h) do { _Pragma("unroll") for (int n = 0; n < 2; ++n) _Pragma("unroll") for (int k = 0; k < 2; ++k) dst[n][k] = *(const PG8_LAS bf16x8*)(lds + PG8_SB(b, h) + boff + n * 2048 + k * 1024); } while (0)
; #define PG8_MMA(ai, bj, At, Bt) do { __builtin_amdgcn_s_setprio(1); _Pragma("unroll") for (int m = 0; m < 4; ++m) _Pragma("unroll") for (int n = 0; n < 2; ++n) _Pragma("unroll") for (int k = 0; k < 2; ++k) \
;         acc[ai][bj][m][n] = __builtin_amdgcn_mfma_f32_16x16x32_bf16(Bt[n][k], At[m][k], acc[ai][bj][m][n], 0, 0, 0); __builtin_amdgcn_s_setprio(0); } while (0)
; #define PG8_WAIT_V(n) asm volatile("s_waitcnt vmcnt(" #n ")" ::: "memory")
; template <class Epi, class Sched, bool ALIGN_EPI = false, bool SP2 = false>
; __device__ __forceinline__ void gemm_phase(PG8_LAS unsigned char* lds, const Gemm g, const Sched& S, const Epi& E) {
;     ...
;             PG8_LDB(B0, 0, 0); PG8_LDB(B1, 0, 1); PG8_SCHED; PG8_LDA(At, 0, 0); PG8_STAGE(PG8_SA(1, 1), a1 + hstep, voffA);
;             PG8_WAIT_V(8); PG8_WAIT_L(0); PG8_BAR; PG8_MMA(0, 0, At, B0); PG8_MMA(0, 1, At, B1); PG8_BAR; PG8_SCHED;
;             PG8_LDA(At, 0, 1); PG8_STAGE(PG8_SB(0, 0), b2, voffB); PG8_STAGE(PG8_SB(0, 1), b2 + hstep, voffB); PG8_STAGE(PG8_SA(0, 0), a2, voffA);
;             PG8_WAIT_V(8); PG8_WAIT_L(0); PG8_BAR; PG8_MMA(1, 0, At, B0); PG8_MMA(1, 1, At, B1); PG8_BAR; PG8_SCHED;
;             PG8_LDB(B0, 1, 0); PG8_LDB(B1, 1, 1); PG8_SCHED; PG8_LDA(At, 1, 0); PG8_STAGE(PG8_SA(0, 1), a2 + hstep, voffA);
;             PG8_WAIT_V(8); PG8_WAIT_L(0); PG8_BAR; PG8_MMA(0, 0, At, B0); PG8_MMA(0, 1, At, B1); PG8_BAR; PG8_SCHED;
;             PG8_LDA(At, 1, 1); PG8_STAGE(PG8_SB(1, 0), b3, voffB); PG8_STAGE(PG8_SB(1, 1), b3 + hstep, voffB); PG8_STAGE(PG8_SA(1, 0), a3, voffA);
;             PG8_WAIT_V(8); PG8_WAIT_L(0); PG8_BAR; PG8_MMA(1, 0, At, B0); PG8_MMA(1, 1, At, B1); PG8_BAR; PG8_SCHED;
	ds_read_b128 v[180:183], v161
	ds_read_b128 v[184:187], v161 offset:1024
	ds_read_b128 v[188:191], v161 offset:2048
	ds_read_b128 v[192:195], v161 offset:3072
	ds_read_b128 v[196:199], v162 offset:16384
	ds_read_b128 v[200:203], v162 offset:17408
	ds_read_b128 v[204:207], v162 offset:18432
	ds_read_b128 v[208:211], v162 offset:19456
	ds_read_b128 v[212:215], v162 offset:20480
	ds_read_b128 v[216:219], v162 offset:21504
	ds_read_b128 v[220:223], v162 offset:22528
	ds_read_b128 v[224:227], v162 offset:23552
	s_add_u32 s22, s22, 0x80
	s_addc_u32 s23, s23, 0
	s_add_u32 s24, s24, 0x80
	s_addc_u32 s25, s25, 0
	s_add_i32 m0, s0, 0x8000
	s_nop 0
	global_load_lds_dwordx4 v140, s[22:23]
	s_add_i32 m0, s0, 0xa000
	s_nop 0
	global_load_lds_dwordx4 v144, s[22:23]
	s_add_i32 m0, s0, 0x18000
	s_nop 0
	global_load_lds_dwordx4 v142, s[24:25]
	s_add_i32 m0, s0, 0x1a000
	s_nop 0
	global_load_lds_dwordx4 v146, s[24:25]
	s_waitcnt lgkmcnt(0)
	v_mfma_f32_16x16x32_bf16 v[52:55], v[180:183], v[196:199], v[52:55]
	v_mfma_f32_16x16x32_bf16 v[48:51], v[188:191], v[196:199], v[48:51]
	v_mfma_f32_16x16x32_bf16 v[36:39], v[180:183], v[204:207], v[36:39]
	v_mfma_f32_16x16x32_bf16 v[32:35], v[188:191], v[204:207], v[32:35]
	v_mfma_f32_16x16x32_bf16 v[20:23], v[180:183], v[212:215], v[20:23]
	v_mfma_f32_16x16x32_bf16 v[16:19], v[188:191], v[212:215], v[16:19]
	v_mfma_f32_16x16x32_bf16 v[4:7], v[180:183], v[220:223], v[4:7]
	v_mfma_f32_16x16x32_bf16 v[0:3], v[188:191], v[220:223], v[0:3]
	v_mfma_f32_16x16x32_bf16 v[52:55], v[184:187], v[200:203], v[52:55]
	v_mfma_f32_16x16x32_bf16 v[48:51], v[192:195], v[200:203], v[48:51]
	v_mfma_f32_16x16x32_bf16 v[36:39], v[184:187], v[208:211], v[36:39]
	v_mfma_f32_16x16x32_bf16 v[32:35], v[192:195], v[208:211], v[32:35]
	v_mfma_f32_16x16x32_bf16 v[20:23], v[184:187], v[216:219], v[20:23]
	v_mfma_f32_16x16x32_bf16 v[16:19], v[192:195], v[216:219], v[16:19]
	v_mfma_f32_16x16x32_bf16 v[4:7], v[184:187], v[224:227], v[4:7]
	v_mfma_f32_16x16x32_bf16 v[0:3], v[192:195], v[224:227], v[0:3]
	s_waitcnt vmcnt(8)
	s_barrier
	ds_read_b128 v[180:183], v164
	ds_read_b128 v[184:187], v164 offset:1024
	ds_read_b128 v[188:191], v164 offset:2048
	ds_read_b128 v[192:195], v164 offset:3072
	ds_read_b128 v[196:199], v162 offset:49152
	ds_read_b128 v[200:203], v162 offset:50176
	ds_read_b128 v[204:207], v162 offset:51200
	ds_read_b128 v[208:211], v162 offset:52224
	ds_read_b128 v[212:215], v162 offset:53248
	ds_read_b128 v[216:219], v162 offset:54272
	ds_read_b128 v[220:223], v162 offset:55296
	ds_read_b128 v[224:227], v162 offset:56320
	s_add_u32 s22, s22, 0x80
	s_addc_u32 s23, s23, 0
	s_add_u32 s24, s24, 0x80
	s_addc_u32 s25, s25, 0
	s_add_i32 m0, s0, 0x4000
	s_nop 0
	global_load_lds_dwordx4 v140, s[22:23]
	s_add_i32 m0, s0, 0x6000
	s_nop 0
	global_load_lds_dwordx4 v144, s[22:23]
	s_add_i32 m0, s0, 0x14000
	s_nop 0
	global_load_lds_dwordx4 v142, s[24:25]
	s_add_i32 m0, s0, 0x16000
	s_nop 0
	global_load_lds_dwordx4 v146, s[24:25]
	s_waitcnt lgkmcnt(0)
	v_mfma_f32_16x16x32_bf16 v[52:55], v[180:183], v[196:199], v[52:55]
	v_mfma_f32_16x16x32_bf16 v[48:51], v[188:191], v[196:199], v[48:51]
	v_mfma_f32_16x16x32_bf16 v[36:39], v[180:183], v[204:207], v[36:39]
	v_mfma_f32_16x16x32_bf16 v[32:35], v[188:191], v[204:207], v[32:35]
	v_mfma_f32_16x16x32_bf16 v[20:23], v[180:183], v[212:215], v[20:23]
	v_mfma_f32_16x16x32_bf16 v[16:19], v[188:191], v[212:215], v[16:19]
	v_mfma_f32_16x16x32_bf16 v[4:7], v[180:183], v[220:223], v[4:7]
	v_mfma_f32_16x16x32_bf16 v[0:3], v[188:191], v[220:223], v[0:3]
	v_mfma_f32_16x16x32_bf16 v[52:55], v[184:187], v[200:203], v[52:55]
	v_mfma_f32_16x16x32_bf16 v[48:51], v[192:195], v[200:203], v[48:51]
	v_mfma_f32_16x16x32_bf16 v[36:39], v[184:187], v[208:211], v[36:39]
	v_mfma_f32_16x16x32_bf16 v[32:35], v[192:195], v[208:211], v[32:35]
	v_mfma_f32_16x16x32_bf16 v[20:23], v[184:187], v[216:219], v[20:23]
	v_mfma_f32_16x16x32_bf16 v[16:19], v[192:195], v[216:219], v[16:19]
	v_mfma_f32_16x16x32_bf16 v[4:7], v[184:187], v[224:227], v[4:7]
	v_mfma_f32_16x16x32_bf16 v[0:3], v[192:195], v[224:227], v[0:3]
	s_waitcnt vmcnt(8)
	s_barrier
	ds_read_b128 v[180:183], v160
	ds_read_b128 v[184:187], v160 offset:1024
	ds_read_b128 v[188:191], v160 offset:2048
	ds_read_b128 v[192:195], v160 offset:3072
	ds_read_b128 v[196:199], v162
	ds_read_b128 v[200:203], v162 offset:1024
	ds_read_b128 v[204:207], v162 offset:2048
	ds_read_b128 v[208:211], v162 offset:3072
	ds_read_b128 v[212:215], v162 offset:4096
	ds_read_b128 v[216:219], v162 offset:5120
	ds_read_b128 v[220:223], v162 offset:6144
	ds_read_b128 v[224:227], v162 offset:7168
	s_add_u32 s22, s22, 0x80
	s_addc_u32 s23, s23, 0
	s_add_u32 s24, s24, 0x80
	s_addc_u32 s25, s25, 0
	s_add_i32 m0, s0, 0xc000
	s_nop 0
	global_load_lds_dwordx4 v140, s[22:23]
	s_add_i32 m0, s0, 0xe000
	s_nop 0
	global_load_lds_dwordx4 v144, s[22:23]
	s_add_i32 m0, s0, 0x1c000
	s_nop 0
	global_load_lds_dwordx4 v142, s[24:25]
	s_add_i32 m0, s0, 0x1e000
	s_nop 0
	global_load_lds_dwordx4 v146, s[24:25]
	s_waitcnt lgkmcnt(0)
	v_mfma_f32_16x16x32_bf16 v[52:55], v[180:183], v[196:199], v[52:55]
	v_mfma_f32_16x16x32_bf16 v[48:51], v[188:191], v[196:199], v[48:51]
	v_mfma_f32_16x16x32_bf16 v[36:39], v[180:183], v[204:207], v[36:39]
	v_mfma_f32_16x16x32_bf16 v[32:35], v[188:191], v[204:207], v[32:35]
	v_mfma_f32_16x16x32_bf16 v[20:23], v[180:183], v[212:215], v[20:23]
	v_mfma_f32_16x16x32_bf16 v[16:19], v[188:191], v[212:215], v[16:19]
	v_mfma_f32_16x16x32_bf16 v[4:7], v[180:183], v[220:223], v[4:7]
	v_mfma_f32_16x16x32_bf16 v[0:3], v[188:191], v[220:223], v[0:3]
	v_mfma_f32_16x16x32_bf16 v[52:55], v[184:187], v[200:203], v[52:55]
	v_mfma_f32_16x16x32_bf16 v[48:51], v[192:195], v[200:203], v[48:51]
	v_mfma_f32_16x16x32_bf16 v[36:39], v[184:187], v[208:211], v[36:39]
	v_mfma_f32_16x16x32_bf16 v[32:35], v[192:195], v[208:211], v[32:35]
	v_mfma_f32_16x16x32_bf16 v[20:23], v[184:187], v[216:219], v[20:23]
	v_mfma_f32_16x16x32_bf16 v[16:19], v[192:195], v[216:219], v[16:19]
	v_mfma_f32_16x16x32_bf16 v[4:7], v[184:187], v[224:227], v[4:7]
	v_mfma_f32_16x16x32_bf16 v[0:3], v[192:195], v[224:227], v[0:3]
	s_waitcnt vmcnt(8)
	s_barrier
; #define PG8_STAGE(bufoff, gbase, voff) do { _Pragma("unroll") for (int _i = 0; _i < 2; ++_i) \
;         __builtin_amdgcn_global_load_lds((const unsigned*)((const char*)(gbase) + (voff)[_i]), (PG8_LAS unsigned*)(lds + (bufoff) + ldsw + _i * 8192), 16, 0, 0); } while (0)
; #define PG8_LDA(dst, b, h) do { _Pragma("unroll") for (int m = 0; m < 4; ++m) _Pragma("unroll") for (int k = 0; k < 2; ++k) dst[m][k] = *(const PG8_LAS bf16x8*)(lds + PG8_SA(b, h) + aoff + m * 2048 + k * 1024); } while (0)
; #define PG8_LDB(dst, b, h) do { _Pragma("unroll") for (int n = 0; n < 2; ++n) _Pragma("unroll") for (int k = 0; k < 2; ++k) dst[n][k] = *(const PG8_LAS bf16x8*)(lds + PG8_SB(b, h) + boff + n * 2048 + k * 1024); } while (0)
; #define PG8_MMA(ai, bj, At, Bt) do { __builtin_amdgcn_s_setprio(1); _Pragma("unroll") for (int m = 0; m < 4; ++m) _Pragma("unroll") for (int n = 0; n < 2; ++n) _Pragma("unroll") for (int k = 0; k < 2; ++k) \
;         acc[ai][bj][m][n] = __builtin_amdgcn_mfma_f32_16x16x32_bf16(Bt[n][k], At[m][k], acc[ai][bj][m][n], 0, 0, 0); __builtin_amdgcn_s_setprio(0); } while (0)
; #define PG8_WAIT_V(n) asm volatile("s_waitcnt vmcnt(" #n ")" ::: "memory")
; template <class Epi, class Sched, bool ALIGN_EPI = false, bool SP2 = false>
; __device__ __forceinline__ void gemm_phase(PG8_LAS unsigned char* lds, const Gemm g, const Sched& S, const Epi& E) {
;     ...
;             PG8_LDB(B0, 0, 0); PG8_LDB(B1, 0, 1); PG8_SCHED; PG8_LDA(At, 0, 0); PG8_STAGE(PG8_SA(1, 1), a1 + hstep, voffA);
;             PG8_WAIT_V(8); PG8_WAIT_L(0); PG8_BAR; PG8_MMA(0, 0, At, B0); PG8_MMA(0, 1, At, B1); PG8_BAR; PG8_SCHED;
;             PG8_LDA(At, 0, 1); PG8_STAGE(PG8_SB(0, 0), b2, voffB); PG8_STAGE(PG8_SB(0, 1), b2 + hstep, voffB); PG8_STAGE(PG8_SA(0, 0), a2, voffA);
;             PG8_WAIT_V(8); PG8_WAIT_L(0); PG8_BAR; PG8_MMA(1, 0, At, B0); PG8_MMA(1, 1, At, B1); PG8_BAR; PG8_SCHED;
;             PG8_LDB(B0, 1, 0); PG8_LDB(B1, 1, 1); PG8_SCHED; PG8_LDA(At, 1, 0); PG8_STAGE(PG8_SA(0, 1), a2 + hstep, voffA);
;             PG8_WAIT_V(8); PG8_WAIT_L(0); PG8_BAR; PG8_MMA(0, 0, At, B0); PG8_MMA(0, 1, At, B1); PG8_BAR; PG8_SCHED;
;             PG8_LDA(At, 1, 1); PG8_STAGE(PG8_SB(1, 0), b3, voffB); PG8_STAGE(PG8_SB(1, 1), b3 + hstep, voffB); PG8_STAGE(PG8_SA(1, 0), a3, voffA);
;             PG8_WAIT_V(8); PG8_WAIT_L(0); PG8_BAR; PG8_MMA(1, 0, At, B0); PG8_MMA(1, 1, At, B1); PG8_BAR; PG8_SCHED;
	ds_read_b128 v[180:183], v163
	ds_read_b128 v[184:187], v163 offset:1024
	ds_read_b128 v[188:191], v163 offset:2048
	ds_read_b128 v[192:195], v163 offset:3072
	ds_read_b128 v[196:199], v162 offset:32768
	ds_read_b128 v[200:203], v162 offset:33792
	ds_read_b128 v[204:207], v162 offset:34816
	ds_read_b128 v[208:211], v162 offset:35840
	ds_read_b128 v[212:215], v162 offset:36864
	ds_read_b128 v[216:219], v162 offset:37888
	ds_read_b128 v[220:223], v162 offset:38912
	ds_read_b128 v[224:227], v162 offset:39936
	s_add_u32 s22, s22, 0x80
	s_addc_u32 s23, s23, 0
	s_add_u32 s24, s24, 0x80
	s_addc_u32 s25, s25, 0
	s_mov_b32 m0, s0
	s_nop 0
	global_load_lds_dwordx4 v140, s[22:23]
	s_add_i32 m0, s0, 0x2000
	s_nop 0
	global_load_lds_dwordx4 v144, s[22:23]
	s_add_i32 m0, s0, 0x10000
	s_nop 0
	global_load_lds_dwordx4 v142, s[24:25]
	s_add_i32 m0, s0, 0x12000
	s_nop 0
	global_load_lds_dwordx4 v146, s[24:25]
	s_waitcnt lgkmcnt(0)
	v_mfma_f32_16x16x32_bf16 v[52:55], v[180:183], v[196:199], v[52:55]
	v_mfma_f32_16x16x32_bf16 v[48:51], v[188:191], v[196:199], v[48:51]
	v_mfma_f32_16x16x32_bf16 v[36:39], v[180:183], v[204:207], v[36:39]
	v_mfma_f32_16x16x32_bf16 v[32:35], v[188:191], v[204:207], v[32:35]
	v_mfma_f32_16x16x32_bf16 v[20:23], v[180:183], v[212:215], v[20:23]
	v_mfma_f32_16x16x32_bf16 v[16:19], v[188:191], v[212:215], v[16:19]
	v_mfma_f32_16x16x32_bf16 v[4:7], v[180:183], v[220:223], v[4:7]
	v_mfma_f32_16x16x32_bf16 v[0:3], v[188:191], v[220:223], v[0:3]
	v_mfma_f32_16x16x32_bf16 v[52:55], v[184:187], v[200:203], v[52:55]
	v_mfma_f32_16x16x32_bf16 v[48:51], v[192:195], v[200:203], v[48:51]
	v_mfma_f32_16x16x32_bf16 v[36:39], v[184:187], v[208:211], v[36:39]
	v_mfma_f32_16x16x32_bf16 v[32:35], v[192:195], v[208:211], v[32:35]
	v_mfma_f32_16x16x32_bf16 v[20:23], v[184:187], v[216:219], v[20:23]
	v_mfma_f32_16x16x32_bf16 v[16:19], v[192:195], v[216:219], v[16:19]
	v_mfma_f32_16x16x32_bf16 v[4:7], v[184:187], v[224:227], v[4:7]
	v_mfma_f32_16x16x32_bf16 v[0:3], v[192:195], v[224:227], v[0:3]
	s_waitcnt vmcnt(8)
	s_barrier
	ds_read_b128 v[180:183], v161
	ds_read_b128 v[184:187], v161 offset:1024
	ds_read_b128 v[188:191], v161 offset:2048
	ds_read_b128 v[192:195], v161 offset:3072
	ds_read_b128 v[196:199], v162 offset:16384
	ds_read_b128 v[200:203], v162 offset:17408
	ds_read_b128 v[204:207], v162 offset:18432
	ds_read_b128 v[208:211], v162 offset:19456
	ds_read_b128 v[212:215], v162 offset:20480
	ds_read_b128 v[216:219], v162 offset:21504
	ds_read_b128 v[220:223], v162 offset:22528
	ds_read_b128 v[224:227], v162 offset:23552
	s_add_u32 s22, s22, 0x80
	s_addc_u32 s23, s23, 0
	s_add_u32 s24, s24, 0x80
	s_addc_u32 s25, s25, 0
	s_add_i32 m0, s0, 0x8000
	s_nop 0
	global_load_lds_dwordx4 v140, s[22:23]
	s_add_i32 m0, s0, 0xa000
	s_nop 0
	global_load_lds_dwordx4 v144, s[22:23]
	s_add_i32 m0, s0, 0x18000
	s_nop 0
	global_load_lds_dwordx4 v142, s[24:25]
	s_add_i32 m0, s0, 0x1a000
	s_nop 0
	global_load_lds_dwordx4 v146, s[24:25]
	s_waitcnt lgkmcnt(0)
	v_mfma_f32_16x16x32_bf16 v[52:55], v[180:183], v[196:199], v[52:55]
	v_mfma_f32_16x16x32_bf16 v[48:51], v[188:191], v[196:199], v[48:51]
	v_mfma_f32_16x16x32_bf16 v[36:39], v[180:183], v[204:207], v[36:39]
	v_mfma_f32_16x16x32_bf16 v[32:35], v[188:191], v[204:207], v[32:35]
	v_mfma_f32_16x16x32_bf16 v[20:23], v[180:183], v[212:215], v[20:23]
	v_mfma_f32_16x16x32_bf16 v[16:19], v[188:191], v[212:215], v[16:19]
	v_mfma_f32_16x16x32_bf16 v[4:7], v[180:183], v[220:223], v[4:7]
	v_mfma_f32_16x16x32_bf16 v[0:3], v[188:191], v[220:223], v[0:3]
	v_mfma_f32_16x16x32_bf16 v[52:55], v[184:187], v[200:203], v[52:55]
	v_mfma_f32_16x16x32_bf16 v[48:51], v[192:195], v[200:203], v[48:51]
	v_mfma_f32_16x16x32_bf16 v[36:39], v[184:187], v[208:211], v[36:39]
	v_mfma_f32_16x16x32_bf16 v[32:35], v[192:195], v[208:211], v[32:35]
	v_mfma_f32_16x16x32_bf16 v[20:23], v[184:187], v[216:219], v[20:23]
	v_mfma_f32_16x16x32_bf16 v[16:19], v[192:195], v[216:219], v[16:19]
	v_mfma_f32_16x16x32_bf16 v[4:7], v[184:187], v[224:227], v[4:7]
	v_mfma_f32_16x16x32_bf16 v[0:3], v[192:195], v[224:227], v[0:3]
	s_waitcnt vmcnt(8)
	s_barrier
	ds_read_b128 v[180:183], v164
	ds_read_b128 v[184:187], v164 offset:1024
	ds_read_b128 v[188:191], v164 offset:2048
	ds_read_b128 v[192:195], v164 offset:3072
	ds_read_b128 v[196:199], v162 offset:49152
	ds_read_b128 v[200:203], v162 offset:50176
	ds_read_b128 v[204:207], v162 offset:51200
	ds_read_b128 v[208:211], v162 offset:52224
	ds_read_b128 v[212:215], v162 offset:53248
	ds_read_b128 v[216:219], v162 offset:54272
	ds_read_b128 v[220:223], v162 offset:55296
	ds_read_b128 v[224:227], v162 offset:56320
	s_add_u32 s22, s22, 0x80
	s_addc_u32 s23, s23, 0
	s_add_u32 s24, s24, 0x80
	s_addc_u32 s25, s25, 0
	s_add_i32 m0, s0, 0x4000
	s_nop 0
	global_load_lds_dwordx4 v140, s[22:23]
	s_add_i32 m0, s0, 0x6000
	s_nop 0
	global_load_lds_dwordx4 v144, s[22:23]
	s_add_i32 m0, s0, 0x14000
	s_nop 0
	global_load_lds_dwordx4 v142, s[24:25]
	s_add_i32 m0, s0, 0x16000
	s_nop 0
	global_load_lds_dwordx4 v146, s[24:25]
	s_waitcnt lgkmcnt(0)
	v_mfma_f32_16x16x32_bf16 v[52:55], v[180:183], v[196:199], v[52:55]
	v_mfma_f32_16x16x32_bf16 v[48:51], v[188:191], v[196:199], v[48:51]
	v_mfma_f32_16x16x32_bf16 v[36:39], v[180:183], v[204:207], v[36:39]
	v_mfma_f32_16x16x32_bf16 v[32:35], v[188:191], v[204:207], v[32:35]
	v_mfma_f32_16x16x32_bf16 v[20:23], v[180:183], v[212:215], v[20:23]
	v_mfma_f32_16x16x32_bf16 v[16:19], v[188:191], v[212:215], v[16:19]
	v_mfma_f32_16x16x32_bf16 v[4:7], v[180:183], v[220:223], v[4:7]
	v_mfma_f32_16x16x32_bf16 v[0:3], v[188:191], v[220:223], v[0:3]
	v_mfma_f32_16x16x32_bf16 v[52:55], v[184:187], v[200:203], v[52:55]
	v_mfma_f32_16x16x32_bf16 v[48:51], v[192:195], v[200:203], v[48:51]
	v_mfma_f32_16x16x32_bf16 v[36:39], v[184:187], v[208:211], v[36:39]
	v_mfma_f32_16x16x32_bf16 v[32:35], v[192:195], v[208:211], v[32:35]
	v_mfma_f32_16x16x32_bf16 v[20:23], v[184:187], v[216:219], v[20:23]
	v_mfma_f32_16x16x32_bf16 v[16:19], v[192:195], v[216:219], v[16:19]
	v_mfma_f32_16x16x32_bf16 v[4:7], v[184:187], v[224:227], v[4:7]
	v_mfma_f32_16x16x32_bf16 v[0:3], v[192:195], v[224:227], v[0:3]
	s_waitcnt vmcnt(8)
	s_barrier
; #define PG8_STAGE(bufoff, gbase, voff) do { _Pragma("unroll") for (int _i = 0; _i < 2; ++_i) \
;         __builtin_amdgcn_global_load_lds((const unsigned*)((const char*)(gbase) + (voff)[_i]), (PG8_LAS unsigned*)(lds + (bufoff) + ldsw + _i * 8192), 16, 0, 0); } while (0)
; #define PG8_LDA(dst, b, h) do { _Pragma("unroll") for (int m = 0; m < 4; ++m) _Pragma("unroll") for (int k = 0; k < 2; ++k) dst[m][k] = *(const PG8_LAS bf16x8*)(lds + PG8_SA(b, h) + aoff + m * 2048 + k * 1024); } while (0)
; #define PG8_LDB(dst, b, h) do { _Pragma("unroll") for (int n = 0; n < 2; ++n) _Pragma("unroll") for (int k = 0; k < 2; ++k) dst[n][k] = *(const PG8_LAS bf16x8*)(lds + PG8_SB(b, h) + boff + n * 2048 + k * 1024); } while (0)
; #define PG8_MMA(ai, bj, At, Bt) do { __builtin_amdgcn_s_setprio(1); _Pragma("unroll") for (int m = 0; m < 4; ++m) _Pragma("unroll") for (int n = 0; n < 2; ++n) _Pragma("unroll") for (int k = 0; k < 2; ++k) \
;         acc[ai][bj][m][n] = __builtin_amdgcn_mfma_f32_16x16x32_bf16(Bt[n][k], At[m][k], acc[ai][bj][m][n], 0, 0, 0); __builtin_amdgcn_s_setprio(0); } while (0)
; #define PG8_WAIT_V(n) asm volatile("s_waitcnt vmcnt(" #n ")" ::: "memory")
; template <class Epi, class Sched, bool ALIGN_EPI = false, bool SP2 = false>
; __device__ __forceinline__ void gemm_phase(PG8_LAS unsigned char* lds, const Gemm g, const Sched& S, const Epi& E) {
;     ...
;             PG8_LDB(B0, 0, 0); PG8_LDB(B1, 0, 1); PG8_SCHED; PG8_LDA(At, 0, 0); PG8_STAGE(PG8_SA(1, 1), a1 + hstep, voffA);
;             PG8_WAIT_V(8); PG8_WAIT_L(0); PG8_BAR; PG8_MMA(0, 0, At, B0); PG8_MMA(0, 1, At, B1); PG8_BAR; PG8_SCHED;
;             PG8_LDA(At, 0, 1); PG8_STAGE(PG8_SB(0, 0), b2, voffB); PG8_STAGE(PG8_SB(0, 1), b2 + hstep, voffB); PG8_STAGE(PG8_SA(0, 0), a2, voffA);
;             PG8_WAIT_V(8); PG8_WAIT_L(0); PG8_BAR; PG8_MMA(1, 0, At, B0); PG8_MMA(1, 1, At, B1); PG8_BAR; PG8_SCHED;
;             PG8_LDB(B0, 1, 0); PG8_LDB(B1, 1, 1); PG8_SCHED; PG8_LDA(At, 1, 0); PG8_STAGE(PG8_SA(0, 1), a2 + hstep, voffA);
;             PG8_WAIT_V(8); PG8_WAIT_L(0); PG8_BAR; PG8_MMA(0, 0, At, B0); PG8_MMA(0, 1, At, B1); PG8_BAR; PG8_SCHED;
;             PG8_LDA(At, 1, 1); PG8_STAGE(PG8_SB(1, 0), b3, voffB); PG8_STAGE(PG8_SB(1, 1), b3 + hstep, voffB); PG8_STAGE(PG8_SA(1, 0), a3, voffA);
;             PG8_WAIT_V(8); PG8_WAIT_L(0); PG8_BAR; PG8_MMA(1, 0, At, B0); PG8_MMA(1, 1, At, B1); PG8_BAR; PG8_SCHED;
	ds_read_b128 v[180:183], v160
	ds_read_b128 v[184:187], v160 offset:1024
	ds_read_b128 v[188:191], v160 offset:2048
	ds_read_b128 v[192:195], v160 offset:3072
	ds_read_b128 v[196:199], v162
	ds_read_b128 v[200:203], v162 offset:1024
	ds_read_b128 v[204:207], v162 offset:2048
	ds_read_b128 v[208:211], v162 offset:3072
	ds_read_b128 v[212:215], v162 offset:4096
	ds_read_b128 v[216:219], v162 offset:5120
	ds_read_b128 v[220:223], v162 offset:6144
	ds_read_b128 v[224:227], v162 offset:7168
	s_add_u32 s22, s22, 0x80
	s_addc_u32 s23, s23, 0
	s_add_u32 s24, s24, 0x80
	s_addc_u32 s25, s25, 0
	s_add_i32 m0, s0, 0xc000
	s_nop 0
	global_load_lds_dwordx4 v140, s[22:23]
	s_add_i32 m0, s0, 0xe000
	s_nop 0
	global_load_lds_dwordx4 v144, s[22:23]
	s_add_i32 m0, s0, 0x1c000
	s_nop 0
	global_load_lds_dwordx4 v142, s[24:25]
	s_add_i32 m0, s0, 0x1e000
	s_nop 0
	global_load_lds_dwordx4 v146, s[24:25]
	s_waitcnt lgkmcnt(0)
	v_mfma_f32_16x16x32_bf16 v[52:55], v[180:183], v[196:199], v[52:55]
	v_mfma_f32_16x16x32_bf16 v[48:51], v[188:191], v[196:199], v[48:51]
	v_mfma_f32_16x16x32_bf16 v[36:39], v[180:183], v[204:207], v[36:39]
	v_mfma_f32_16x16x32_bf16 v[32:35], v[188:191], v[204:207], v[32:35]
	v_mfma_f32_16x16x32_bf16 v[20:23], v[180:183], v[212:215], v[20:23]
	v_mfma_f32_16x16x32_bf16 v[16:19], v[188:191], v[212:215], v[16:19]
	v_mfma_f32_16x16x32_bf16 v[4:7], v[180:183], v[220:223], v[4:7]
	v_mfma_f32_16x16x32_bf16 v[0:3], v[188:191], v[220:223], v[0:3]
	v_mfma_f32_16x16x32_bf16 v[52:55], v[184:187], v[200:203], v[52:55]
	v_mfma_f32_16x16x32_bf16 v[48:51], v[192:195], v[200:203], v[48:51]
	v_mfma_f32_16x16x32_bf16 v[36:39], v[184:187], v[208:211], v[36:39]
	v_mfma_f32_16x16x32_bf16 v[32:35], v[192:195], v[208:211], v[32:35]
	v_mfma_f32_16x16x32_bf16 v[20:23], v[184:187], v[216:219], v[20:23]
	v_mfma_f32_16x16x32_bf16 v[16:19], v[192:195], v[216:219], v[16:19]
	v_mfma_f32_16x16x32_bf16 v[4:7], v[184:187], v[224:227], v[4:7]
	v_mfma_f32_16x16x32_bf16 v[0:3], v[192:195], v[224:227], v[0:3]
	s_waitcnt vmcnt(8)
	s_barrier
	ds_read_b128 v[180:183], v163
	ds_read_b128 v[184:187], v163 offset:1024
	ds_read_b128 v[188:191], v163 offset:2048
	ds_read_b128 v[192:195], v163 offset:3072
	ds_read_b128 v[196:199], v162 offset:32768
	ds_read_b128 v[200:203], v162 offset:33792
	ds_read_b128 v[204:207], v162 offset:34816
	ds_read_b128 v[208:211], v162 offset:35840
	ds_read_b128 v[212:215], v162 offset:36864
	ds_read_b128 v[216:219], v162 offset:37888
	ds_read_b128 v[220:223], v162 offset:38912
	ds_read_b128 v[224:227], v162 offset:39936
	s_add_u32 s22, s22, 0x80
	s_addc_u32 s23, s23, 0
	s_add_u32 s24, s24, 0x80
	s_addc_u32 s25, s25, 0
	s_mov_b32 m0, s0
	s_nop 0
	global_load_lds_dwordx4 v140, s[22:23]
	s_add_i32 m0, s0, 0x2000
	s_nop 0
	global_load_lds_dwordx4 v144, s[22:23]
	s_add_i32 m0, s0, 0x10000
	s_nop 0
	global_load_lds_dwordx4 v142, s[24:25]
	s_add_i32 m0, s0, 0x12000
	s_nop 0
	global_load_lds_dwordx4 v146, s[24:25]
	s_waitcnt lgkmcnt(0)
	v_mfma_f32_16x16x32_bf16 v[52:55], v[180:183], v[196:199], v[52:55]
	v_mfma_f32_16x16x32_bf16 v[48:51], v[188:191], v[196:199], v[48:51]
	v_mfma_f32_16x16x32_bf16 v[36:39], v[180:183], v[204:207], v[36:39]
	v_mfma_f32_16x16x32_bf16 v[32:35], v[188:191], v[204:207], v[32:35]
	v_mfma_f32_16x16x32_bf16 v[20:23], v[180:183], v[212:215], v[20:23]
	v_mfma_f32_16x16x32_bf16 v[16:19], v[188:191], v[212:215], v[16:19]
	v_mfma_f32_16x16x32_bf16 v[4:7], v[180:183], v[220:223], v[4:7]
	v_mfma_f32_16x16x32_bf16 v[0:3], v[188:191], v[220:223], v[0:3]
	v_mfma_f32_16x16x32_bf16 v[52:55], v[184:187], v[200:203], v[52:55]
	v_mfma_f32_16x16x32_bf16 v[48:51], v[192:195], v[200:203], v[48:51]
	v_mfma_f32_16x16x32_bf16 v[36:39], v[184:187], v[208:211], v[36:39]
	v_mfma_f32_16x16x32_bf16 v[32:35], v[192:195], v[208:211], v[32:35]
	v_mfma_f32_16x16x32_bf16 v[20:23], v[184:187], v[216:219], v[20:23]
	v_mfma_f32_16x16x32_bf16 v[16:19], v[192:195], v[216:219], v[16:19]
	v_mfma_f32_16x16x32_bf16 v[4:7], v[184:187], v[224:227], v[4:7]
	v_mfma_f32_16x16x32_bf16 v[0:3], v[192:195], v[224:227], v[0:3]
	s_waitcnt vmcnt(8)
	s_barrier
	ds_read_b128 v[180:183], v161
	ds_read_b128 v[184:187], v161 offset:1024
	ds_read_b128 v[188:191], v161 offset:2048
	ds_read_b128 v[192:195], v161 offset:3072
	ds_read_b128 v[196:199], v162 offset:16384
	ds_read_b128 v[200:203], v162 offset:17408
	ds_read_b128 v[204:207], v162 offset:18432
	ds_read_b128 v[208:211], v162 offset:19456
	ds_read_b128 v[212:215], v162 offset:20480
	ds_read_b128 v[216:219], v162 offset:21504
	ds_read_b128 v[220:223], v162 offset:22528
	ds_read_b128 v[224:227], v162 offset:23552
	s_add_u32 s22, s22, 0x80
	s_addc_u32 s23, s23, 0
	s_add_u32 s24, s24, 0x80
	s_addc_u32 s25, s25, 0
	s_add_i32 m0, s0, 0x8000
	s_nop 0
	global_load_lds_dwordx4 v140, s[22:23]
	s_add_i32 m0, s0, 0xa000
	s_nop 0
	global_load_lds_dwordx4 v144, s[22:23]
	s_add_i32 m0, s0, 0x18000
	s_nop 0
	global_load_lds_dwordx4 v142, s[24:25]
	s_add_i32 m0, s0, 0x1a000
	s_nop 0
	global_load_lds_dwordx4 v146, s[24:25]
	s_waitcnt lgkmcnt(0)
	v_mfma_f32_16x16x32_bf16 v[52:55], v[180:183], v[196:199], v[52:55]
	v_mfma_f32_16x16x32_bf16 v[48:51], v[188:191], v[196:199], v[48:51]
	v_mfma_f32_16x16x32_bf16 v[36:39], v[180:183], v[204:207], v[36:39]
	v_mfma_f32_16x16x32_bf16 v[32:35], v[188:191], v[204:207], v[32:35]
	v_mfma_f32_16x16x32_bf16 v[20:23], v[180:183], v[212:215], v[20:23]
	v_mfma_f32_16x16x32_bf16 v[16:19], v[188:191], v[212:215], v[16:19]
	v_mfma_f32_16x16x32_bf16 v[4:7], v[180:183], v[220:223], v[4:7]
	v_mfma_f32_16x16x32_bf16 v[0:3], v[188:191], v[220:223], v[0:3]
	v_mfma_f32_16x16x32_bf16 v[52:55], v[184:187], v[200:203], v[52:55]
	v_mfma_f32_16x16x32_bf16 v[48:51], v[192:195], v[200:203], v[48:51]
	v_mfma_f32_16x16x32_bf16 v[36:39], v[184:187], v[208:211], v[36:39]
	v_mfma_f32_16x16x32_bf16 v[32:35], v[192:195], v[208:211], v[32:35]
	v_mfma_f32_16x16x32_bf16 v[20:23], v[184:187], v[216:219], v[20:23]
	v_mfma_f32_16x16x32_bf16 v[16:19], v[192:195], v[216:219], v[16:19]
	v_mfma_f32_16x16x32_bf16 v[4:7], v[184:187], v[224:227], v[4:7]
	v_mfma_f32_16x16x32_bf16 v[0:3], v[192:195], v[224:227], v[0:3]
	s_waitcnt vmcnt(8)
	s_barrier
; #define PG8_STAGE(bufoff, gbase, voff) do { _Pragma("unroll") for (int _i = 0; _i < 2; ++_i) \
;         __builtin_amdgcn_global_load_lds((const unsigned*)((const char*)(gbase) + (voff)[_i]), (PG8_LAS unsigned*)(lds + (bufoff) + ldsw + _i * 8192), 16, 0, 0); } while (0)
; #define PG8_LDA(dst, b, h) do { _Pragma("unroll") for (int m = 0; m < 4; ++m) _Pragma("unroll") for (int k = 0; k < 2; ++k) dst[m][k] = *(const PG8_LAS bf16x8*)(lds + PG8_SA(b, h) + aoff + m * 2048 + k * 1024); } while (0)
; #define PG8_LDB(dst, b, h) do { _Pragma("unroll") for (int n = 0; n < 2; ++n) _Pragma("unroll") for (int k = 0; k < 2; ++k) dst[n][k] = *(const PG8_LAS bf16x8*)(lds + PG8_SB(b, h) + boff + n * 2048 + k * 1024); } while (0)
; #define PG8_MMA(ai, bj, At, Bt) do { __builtin_amdgcn_s_setprio(1); _Pragma("unroll") for (int m = 0; m < 4; ++m) _Pragma("unroll") for (int n = 0; n < 2; ++n) _Pragma("unroll") for (int k = 0; k < 2; ++k) \
;         acc[ai][bj][m][n] = __builtin_amdgcn_mfma_f32_16x16x32_bf16(Bt[n][k], At[m][k], acc[ai][bj][m][n], 0, 0, 0); __builtin_amdgcn_s_setprio(0); } while (0)
; #define PG8_WAIT_V(n) asm volatile("s_waitcnt vmcnt(" #n ")" ::: "memory")
; template <class Epi, class Sched, bool ALIGN_EPI = false, bool SP2 = false>
; __device__ __forceinline__ void gemm_phase(PG8_LAS unsigned char* lds, const Gemm g, const Sched& S, const Epi& E) {
;     ...
;             PG8_LDB(B0, 0, 0); PG8_LDB(B1, 0, 1); PG8_SCHED; PG8_LDA(At, 0, 0); PG8_STAGE(PG8_SA(1, 1), a1 + hstep, voffA);
;             PG8_WAIT_V(8); PG8_WAIT_L(0); PG8_BAR; PG8_MMA(0, 0, At, B0); PG8_MMA(0, 1, At, B1); PG8_BAR; PG8_SCHED;
;             PG8_LDA(At, 0, 1); PG8_STAGE(PG8_SB(0, 0), b2, voffB); PG8_STAGE(PG8_SB(0, 1), b2 + hstep, voffB); PG8_STAGE(PG8_SA(0, 0), a2, voffA);
;             PG8_WAIT_V(8); PG8_WAIT_L(0); PG8_BAR; PG8_MMA(1, 0, At, B0); PG8_MMA(1, 1, At, B1); PG8_BAR; PG8_SCHED;
;             PG8_LDB(B0, 1, 0); PG8_LDB(B1, 1, 1); PG8_SCHED; PG8_LDA(At, 1, 0); PG8_STAGE(PG8_SA(0, 1), a2 + hstep, voffA);
;             PG8_WAIT_V(8); PG8_WAIT_L(0); PG8_BAR; PG8_MMA(0, 0, At, B0); PG8_MMA(0, 1, At, B1); PG8_BAR; PG8_SCHED;
;             PG8_LDA(At, 1, 1); PG8_STAGE(PG8_SB(1, 0), b3, voffB); PG8_STAGE(PG8_SB(1, 1), b3 + hstep, voffB); PG8_STAGE(PG8_SA(1, 0), a3, voffA);
;             PG8_WAIT_V(8); PG8_WAIT_L(0); PG8_BAR; PG8_MMA(1, 0, At, B0); PG8_MMA(1, 1, At, B1); PG8_BAR; PG8_SCHED;
	ds_read_b128 v[180:183], v164
	ds_read_b128 v[184:187], v164 offset:1024
	ds_read_b128 v[188:191], v164 offset:2048
	ds_read_b128 v[192:195], v164 offset:3072
	ds_read_b128 v[196:199], v162 offset:49152
	ds_read_b128 v[200:203], v162 offset:50176
	ds_read_b128 v[204:207], v162 offset:51200
	ds_read_b128 v[208:211], v162 offset:52224
	ds_read_b128 v[212:215], v162 offset:53248
	ds_read_b128 v[216:219], v162 offset:54272
	ds_read_b128 v[220:223], v162 offset:55296
	ds_read_b128 v[224:227], v162 offset:56320
	s_waitcnt lgkmcnt(0)
	v_mfma_f32_16x16x32_bf16 v[52:55], v[180:183], v[196:199], v[52:55]
	v_mfma_f32_16x16x32_bf16 v[48:51], v[188:191], v[196:199], v[48:51]
	v_mfma_f32_16x16x32_bf16 v[36:39], v[180:183], v[204:207], v[36:39]
	v_mfma_f32_16x16x32_bf16 v[32:35], v[188:191], v[204:207], v[32:35]
	v_mfma_f32_16x16x32_bf16 v[20:23], v[180:183], v[212:215], v[20:23]
	v_mfma_f32_16x16x32_bf16 v[16:19], v[188:191], v[212:215], v[16:19]
	v_mfma_f32_16x16x32_bf16 v[4:7], v[180:183], v[220:223], v[4:7]
	v_mfma_f32_16x16x32_bf16 v[0:3], v[188:191], v[220:223], v[0:3]
	v_mfma_f32_16x16x32_bf16 v[52:55], v[184:187], v[200:203], v[52:55]
	v_mfma_f32_16x16x32_bf16 v[48:51], v[192:195], v[200:203], v[48:51]
	v_mfma_f32_16x16x32_bf16 v[36:39], v[184:187], v[208:211], v[36:39]
	v_mfma_f32_16x16x32_bf16 v[32:35], v[192:195], v[208:211], v[32:35]
	v_mfma_f32_16x16x32_bf16 v[20:23], v[184:187], v[216:219], v[20:23]
	v_mfma_f32_16x16x32_bf16 v[16:19], v[192:195], v[216:219], v[16:19]
	v_mfma_f32_16x16x32_bf16 v[4:7], v[184:187], v[224:227], v[4:7]
	v_mfma_f32_16x16x32_bf16 v[0:3], v[192:195], v[224:227], v[0:3]
	s_waitcnt vmcnt(4)
	s_barrier
	ds_read_b128 v[180:183], v160
	ds_read_b128 v[184:187], v160 offset:1024
	ds_read_b128 v[188:191], v160 offset:2048
	ds_read_b128 v[192:195], v160 offset:3072
	ds_read_b128 v[196:199], v162
	ds_read_b128 v[200:203], v162 offset:1024
	ds_read_b128 v[204:207], v162 offset:2048
	ds_read_b128 v[208:211], v162 offset:3072
	ds_read_b128 v[212:215], v162 offset:4096
	ds_read_b128 v[216:219], v162 offset:5120
	ds_read_b128 v[220:223], v162 offset:6144
	ds_read_b128 v[224:227], v162 offset:7168
	s_waitcnt lgkmcnt(0)
	v_mfma_f32_16x16x32_bf16 v[52:55], v[180:183], v[196:199], v[52:55]
	v_mfma_f32_16x16x32_bf16 v[48:51], v[188:191], v[196:199], v[48:51]
	v_mfma_f32_16x16x32_bf16 v[36:39], v[180:183], v[204:207], v[36:39]
	v_mfma_f32_16x16x32_bf16 v[32:35], v[188:191], v[204:207], v[32:35]
	v_mfma_f32_16x16x32_bf16 v[20:23], v[180:183], v[212:215], v[20:23]
	v_mfma_f32_16x16x32_bf16 v[16:19], v[188:191], v[212:215], v[16:19]
	v_mfma_f32_16x16x32_bf16 v[4:7], v[180:183], v[220:223], v[4:7]
	v_mfma_f32_16x16x32_bf16 v[0:3], v[188:191], v[220:223], v[0:3]
	v_mfma_f32_16x16x32_bf16 v[52:55], v[184:187], v[200:203], v[52:55]
	v_mfma_f32_16x16x32_bf16 v[48:51], v[192:195], v[200:203], v[48:51]
	v_mfma_f32_16x16x32_bf16 v[36:39], v[184:187], v[208:211], v[36:39]
	v_mfma_f32_16x16x32_bf16 v[32:35], v[192:195], v[208:211], v[32:35]
	v_mfma_f32_16x16x32_bf16 v[20:23], v[184:187], v[216:219], v[20:23]
	v_mfma_f32_16x16x32_bf16 v[16:19], v[192:195], v[216:219], v[16:19]
	v_mfma_f32_16x16x32_bf16 v[4:7], v[184:187], v[224:227], v[4:7]
	v_mfma_f32_16x16x32_bf16 v[0:3], v[192:195], v[224:227], v[0:3]
	s_waitcnt vmcnt(0)
	s_barrier
	ds_read_b128 v[180:183], v163
	ds_read_b128 v[184:187], v163 offset:1024
	ds_read_b128 v[188:191], v163 offset:2048
	ds_read_b128 v[192:195], v163 offset:3072
	ds_read_b128 v[196:199], v162 offset:32768
	ds_read_b128 v[200:203], v162 offset:33792
	ds_read_b128 v[204:207], v162 offset:34816
	ds_read_b128 v[208:211], v162 offset:35840
	ds_read_b128 v[212:215], v162 offset:36864
	ds_read_b128 v[216:219], v162 offset:37888
	ds_read_b128 v[220:223], v162 offset:38912
	ds_read_b128 v[224:227], v162 offset:39936
	s_waitcnt lgkmcnt(0)
	v_mfma_f32_16x16x32_bf16 v[52:55], v[180:183], v[196:199], v[52:55]
	v_mfma_f32_16x16x32_bf16 v[48:51], v[188:191], v[196:199], v[48:51]
	v_mfma_f32_16x16x32_bf16 v[36:39], v[180:183], v[204:207], v[36:39]
	v_mfma_f32_16x16x32_bf16 v[32:35], v[188:191], v[204:207], v[32:35]
	v_mfma_f32_16x16x32_bf16 v[20:23], v[180:183], v[212:215], v[20:23]
	v_mfma_f32_16x16x32_bf16 v[16:19], v[188:191], v[212:215], v[16:19]
	v_mfma_f32_16x16x32_bf16 v[4:7], v[180:183], v[220:223], v[4:7]
	v_mfma_f32_16x16x32_bf16 v[0:3], v[188:191], v[220:223], v[0:3]
	v_mfma_f32_16x16x32_bf16 v[52:55], v[184:187], v[200:203], v[52:55]
	v_mfma_f32_16x16x32_bf16 v[48:51], v[192:195], v[200:203], v[48:51]
	v_mfma_f32_16x16x32_bf16 v[36:39], v[184:187], v[208:211], v[36:39]
	v_mfma_f32_16x16x32_bf16 v[32:35], v[192:195], v[208:211], v[32:35]
	v_mfma_f32_16x16x32_bf16 v[20:23], v[184:187], v[216:219], v[20:23]
	v_mfma_f32_16x16x32_bf16 v[16:19], v[192:195], v[216:219], v[16:19]
	v_mfma_f32_16x16x32_bf16 v[4:7], v[184:187], v[224:227], v[4:7]
	v_mfma_f32_16x16x32_bf16 v[0:3], v[192:195], v[224:227], v[0:3]
	s_branch .LBB0_620
